# GLA key-prep rope shuffles: ds_bpermute pairs + per-use address math replaced by DPP row_shl/row_shr moves
# speedup vs baseline: 1.0118x; 1.0041x over previous
; #define GAS __attribute__((address_space(1)))
; #define LAS __attribute__((address_space(3)))
; __device__ __forceinline__ float bfe(const v4u& w, int c) { return (c & 1) ? bfhi(w[c >> 1]) : bflo(w[c >> 1]); }
; __device__ __forceinline__ float bfe2(const v2u& w, int c) { return (c & 1) ? bfhi(w[c >> 1]) : bflo(w[c >> 1]); }
; template <int DIR> __device__ __forceinline__ void prep_gla_k(const ScanBufs<64>& B, const bf16* P, const float* w2g, const float* b2g, const f32x2* RR, const LAS f32x2* RC  , int g, int half, int lane, LAS v4u* Wl, LAS v4u* Gl  ) {
;     ...
;             { const int hgn = 2 * i8 + hh + 1; if (hgn < 16) { const int tb = DIR ? 4 * hgn : 60 - 4 * hgn;
; #pragma unroll
;                 for (int j = 0; j < 4; ++j) { const size_t ro = (size_t)(tb + j) * NINP; krn[j] = *(const GAS v2u*)(kp0 + ro); qrn[j] = *(const GAS v2u*)(qp0 + ro); } } }
; #pragma unroll
;             for (int j = 0; j < 4; ++j) { const int tt_ = t8 * 8 + hf * 4 + j; l0[j] = Gl[2 * tt_]; l1[j] = Gl[2 * tt_ + 1]; }
; #pragma unroll
;             for (int jj = 0; jj < 4; ++jj) { const int j = DIR ? jj : 3 - jj; const int t = t8 * 8 + hf * 4 + j; float ev[4], kv[4];
;                 f32x2 csc[4];
;                 { const LAS f32x4* rc4 = (const LAS f32x4*)(RC + t * 16 + j0); const f32x4 ra = rc4[0], rb = rc4[1];
;                   csc[0] = isrow ? csr[0] : (f32x2){ra[0], ra[1]}; csc[1] = isrow ? csr[1] : (f32x2){ra[2], ra[3]}; csc[2] = isrow ? csr[2] : (f32x2){rb[0], rb[1]}; csc[3] = isrow ? csr[3] : (f32x2){rb[2], rb[3]}; }
; #pragma unroll
;                 for (int c = 0; c < 4; ++c) { float x = b2[c];
; #pragma unroll
;                     for (int r = 0; r < 8; ++r) { x += bfe(l0[j], r) * w2[r][c]; x += bfe(l1[j], r) * w2[8 + r][c]; }
;                     const float la = (fminf(x, 0.f) * 1.4426950408889634f - __log2f(1.f + __expf(-fabsf(x)))) * 0.0625f;
;                     float k = bfe2(kr[j], c), q = bfe2(qr2[j], c);
;                     if (lat) { const f32x2 cs = csc[c]; const float pt = __shfl_xor(k, 4), pq = __shfl_xor(q, 4); k = k * cs.x + (second ? pt : -pt) * cs.y; q = q * cs.x + (second ? pq : -pq) * cs.y; }
.LBB0_688:
	v_lshl_add_u64 v[150:151], s[70:71], 0, v[108:109]
	s_mov_b32 s23, 0x2e425000
	v_add_co_u32_e32 v82, vcc, s23, v150
	s_mov_b32 s23, 0x2e42d000
	s_nop 0
	v_addc_co_u32_e32 v83, vcc, 0, v151, vcc
	v_add_co_u32_e32 v84, vcc, s23, v150
	s_mov_b32 s23, 0x2e436000
	s_nop 0
	v_addc_co_u32_e32 v85, vcc, 0, v151, vcc
	global_load_dwordx2 v[146:147], v[82:83], off offset:1024
	global_load_dwordx2 v[142:143], v[84:85], off offset:3584
	global_load_dwordx2 v[144:145], v[84:85], off offset:2560
	global_load_dwordx2 v[148:149], v[82:83], off
	v_add_co_u32_e32 v82, vcc, s23, v150
	s_mov_b32 s23, 0x2e43f000
	s_nop 0
	v_addc_co_u32_e32 v83, vcc, 0, v151, vcc
	v_add_co_u32_e32 v84, vcc, s23, v150
	s_mov_b32 s23, 0x2e43e000
	s_nop 0
	v_addc_co_u32_e32 v85, vcc, 0, v151, vcc
	v_add_co_u32_e32 v86, vcc, s23, v150
	s_add_i32 s31, s1, 0
	s_nop 0
	v_addc_co_u32_e32 v87, vcc, 0, v151, vcc
	global_load_dwordx2 v[132:133], v[82:83], off offset:2048
	global_load_dwordx2 v[122:123], v[84:85], off offset:512
	global_load_dwordx2 v[124:125], v[86:87], off offset:3584
	global_load_dwordx2 v[134:135], v[82:83], off offset:1024
	s_add_i32 s23, s31, 0x12000
	v_mov_b32_e32 v64, s23
	s_add_i32 s23, s31, 0x12010
	ds_read_b128 v[82:85], v64
	v_mov_b32_e32 v64, s23
	ds_read_b128 v[86:89], v64
	s_add_i32 s23, s31, 0x12020
	v_mov_b32_e32 v64, s23
	s_add_i32 s23, s31, 0x12030
	s_waitcnt lgkmcnt(1)
	v_readfirstlane_b32 s62, v82
	v_readfirstlane_b32 s59, v83
	v_readfirstlane_b32 s58, v84
	v_readfirstlane_b32 s57, v85
	ds_read_b128 v[82:85], v64
	v_mov_b32_e32 v64, s23
	s_waitcnt lgkmcnt(1)
	v_readfirstlane_b32 s64, v86
	v_readfirstlane_b32 s63, v87
	v_readfirstlane_b32 s60, v88
	v_readfirstlane_b32 s61, v89
	ds_read_b128 v[86:89], v64
	s_add_i32 s23, s31, 0x12040
	v_mov_b32_e32 v64, s23
	s_add_i32 s23, s31, 0x12050
	s_waitcnt lgkmcnt(1)
	v_readfirstlane_b32 s54, v82
	v_readfirstlane_b32 s51, v83
	v_readfirstlane_b32 s50, v84
	v_readfirstlane_b32 s49, v85
	ds_read_b128 v[82:85], v64
	v_mov_b32_e32 v64, s23
	s_waitcnt lgkmcnt(1)
	v_readfirstlane_b32 s56, v86
	v_readfirstlane_b32 s55, v87
	v_readfirstlane_b32 s52, v88
	v_readfirstlane_b32 s53, v89
	ds_read_b128 v[86:89], v64
	s_add_i32 s23, s31, 0x12060
	v_mov_b32_e32 v64, s23
	s_add_i32 s23, s31, 0x12070
	s_waitcnt lgkmcnt(1)
	v_readfirstlane_b32 s46, v82
	v_readfirstlane_b32 s33, v83
	v_readfirstlane_b32 s35, v84
	v_readfirstlane_b32 s34, v85
	ds_read_b128 v[82:85], v64
	v_mov_b32_e32 v64, s23
	s_waitcnt lgkmcnt(1)
	v_readfirstlane_b32 s48, v86
	v_readfirstlane_b32 s47, v87
	v_readfirstlane_b32 s36, v88
	v_readfirstlane_b32 s37, v89
	ds_read_b128 v[86:89], v64
	v_add_u32_e32 v180, 0, v159
	s_waitcnt lgkmcnt(1)
	v_readfirstlane_b32 s28, v82
	v_add_u32_e32 v64, 0x10000, v180
	v_add_u32_e32 v82, 0x10010, v180
	v_readfirstlane_b32 s26, v83
	v_readfirstlane_b32 s24, v84
	v_readfirstlane_b32 s23, v85
	s_waitcnt lgkmcnt(0)
	v_readfirstlane_b32 s30, v86
	v_readfirstlane_b32 s29, v87
	v_readfirstlane_b32 s27, v88
	v_readfirstlane_b32 s25, v89
	ds_read_b128 v[86:89], v64
	ds_read_b128 v[82:85], v82
	v_cndmask_b32_e64 v64, 0, 1, s[44:45]
	s_waitcnt vmcnt(12)
	v_lshlrev_b32_e32 v115, 16, v140
	v_cmp_ne_u32_e64 s[42:43], 1, v64
	s_andn2_b64 vcc, exec, s[44:45]
	v_lshlrev_b32_e32 v114, 16, v138
	s_cbranch_vccnz .LBB0_692
	s_waitcnt lgkmcnt(1)
	v_cndmask_b32_e64 v86, v86, v74, s[38:39]
	s_nop 1
	v_mov_b32_dpp v116, v115 row_shl:4 row_mask:0xf bank_mask:0x5
	v_mov_b32_dpp v116, v115 row_shr:4 row_mask:0xf bank_mask:0xa
	v_mov_b32_dpp v130, v114 row_shl:4 row_mask:0xf bank_mask:0x5
	v_mov_b32_dpp v130, v114 row_shr:4 row_mask:0xf bank_mask:0xa
	v_cndmask_b32_e64 v64, v87, v75, s[38:39]
	s_waitcnt lgkmcnt(0)
	v_cndmask_b32_e64 v117, v116, -v116, s[40:41]
	s_waitcnt lgkmcnt(0)
	v_cndmask_b32_e64 v116, v130, -v130, s[40:41]
	v_pk_mul_f32 v[116:117], v[64:65], v[116:117] op_sel_hi:[0,1]
	v_pk_fma_f32 v[114:115], v[86:87], v[114:115], v[116:117] op_sel_hi:[0,1,1]
	v_and_b32_e32 v87, 0xffff0000, v140
	s_and_b64 vcc, exec, s[42:43]
	v_and_b32_e32 v86, 0xffff0000, v138
	s_cbranch_vccz .LBB0_693

; __device__ __forceinline__ float bfe2(const v2u& w, int c) { return (c & 1) ? bfhi(w[c >> 1]) : bflo(w[c >> 1]); }
; template <int DIR> __device__ __forceinline__ void prep_gla_k(const ScanBufs<64>& B, const bf16* P, const float* w2g, const float* b2g, const f32x2* RR, const LAS f32x2* RC  , int g, int half, int lane, LAS v4u* Wl, LAS v4u* Gl  ) {
;     ...
;                     float k = bfe2(kr[j], c), q = bfe2(qr2[j], c);
;                     if (lat) { const f32x2 cs = csc[c]; const float pt = __shfl_xor(k, 4), pq = __shfl_xor(q, 4); k = k * cs.x + (second ? pt : -pt) * cs.y; q = q * cs.x + (second ? pq : -pq) * cs.y; }
.LBB0_691:
	s_waitcnt lgkmcnt(0)
	v_cndmask_b32_e64 v82, v82, v70, s[38:39]
	s_nop 1
	v_mov_b32_dpp v116, v89 row_shl:4 row_mask:0xf bank_mask:0x5
	v_mov_b32_dpp v116, v89 row_shr:4 row_mask:0xf bank_mask:0xa
	v_mov_b32_dpp v130, v88 row_shl:4 row_mask:0xf bank_mask:0x5
	v_mov_b32_dpp v130, v88 row_shr:4 row_mask:0xf bank_mask:0xa
	v_cndmask_b32_e64 v64, v83, v71, s[38:39]
	s_waitcnt lgkmcnt(0)
	v_cndmask_b32_e64 v117, v116, -v116, s[40:41]
	s_waitcnt lgkmcnt(0)
	v_cndmask_b32_e64 v116, v130, -v130, s[40:41]
	v_pk_mul_f32 v[116:117], v[64:65], v[116:117] op_sel_hi:[0,1]
	v_pk_fma_f32 v[88:89], v[82:83], v[88:89], v[116:117] op_sel_hi:[0,1,1]
	v_and_b32_e32 v83, 0xffff0000, v141
	s_and_b64 vcc, exec, s[42:43]
	v_and_b32_e32 v82, 0xffff0000, v139
	s_cbranch_vccz .LBB0_695
	s_branch .LBB0_696

; __device__ __forceinline__ float bfe2(const v2u& w, int c) { return (c & 1) ? bfhi(w[c >> 1]) : bflo(w[c >> 1]); }
; template <int DIR> __device__ __forceinline__ void prep_gla_k(const ScanBufs<64>& B, const bf16* P, const float* w2g, const float* b2g, const f32x2* RR, const LAS f32x2* RC  , int g, int half, int lane, LAS v4u* Wl, LAS v4u* Gl  ) {
;     ...
;                     float k = bfe2(kr[j], c), q = bfe2(qr2[j], c);
;                     if (lat) { const f32x2 cs = csc[c]; const float pt = __shfl_xor(k, 4), pq = __shfl_xor(q, 4); k = k * cs.x + (second ? pt : -pt) * cs.y; q = q * cs.x + (second ? pq : -pq) * cs.y; }
.LBB0_693:
	v_cndmask_b32_e64 v88, v88, v76, s[38:39]
	s_nop 0
	s_nop 1
	v_mov_b32_dpp v116, v87 row_shl:4 row_mask:0xf bank_mask:0x5
	v_mov_b32_dpp v116, v87 row_shr:4 row_mask:0xf bank_mask:0xa
	v_mov_b32_dpp v130, v86 row_shl:4 row_mask:0xf bank_mask:0x5
	v_mov_b32_dpp v130, v86 row_shr:4 row_mask:0xf bank_mask:0xa
	v_cndmask_b32_e64 v64, v89, v77, s[38:39]
	s_waitcnt lgkmcnt(0)
	v_cndmask_b32_e64 v117, v116, -v116, s[40:41]
	s_waitcnt lgkmcnt(0)
	v_cndmask_b32_e64 v116, v130, -v130, s[40:41]
	v_pk_mul_f32 v[116:117], v[64:65], v[116:117] op_sel_hi:[0,1]
	v_pk_fma_f32 v[86:87], v[88:89], v[86:87], v[116:117] op_sel_hi:[0,1,1]
	v_lshlrev_b32_e32 v89, 16, v141
	s_and_b64 vcc, exec, s[42:43]
	v_lshlrev_b32_e32 v88, 16, v139
	s_cbranch_vccz .LBB0_691

; #define GAS __attribute__((address_space(1)))
; __device__ __forceinline__ unsigned pk2(float lo, float hi) { const f32x2_t v = {lo, hi}; const bf16x2_t b = __builtin_convertvector(v, bf16x2_t); return __builtin_bit_cast(unsigned, b); }
; __device__ __forceinline__ float ex2(float x) { return __builtin_amdgcn_exp2f(x); }
; __device__ __forceinline__ float bfe2(const v2u& w, int c) { return (c & 1) ? bfhi(w[c >> 1]) : bflo(w[c >> 1]); }
; template <int DIR> __device__ __forceinline__ void prep_gla_k(const ScanBufs<64>& B, const bf16* P, const float* w2g, const float* b2g, const f32x2* RR, const LAS f32x2* RC  , int g, int half, int lane, LAS v4u* Wl, LAS v4u* Gl  ) {
;     ...
;                     float k = bfe2(kr[j], c), q = bfe2(qr2[j], c);
;                     if (lat) { const f32x2 cs = csc[c]; const float pt = __shfl_xor(k, 4), pq = __shfl_xor(q, 4); k = k * cs.x + (second ? pt : -pt) * cs.y; q = q * cs.x + (second ? pq : -pq) * cs.y; }
;                     const float e = cum[c]; cum[c] += la; kv[c] = k * ex2(e); kp[hf * 4 + j][c] = kv[c]; ev[c] = q * 0.125f * ex2(fminf(-e, 126.f)); }
;                 { v2u ew; ew.x = pk2(ev[0], ev[1]); ew.y = pk2(ev[2], ev[3]); *(GAS v2u*)(Ep + (size_t)t * 512) = ew; }
;                 { v2u kw; kw.x = pk2(kv[0], kv[1]); kw.y = pk2(kv[2], kv[3]); *(GAS v2u*)(Kp + (size_t)t * 512) = kw; } } }
.LBB0_695:
	v_cndmask_b32_e64 v84, v84, v72, s[38:39]
	s_nop 0
	s_nop 1
	v_mov_b32_dpp v116, v83 row_shl:4 row_mask:0xf bank_mask:0x5
	v_mov_b32_dpp v116, v83 row_shr:4 row_mask:0xf bank_mask:0xa
	v_mov_b32_dpp v130, v82 row_shl:4 row_mask:0xf bank_mask:0x5
	v_mov_b32_dpp v130, v82 row_shr:4 row_mask:0xf bank_mask:0xa
	v_cndmask_b32_e64 v64, v85, v73, s[38:39]
	s_waitcnt lgkmcnt(0)
	v_cndmask_b32_e64 v117, v116, -v116, s[40:41]
	s_waitcnt lgkmcnt(0)
	v_cndmask_b32_e64 v116, v130, -v130, s[40:41]
	v_pk_mul_f32 v[116:117], v[64:65], v[116:117] op_sel_hi:[0,1]
	v_pk_fma_f32 v[82:83], v[84:85], v[82:83], v[116:117] op_sel_hi:[0,1,1]
.LBB0_696:
	v_max_f32_e64 v85, -v80, -v80
	v_min_f32_e32 v85, 0x42fc0000, v85
	v_exp_f32_e32 v85, v85
	v_mul_f32_e32 v84, 0x3e000000, v89
	v_exp_f32_e32 v64, v80
	v_lshl_add_u64 v[116:117], s[70:71], 0, v[106:107]
	v_mul_f32_e32 v84, v85, v84
	v_exp_f32_e32 v85, v79
	s_mov_b32 s65, 0x66800000
	v_add_co_u32_e32 v138, vcc, s65, v116
	v_mul_f32_e32 v160, v85, v86
	v_max_f32_e64 v86, -v79, -v79
	v_min_f32_e32 v86, 0x42fc0000, v86
	v_exp_f32_e32 v86, v86
	v_mul_f32_e32 v85, 0x3e000000, v87
	v_max_f32_e64 v87, -v78, -v78
	v_min_f32_e32 v87, 0x42fc0000, v87
	v_mul_f32_e32 v85, v86, v85
	v_exp_f32_e32 v86, v78
	v_exp_f32_e32 v87, v87
	v_addc_co_u32_e32 v139, vcc, 0, v117, vcc
	v_mul_f32_e32 v114, v86, v114
	v_mul_f32_e32 v86, 0x3e000000, v115
	v_mul_f32_e32 v86, v87, v86
	v_exp_f32_e32 v87, v81
	v_mul_f32_e32 v64, v64, v88
	v_lshlrev_b32_e32 v131, 16, v128
	v_lshlrev_b32_e32 v130, 16, v126
	v_mul_f32_e32 v115, v87, v82
	v_mul_f32_e32 v82, 0x3e000000, v83
	v_max_f32_e64 v83, -v81, -v81
	v_min_f32_e32 v83, 0x42fc0000, v83
	v_exp_f32_e32 v83, v83
	s_nop 0
	v_mul_f32_e32 v83, v83, v82
	v_cvt_pk_bf16_f32 v82, v86, v85
	v_cvt_pk_bf16_f32 v83, v84, v83
	v_add_co_u32_e32 v84, vcc, 0x65600000, v116
	global_store_dwordx2 v[138:139], v[82:83], off
	v_cvt_pk_bf16_f32 v82, v114, v160
	v_cvt_pk_bf16_f32 v83, v64, v115
	v_addc_co_u32_e32 v85, vcc, 0, v117, vcc
	global_store_dwordx2 v[84:85], v[82:83], off
	v_add_u32_e32 v82, 0x10080, v180
	ds_read_b128 v[86:89], v82
	v_add_u32_e32 v82, 0x10090, v180
	ds_read_b128 v[82:85], v82
	s_and_b64 vcc, exec, s[42:43]
	s_cbranch_vccnz .LBB0_700
	s_waitcnt lgkmcnt(1)
	v_cndmask_b32_e64 v86, v86, v74, s[38:39]
	s_nop 1
	v_mov_b32_dpp v140, v131 row_shl:4 row_mask:0xf bank_mask:0x5
	v_mov_b32_dpp v140, v131 row_shr:4 row_mask:0xf bank_mask:0xa
	v_mov_b32_dpp v152, v130 row_shl:4 row_mask:0xf bank_mask:0x5
	v_mov_b32_dpp v152, v130 row_shr:4 row_mask:0xf bank_mask:0xa
	v_cndmask_b32_e64 v136, v87, v75, s[38:39]
	s_waitcnt lgkmcnt(0)
	v_cndmask_b32_e64 v141, v140, -v140, s[40:41]
	s_waitcnt lgkmcnt(0)
	v_cndmask_b32_e64 v140, v152, -v152, s[40:41]
	v_pk_mul_f32 v[140:141], v[136:137], v[140:141] op_sel_hi:[0,1]
	v_pk_fma_f32 v[130:131], v[86:87], v[130:131], v[140:141] op_sel_hi:[0,1,1]
	v_and_b32_e32 v87, 0xffff0000, v128
	s_and_b64 vcc, exec, s[42:43]
	v_and_b32_e32 v86, 0xffff0000, v126
	s_cbranch_vccz .LBB0_701

; __device__ __forceinline__ float bfe2(const v2u& w, int c) { return (c & 1) ? bfhi(w[c >> 1]) : bflo(w[c >> 1]); }
; template <int DIR> __device__ __forceinline__ void prep_gla_k(const ScanBufs<64>& B, const bf16* P, const float* w2g, const float* b2g, const f32x2* RR, const LAS f32x2* RC  , int g, int half, int lane, LAS v4u* Wl, LAS v4u* Gl  ) {
;     ...
;                     float k = bfe2(kr[j], c), q = bfe2(qr2[j], c);
;                     if (lat) { const f32x2 cs = csc[c]; const float pt = __shfl_xor(k, 4), pq = __shfl_xor(q, 4); k = k * cs.x + (second ? pt : -pt) * cs.y; q = q * cs.x + (second ? pq : -pq) * cs.y; }
.LBB0_699:
	s_waitcnt lgkmcnt(0)
	v_cndmask_b32_e64 v82, v82, v70, s[38:39]
	s_nop 1
	v_mov_b32_dpp v128, v89 row_shl:4 row_mask:0xf bank_mask:0x5
	v_mov_b32_dpp v128, v89 row_shr:4 row_mask:0xf bank_mask:0xa
	v_mov_b32_dpp v136, v88 row_shl:4 row_mask:0xf bank_mask:0x5
	v_mov_b32_dpp v136, v88 row_shr:4 row_mask:0xf bank_mask:0xa
	v_cndmask_b32_e64 v126, v83, v71, s[38:39]
	s_waitcnt lgkmcnt(0)
	v_cndmask_b32_e64 v141, v128, -v128, s[40:41]
	s_waitcnt lgkmcnt(0)
	v_cndmask_b32_e64 v140, v136, -v136, s[40:41]
	v_pk_mul_f32 v[140:141], v[126:127], v[140:141] op_sel_hi:[0,1]
	v_pk_fma_f32 v[88:89], v[82:83], v[88:89], v[140:141] op_sel_hi:[0,1,1]
	v_and_b32_e32 v83, 0xffff0000, v129
	s_and_b64 vcc, exec, s[42:43]
	v_and_b32_e32 v82, 0xffff0000, v127
	s_cbranch_vccz .LBB0_703
	s_branch .LBB0_704

; __device__ __forceinline__ float bfe2(const v2u& w, int c) { return (c & 1) ? bfhi(w[c >> 1]) : bflo(w[c >> 1]); }
; template <int DIR> __device__ __forceinline__ void prep_gla_k(const ScanBufs<64>& B, const bf16* P, const float* w2g, const float* b2g, const f32x2* RR, const LAS f32x2* RC  , int g, int half, int lane, LAS v4u* Wl, LAS v4u* Gl  ) {
;     ...
;                     float k = bfe2(kr[j], c), q = bfe2(qr2[j], c);
;                     if (lat) { const f32x2 cs = csc[c]; const float pt = __shfl_xor(k, 4), pq = __shfl_xor(q, 4); k = k * cs.x + (second ? pt : -pt) * cs.y; q = q * cs.x + (second ? pq : -pq) * cs.y; }
.LBB0_701:
	v_cndmask_b32_e64 v88, v88, v76, s[38:39]
	s_nop 0
	s_nop 1
	v_mov_b32_dpp v128, v87 row_shl:4 row_mask:0xf bank_mask:0x5
	v_mov_b32_dpp v128, v87 row_shr:4 row_mask:0xf bank_mask:0xa
	v_mov_b32_dpp v136, v86 row_shl:4 row_mask:0xf bank_mask:0x5
	v_mov_b32_dpp v136, v86 row_shr:4 row_mask:0xf bank_mask:0xa
	v_cndmask_b32_e64 v126, v89, v77, s[38:39]
	s_waitcnt lgkmcnt(0)
	v_cndmask_b32_e64 v141, v128, -v128, s[40:41]
	s_waitcnt lgkmcnt(0)
	v_cndmask_b32_e64 v140, v136, -v136, s[40:41]
	v_pk_mul_f32 v[140:141], v[126:127], v[140:141] op_sel_hi:[0,1]
	v_pk_fma_f32 v[86:87], v[88:89], v[86:87], v[140:141] op_sel_hi:[0,1,1]
	v_lshlrev_b32_e32 v89, 16, v129
	s_and_b64 vcc, exec, s[42:43]
	v_lshlrev_b32_e32 v88, 16, v127
	s_cbranch_vccz .LBB0_699

; #define GAS __attribute__((address_space(1)))
; __device__ __forceinline__ unsigned pk2(float lo, float hi) { const f32x2_t v = {lo, hi}; const bf16x2_t b = __builtin_convertvector(v, bf16x2_t); return __builtin_bit_cast(unsigned, b); }
; __device__ __forceinline__ float ex2(float x) { return __builtin_amdgcn_exp2f(x); }
; __device__ __forceinline__ float bfe(const v4u& w, int c) { return (c & 1) ? bfhi(w[c >> 1]) : bflo(w[c >> 1]); }
; __device__ __forceinline__ float bfe2(const v2u& w, int c) { return (c & 1) ? bfhi(w[c >> 1]) : bflo(w[c >> 1]); }
; template <int DIR> __device__ __forceinline__ void prep_gla_k(const ScanBufs<64>& B, const bf16* P, const float* w2g, const float* b2g, const f32x2* RR, const LAS f32x2* RC  , int g, int half, int lane, LAS v4u* Wl, LAS v4u* Gl  ) {
;     ...
;                 for (int c = 0; c < 4; ++c) { float x = b2[c];
; #pragma unroll
;                     for (int r = 0; r < 8; ++r) { x += bfe(l0[j], r) * w2[r][c]; x += bfe(l1[j], r) * w2[8 + r][c]; }
;                     const float la = (fminf(x, 0.f) * 1.4426950408889634f - __log2f(1.f + __expf(-fabsf(x)))) * 0.0625f;
;                     float k = bfe2(kr[j], c), q = bfe2(qr2[j], c);
;                     if (lat) { const f32x2 cs = csc[c]; const float pt = __shfl_xor(k, 4), pq = __shfl_xor(q, 4); k = k * cs.x + (second ? pt : -pt) * cs.y; q = q * cs.x + (second ? pq : -pq) * cs.y; }
;                     const float e = cum[c]; cum[c] += la; kv[c] = k * ex2(e); kp[hf * 4 + j][c] = kv[c]; ev[c] = q * 0.125f * ex2(fminf(-e, 126.f)); }
;                 { v2u ew; ew.x = pk2(ev[0], ev[1]); ew.y = pk2(ev[2], ev[3]); *(GAS v2u*)(Ep + (size_t)t * 512) = ew; }
;                 { v2u kw; kw.x = pk2(kv[0], kv[1]); kw.y = pk2(kv[2], kv[3]); *(GAS v2u*)(Kp + (size_t)t * 512) = kw; } } }
.LBB0_703:
	v_cndmask_b32_e64 v84, v84, v72, s[38:39]
	s_nop 0
	s_nop 1
	v_mov_b32_dpp v127, v83 row_shl:4 row_mask:0xf bank_mask:0x5
	v_mov_b32_dpp v127, v83 row_shr:4 row_mask:0xf bank_mask:0xa
	v_mov_b32_dpp v128, v82 row_shl:4 row_mask:0xf bank_mask:0x5
	v_mov_b32_dpp v128, v82 row_shr:4 row_mask:0xf bank_mask:0xa
	v_cndmask_b32_e64 v126, v85, v73, s[38:39]
	s_waitcnt lgkmcnt(0)
	v_cndmask_b32_e64 v129, v127, -v127, s[40:41]
	s_waitcnt lgkmcnt(0)
	v_cndmask_b32_e64 v128, v128, -v128, s[40:41]
	v_pk_mul_f32 v[126:127], v[126:127], v[128:129] op_sel_hi:[0,1]
	v_pk_fma_f32 v[82:83], v[84:85], v[82:83], v[126:127] op_sel_hi:[0,1,1]
.LBB0_704:
	s_lshl_b32 s73, s62, 16
	s_lshl_b32 s72, s64, 16
	v_fma_f32 v84, s73, v2, v68
	s_and_b32 s71, s62, 0xffff0000
	v_fmac_f32_e32 v84, s72, v30
	s_and_b32 s70, s64, 0xffff0000
	v_fmac_f32_e32 v84, s71, v6
	s_lshl_b32 s69, s59, 16
	v_fmac_f32_e32 v84, s70, v38
	s_lshl_b32 s68, s63, 16
	v_fmac_f32_e32 v84, s69, v10
	s_and_b32 s67, s59, 0xffff0000
	v_fmac_f32_e32 v84, s68, v42
	s_and_b32 s66, s63, 0xffff0000
	v_fmac_f32_e32 v84, s67, v14
	s_lshl_b32 s65, s58, 16
	v_fmac_f32_e32 v84, s66, v46
	s_lshl_b32 s64, s60, 16
	v_fmac_f32_e32 v84, s65, v18
	s_and_b32 s63, s58, 0xffff0000
	v_fmac_f32_e32 v84, s64, v54
	s_and_b32 s62, s60, 0xffff0000
	v_fmac_f32_e32 v84, s63, v34
	s_lshl_b32 s60, s57, 16
	v_fmac_f32_e32 v84, s62, v50
	s_lshl_b32 s59, s61, 16
	v_fmac_f32_e32 v84, s60, v22
	s_and_b32 s58, s57, 0xffff0000
	v_fmac_f32_e32 v84, s59, v58
	s_and_b32 s57, s61, 0xffff0000
	v_fmac_f32_e32 v84, s58, v26
	v_fmac_f32_e32 v84, s57, v62
	s_mov_b32 s74, 0xbfb8aa3b
	v_min_f32_e32 v85, 0, v84
	v_mul_f32_e64 v84, |v84|, s74
	v_exp_f32_e32 v84, v84
	s_mov_b32 s75, 0x3fb8aa3b
	s_mov_b32 s61, 0x42fc0000
	s_waitcnt vmcnt(12)
	v_lshlrev_b32_e32 v127, 16, v120
	v_add_f32_e32 v84, 1.0, v84
	v_log_f32_e32 v84, v84
	v_lshlrev_b32_e32 v126, 16, v118
	v_fma_f32 v84, v85, s75, -v84
	v_fmac_f32_e32 v80, 0x3d800000, v84
	v_exp_f32_e32 v84, v80
	v_min_f32_e64 v85, -v80, s61
	v_exp_f32_e32 v85, v85
	v_mul_f32_e32 v161, v84, v88
	v_mul_f32_e32 v84, 0x3e000000, v89
	v_mul_f32_e32 v84, v85, v84
	v_fma_f32 v85, s73, v1, v67
	v_fmac_f32_e32 v85, s72, v29
	v_fmac_f32_e32 v85, s71, v5
	v_fmac_f32_e32 v85, s70, v37
	v_fmac_f32_e32 v85, s69, v9
	v_fmac_f32_e32 v85, s68, v41
	v_fmac_f32_e32 v85, s67, v13
	v_fmac_f32_e32 v85, s66, v45
	v_fmac_f32_e32 v85, s65, v17
	v_fmac_f32_e32 v85, s64, v53
	v_fmac_f32_e32 v85, s63, v33
	v_fmac_f32_e32 v85, s62, v49
	v_fmac_f32_e32 v85, s60, v21
	v_fmac_f32_e32 v85, s59, v57
	v_fmac_f32_e32 v85, s58, v25
	v_fmac_f32_e32 v85, s57, v61
	v_min_f32_e32 v88, 0, v85
	v_mul_f32_e64 v85, |v85|, s74
	v_exp_f32_e32 v85, v85
	s_nop 0
	v_add_f32_e32 v85, 1.0, v85
	v_log_f32_e32 v85, v85
	s_nop 0
	v_fma_f32 v85, v88, s75, -v85
	v_fmac_f32_e32 v79, 0x3d800000, v85
	v_exp_f32_e32 v85, v79
	s_nop 0
	v_mul_f32_e32 v178, v85, v86
	v_min_f32_e64 v86, -v79, s61
	v_exp_f32_e32 v86, v86
	v_mul_f32_e32 v85, 0x3e000000, v87
	v_mul_f32_e32 v85, v86, v85
	v_fma_f32 v86, s73, v0, v66
	v_fmac_f32_e32 v86, s72, v28
	v_fmac_f32_e32 v86, s71, v4
	v_fmac_f32_e32 v86, s70, v36
	v_fmac_f32_e32 v86, s69, v8
	v_fmac_f32_e32 v86, s68, v40
	v_fmac_f32_e32 v86, s67, v12
	v_fmac_f32_e32 v86, s66, v44
	v_fmac_f32_e32 v86, s65, v16
	v_fmac_f32_e32 v86, s64, v52
	v_fmac_f32_e32 v86, s63, v32
	v_fmac_f32_e32 v86, s62, v48
	v_fmac_f32_e32 v86, s60, v20
	v_fmac_f32_e32 v86, s59, v56
	v_fmac_f32_e32 v86, s58, v24
	v_fmac_f32_e32 v86, s57, v60
	v_min_f32_e32 v87, 0, v86
	v_mul_f32_e64 v86, |v86|, s74
	v_exp_f32_e32 v86, v86
	s_nop 0
	v_add_f32_e32 v86, 1.0, v86
	v_log_f32_e32 v86, v86
	s_nop 0
	v_fma_f32 v86, v87, s75, -v86
	v_fmac_f32_e32 v78, 0x3d800000, v86
	v_exp_f32_e32 v86, v78
	v_min_f32_e64 v87, -v78, s61
	v_exp_f32_e32 v87, v87
	v_mul_f32_e32 v179, v86, v130
	v_mul_f32_e32 v86, 0x3e000000, v131
	v_mul_f32_e32 v86, v87, v86
	v_fma_f32 v87, s73, v3, v69
	v_fmac_f32_e32 v87, s72, v31
	v_fmac_f32_e32 v87, s71, v7
	v_fmac_f32_e32 v87, s70, v39
	v_fmac_f32_e32 v87, s69, v11
	v_fmac_f32_e32 v87, s68, v43
	v_fmac_f32_e32 v87, s67, v15
	v_fmac_f32_e32 v87, s66, v47
	v_fmac_f32_e32 v87, s65, v19
	v_fmac_f32_e32 v87, s64, v55
	v_fmac_f32_e32 v87, s63, v35
	v_fmac_f32_e32 v87, s62, v51
	v_fmac_f32_e32 v87, s60, v23
	v_fmac_f32_e32 v87, s59, v59
	v_fmac_f32_e32 v87, s58, v27
	v_fmac_f32_e32 v87, s57, v63
	v_min_f32_e32 v88, 0, v87
	v_mul_f32_e64 v87, |v87|, s74
	v_exp_f32_e32 v87, v87
	s_nop 0
	v_add_f32_e32 v87, 1.0, v87
	v_log_f32_e32 v87, v87
	s_nop 0
	v_fma_f32 v87, v88, s75, -v87
	v_fmac_f32_e32 v81, 0x3d800000, v87
	v_exp_f32_e32 v87, v81
	s_nop 0
	v_mul_f32_e32 v131, v87, v82
	v_mul_f32_e32 v82, 0x3e000000, v83
	v_min_f32_e64 v83, -v81, s61
	v_exp_f32_e32 v83, v83
	s_nop 0
	v_mul_f32_e32 v83, v83, v82
	v_cvt_pk_bf16_f32 v82, v86, v85
	v_cvt_pk_bf16_f32 v83, v84, v83
	v_add_co_u32_e32 v84, vcc, 0x65600000, v116
	global_store_dwordx2 v[138:139], v[82:83], off offset:1024
	v_cvt_pk_bf16_f32 v82, v179, v178
	v_cvt_pk_bf16_f32 v83, v161, v131
	v_addc_co_u32_e32 v85, vcc, 0, v117, vcc
	global_store_dwordx2 v[84:85], v[82:83], off offset:1024
	v_add_u32_e32 v82, 0x10100, v180
	ds_read_b128 v[86:89], v82
	v_add_u32_e32 v82, 0x10110, v180
	ds_read_b128 v[82:85], v82
	s_and_b64 vcc, exec, s[42:43]
	s_cbranch_vccnz .LBB0_708
	s_waitcnt lgkmcnt(1)
	v_cndmask_b32_e64 v86, v86, v74, s[38:39]
	s_nop 1
	v_mov_b32_dpp v129, v127 row_shl:4 row_mask:0xf bank_mask:0x5
	v_mov_b32_dpp v129, v127 row_shr:4 row_mask:0xf bank_mask:0xa
	v_mov_b32_dpp v130, v126 row_shl:4 row_mask:0xf bank_mask:0x5
	v_mov_b32_dpp v130, v126 row_shr:4 row_mask:0xf bank_mask:0xa
	v_cndmask_b32_e64 v128, v87, v75, s[38:39]
	s_waitcnt lgkmcnt(0)
	v_cndmask_b32_e64 v141, v129, -v129, s[40:41]
	s_waitcnt lgkmcnt(0)
	v_cndmask_b32_e64 v140, v130, -v130, s[40:41]
	v_pk_mul_f32 v[128:129], v[128:129], v[140:141] op_sel_hi:[0,1]
	v_pk_fma_f32 v[126:127], v[86:87], v[126:127], v[128:129] op_sel_hi:[0,1,1]
	v_and_b32_e32 v87, 0xffff0000, v120
	s_and_b64 vcc, exec, s[42:43]
	v_and_b32_e32 v86, 0xffff0000, v118
	s_cbranch_vccz .LBB0_709

; __device__ __forceinline__ float bfe2(const v2u& w, int c) { return (c & 1) ? bfhi(w[c >> 1]) : bflo(w[c >> 1]); }
; template <int DIR> __device__ __forceinline__ void prep_gla_k(const ScanBufs<64>& B, const bf16* P, const float* w2g, const float* b2g, const f32x2* RR, const LAS f32x2* RC  , int g, int half, int lane, LAS v4u* Wl, LAS v4u* Gl  ) {
;     ...
;                     float k = bfe2(kr[j], c), q = bfe2(qr2[j], c);
;                     if (lat) { const f32x2 cs = csc[c]; const float pt = __shfl_xor(k, 4), pq = __shfl_xor(q, 4); k = k * cs.x + (second ? pt : -pt) * cs.y; q = q * cs.x + (second ? pq : -pq) * cs.y; }
.LBB0_707:
	s_waitcnt lgkmcnt(0)
	v_cndmask_b32_e64 v82, v82, v70, s[38:39]
	s_nop 1
	v_mov_b32_dpp v120, v89 row_shl:4 row_mask:0xf bank_mask:0x5
	v_mov_b32_dpp v120, v89 row_shr:4 row_mask:0xf bank_mask:0xa
	v_mov_b32_dpp v128, v88 row_shl:4 row_mask:0xf bank_mask:0x5
	v_mov_b32_dpp v128, v88 row_shr:4 row_mask:0xf bank_mask:0xa
	v_cndmask_b32_e64 v118, v83, v71, s[38:39]
	s_waitcnt lgkmcnt(0)
	v_cndmask_b32_e64 v129, v120, -v120, s[40:41]
	s_waitcnt lgkmcnt(0)
	v_cndmask_b32_e64 v128, v128, -v128, s[40:41]
	v_pk_mul_f32 v[128:129], v[118:119], v[128:129] op_sel_hi:[0,1]
	v_pk_fma_f32 v[88:89], v[82:83], v[88:89], v[128:129] op_sel_hi:[0,1,1]
	v_and_b32_e32 v83, 0xffff0000, v121
	s_and_b64 vcc, exec, s[42:43]
	v_and_b32_e32 v82, 0xffff0000, v119
	s_cbranch_vccz .LBB0_711
	s_branch .LBB0_712

; __device__ __forceinline__ float bfe2(const v2u& w, int c) { return (c & 1) ? bfhi(w[c >> 1]) : bflo(w[c >> 1]); }
; template <int DIR> __device__ __forceinline__ void prep_gla_k(const ScanBufs<64>& B, const bf16* P, const float* w2g, const float* b2g, const f32x2* RR, const LAS f32x2* RC  , int g, int half, int lane, LAS v4u* Wl, LAS v4u* Gl  ) {
;     ...
;                     float k = bfe2(kr[j], c), q = bfe2(qr2[j], c);
;                     if (lat) { const f32x2 cs = csc[c]; const float pt = __shfl_xor(k, 4), pq = __shfl_xor(q, 4); k = k * cs.x + (second ? pt : -pt) * cs.y; q = q * cs.x + (second ? pq : -pq) * cs.y; }
.LBB0_709:
	v_cndmask_b32_e64 v88, v88, v76, s[38:39]
	s_nop 0
	s_nop 1
	v_mov_b32_dpp v120, v87 row_shl:4 row_mask:0xf bank_mask:0x5
	v_mov_b32_dpp v120, v87 row_shr:4 row_mask:0xf bank_mask:0xa
	v_mov_b32_dpp v128, v86 row_shl:4 row_mask:0xf bank_mask:0x5
	v_mov_b32_dpp v128, v86 row_shr:4 row_mask:0xf bank_mask:0xa
	v_cndmask_b32_e64 v118, v89, v77, s[38:39]
	s_waitcnt lgkmcnt(0)
	v_cndmask_b32_e64 v129, v120, -v120, s[40:41]
	s_waitcnt lgkmcnt(0)
	v_cndmask_b32_e64 v128, v128, -v128, s[40:41]
	v_pk_mul_f32 v[128:129], v[118:119], v[128:129] op_sel_hi:[0,1]
	v_pk_fma_f32 v[86:87], v[88:89], v[86:87], v[128:129] op_sel_hi:[0,1,1]
	v_lshlrev_b32_e32 v89, 16, v121
	s_and_b64 vcc, exec, s[42:43]
	v_lshlrev_b32_e32 v88, 16, v119
	s_cbranch_vccz .LBB0_707

; #define GAS __attribute__((address_space(1)))
; __device__ __forceinline__ unsigned pk2(float lo, float hi) { const f32x2_t v = {lo, hi}; const bf16x2_t b = __builtin_convertvector(v, bf16x2_t); return __builtin_bit_cast(unsigned, b); }
; __device__ __forceinline__ float ex2(float x) { return __builtin_amdgcn_exp2f(x); }
; __device__ __forceinline__ float bfe(const v4u& w, int c) { return (c & 1) ? bfhi(w[c >> 1]) : bflo(w[c >> 1]); }
; __device__ __forceinline__ float bfe2(const v2u& w, int c) { return (c & 1) ? bfhi(w[c >> 1]) : bflo(w[c >> 1]); }
; template <int DIR> __device__ __forceinline__ void prep_gla_k(const ScanBufs<64>& B, const bf16* P, const float* w2g, const float* b2g, const f32x2* RR, const LAS f32x2* RC  , int g, int half, int lane, LAS v4u* Wl, LAS v4u* Gl  ) {
;     ...
;                 for (int c = 0; c < 4; ++c) { float x = b2[c];
; #pragma unroll
;                     for (int r = 0; r < 8; ++r) { x += bfe(l0[j], r) * w2[r][c]; x += bfe(l1[j], r) * w2[8 + r][c]; }
;                     const float la = (fminf(x, 0.f) * 1.4426950408889634f - __log2f(1.f + __expf(-fabsf(x)))) * 0.0625f;
;                     float k = bfe2(kr[j], c), q = bfe2(qr2[j], c);
;                     if (lat) { const f32x2 cs = csc[c]; const float pt = __shfl_xor(k, 4), pq = __shfl_xor(q, 4); k = k * cs.x + (second ? pt : -pt) * cs.y; q = q * cs.x + (second ? pq : -pq) * cs.y; }
;                     const float e = cum[c]; cum[c] += la; kv[c] = k * ex2(e); kp[hf * 4 + j][c] = kv[c]; ev[c] = q * 0.125f * ex2(fminf(-e, 126.f)); }
;                 { v2u ew; ew.x = pk2(ev[0], ev[1]); ew.y = pk2(ev[2], ev[3]); *(GAS v2u*)(Ep + (size_t)t * 512) = ew; }
;                 { v2u kw; kw.x = pk2(kv[0], kv[1]); kw.y = pk2(kv[2], kv[3]); *(GAS v2u*)(Kp + (size_t)t * 512) = kw; } } }
.LBB0_711:
	v_cndmask_b32_e64 v84, v84, v72, s[38:39]
	s_nop 0
	s_nop 1
	v_mov_b32_dpp v119, v83 row_shl:4 row_mask:0xf bank_mask:0x5
	v_mov_b32_dpp v119, v83 row_shr:4 row_mask:0xf bank_mask:0xa
	v_mov_b32_dpp v120, v82 row_shl:4 row_mask:0xf bank_mask:0x5
	v_mov_b32_dpp v120, v82 row_shr:4 row_mask:0xf bank_mask:0xa
	v_cndmask_b32_e64 v118, v85, v73, s[38:39]
	s_waitcnt lgkmcnt(0)
	v_cndmask_b32_e64 v121, v119, -v119, s[40:41]
	s_waitcnt lgkmcnt(0)
	v_cndmask_b32_e64 v120, v120, -v120, s[40:41]
	v_pk_mul_f32 v[118:119], v[118:119], v[120:121] op_sel_hi:[0,1]
	v_pk_fma_f32 v[82:83], v[84:85], v[82:83], v[118:119] op_sel_hi:[0,1,1]
.LBB0_712:
	s_lshl_b32 s65, s54, 16
	s_lshl_b32 s64, s56, 16
	v_fma_f32 v84, s65, v2, v68
	s_and_b32 s63, s54, 0xffff0000
	v_fmac_f32_e32 v84, s64, v30
	s_and_b32 s62, s56, 0xffff0000
	v_fmac_f32_e32 v84, s63, v6
	s_lshl_b32 s61, s51, 16
	v_fmac_f32_e32 v84, s62, v38
	s_lshl_b32 s60, s55, 16
	v_fmac_f32_e32 v84, s61, v10
	s_and_b32 s59, s51, 0xffff0000
	v_fmac_f32_e32 v84, s60, v42
	s_and_b32 s58, s55, 0xffff0000
	v_fmac_f32_e32 v84, s59, v14
	s_lshl_b32 s57, s50, 16
	v_fmac_f32_e32 v84, s58, v46
	s_lshl_b32 s56, s52, 16
	v_fmac_f32_e32 v84, s57, v18
	s_and_b32 s55, s50, 0xffff0000
	v_fmac_f32_e32 v84, s56, v54
	s_and_b32 s54, s52, 0xffff0000
	v_fmac_f32_e32 v84, s55, v34
	s_lshl_b32 s52, s49, 16
	v_fmac_f32_e32 v84, s54, v50
	s_lshl_b32 s51, s53, 16
	v_fmac_f32_e32 v84, s52, v22
	s_and_b32 s50, s49, 0xffff0000
	v_fmac_f32_e32 v84, s51, v58
	s_and_b32 s49, s53, 0xffff0000
	v_fmac_f32_e32 v84, s50, v26
	v_fmac_f32_e32 v84, s49, v62
	s_mov_b32 s66, 0xbfb8aa3b
	v_min_f32_e32 v85, 0, v84
	v_mul_f32_e64 v84, |v84|, s66
	v_exp_f32_e32 v84, v84
	s_mov_b32 s67, 0x3fb8aa3b
	s_mov_b32 s53, 0x42fc0000
	s_waitcnt vmcnt(12)
	v_lshlrev_b32_e32 v119, 16, v112
	v_add_f32_e32 v84, 1.0, v84
	v_log_f32_e32 v84, v84
	v_lshlrev_b32_e32 v118, 16, v110
	v_fma_f32 v84, v85, s67, -v84
	v_fmac_f32_e32 v80, 0x3d800000, v84
	v_exp_f32_e32 v84, v80
	v_min_f32_e64 v85, -v80, s53
	v_exp_f32_e32 v85, v85
	v_mul_f32_e32 v130, v84, v88
	v_mul_f32_e32 v84, 0x3e000000, v89
	v_mul_f32_e32 v84, v85, v84
	v_fma_f32 v85, s65, v1, v67
	v_fmac_f32_e32 v85, s64, v29
	v_fmac_f32_e32 v85, s63, v5
	v_fmac_f32_e32 v85, s62, v37
	v_fmac_f32_e32 v85, s61, v9
	v_fmac_f32_e32 v85, s60, v41
	v_fmac_f32_e32 v85, s59, v13
	v_fmac_f32_e32 v85, s58, v45
	v_fmac_f32_e32 v85, s57, v17
	v_fmac_f32_e32 v85, s56, v53
	v_fmac_f32_e32 v85, s55, v33
	v_fmac_f32_e32 v85, s54, v49
	v_fmac_f32_e32 v85, s52, v21
	v_fmac_f32_e32 v85, s51, v57
	v_fmac_f32_e32 v85, s50, v25
	v_fmac_f32_e32 v85, s49, v61
	v_min_f32_e32 v88, 0, v85
	v_mul_f32_e64 v85, |v85|, s66
	v_exp_f32_e32 v85, v85
	s_nop 0
	v_add_f32_e32 v85, 1.0, v85
	v_log_f32_e32 v85, v85
	s_nop 0
	v_fma_f32 v85, v88, s67, -v85
	v_fmac_f32_e32 v79, 0x3d800000, v85
	v_exp_f32_e32 v85, v79
	s_nop 0
	v_mul_f32_e32 v181, v85, v86
	v_min_f32_e64 v86, -v79, s53
	v_exp_f32_e32 v86, v86
	v_mul_f32_e32 v85, 0x3e000000, v87
	v_mul_f32_e32 v85, v86, v85
	v_fma_f32 v86, s65, v0, v66
	v_fmac_f32_e32 v86, s64, v28
	v_fmac_f32_e32 v86, s63, v4
	v_fmac_f32_e32 v86, s62, v36
	v_fmac_f32_e32 v86, s61, v8
	v_fmac_f32_e32 v86, s60, v40
	v_fmac_f32_e32 v86, s59, v12
	v_fmac_f32_e32 v86, s58, v44
	v_fmac_f32_e32 v86, s57, v16
	v_fmac_f32_e32 v86, s56, v52
	v_fmac_f32_e32 v86, s55, v32
	v_fmac_f32_e32 v86, s54, v48
	v_fmac_f32_e32 v86, s52, v20
	v_fmac_f32_e32 v86, s51, v56
	v_fmac_f32_e32 v86, s50, v24
	v_fmac_f32_e32 v86, s49, v60
	v_min_f32_e32 v87, 0, v86
	v_mul_f32_e64 v86, |v86|, s66
	v_exp_f32_e32 v86, v86
	s_nop 0
	v_add_f32_e32 v86, 1.0, v86
	v_log_f32_e32 v86, v86
	s_nop 0
	v_fma_f32 v86, v87, s67, -v86
	v_fmac_f32_e32 v78, 0x3d800000, v86
	v_exp_f32_e32 v86, v78
	v_min_f32_e64 v87, -v78, s53
	v_exp_f32_e32 v87, v87
	v_mul_f32_e32 v136, v86, v126
	v_mul_f32_e32 v86, 0x3e000000, v127
	v_mul_f32_e32 v86, v87, v86
	v_fma_f32 v87, s65, v3, v69
	v_fmac_f32_e32 v87, s64, v31
	v_fmac_f32_e32 v87, s63, v7
	v_fmac_f32_e32 v87, s62, v39
	v_fmac_f32_e32 v87, s61, v11
	v_fmac_f32_e32 v87, s60, v43
	v_fmac_f32_e32 v87, s59, v15
	v_fmac_f32_e32 v87, s58, v47
	v_fmac_f32_e32 v87, s57, v19
	v_fmac_f32_e32 v87, s56, v55
	v_fmac_f32_e32 v87, s55, v35
	v_fmac_f32_e32 v87, s54, v51
	v_fmac_f32_e32 v87, s52, v23
	v_fmac_f32_e32 v87, s51, v59
	v_fmac_f32_e32 v87, s50, v27
	v_fmac_f32_e32 v87, s49, v63
	v_min_f32_e32 v88, 0, v87
	v_mul_f32_e64 v87, |v87|, s66
	v_exp_f32_e32 v87, v87
	s_nop 0
	v_add_f32_e32 v87, 1.0, v87
	v_log_f32_e32 v87, v87
	s_nop 0
	v_fma_f32 v87, v88, s67, -v87
	v_fmac_f32_e32 v81, 0x3d800000, v87
	v_exp_f32_e32 v87, v81
	s_nop 0
	v_mul_f32_e32 v182, v87, v82
	v_mul_f32_e32 v82, 0x3e000000, v83
	v_min_f32_e64 v83, -v81, s53
	v_exp_f32_e32 v83, v83
	s_nop 0
	v_mul_f32_e32 v83, v83, v82
	v_cvt_pk_bf16_f32 v82, v86, v85
	v_cvt_pk_bf16_f32 v83, v84, v83
	v_add_co_u32_e32 v84, vcc, 0x65600000, v116
	global_store_dwordx2 v[138:139], v[82:83], off offset:2048
	v_cvt_pk_bf16_f32 v82, v136, v181
	v_cvt_pk_bf16_f32 v83, v130, v182
	v_addc_co_u32_e32 v85, vcc, 0, v117, vcc
	global_store_dwordx2 v[84:85], v[82:83], off offset:2048
	v_add_u32_e32 v82, 0x10180, v180
	ds_read_b128 v[86:89], v82
	v_add_u32_e32 v82, 0x10190, v180
	ds_read_b128 v[82:85], v82
	s_and_b64 vcc, exec, s[42:43]
	s_cbranch_vccnz .LBB0_716
	s_waitcnt lgkmcnt(1)
	v_cndmask_b32_e64 v86, v86, v74, s[38:39]
	s_nop 1
	v_mov_b32_dpp v121, v119 row_shl:4 row_mask:0xf bank_mask:0x5
	v_mov_b32_dpp v121, v119 row_shr:4 row_mask:0xf bank_mask:0xa
	v_mov_b32_dpp v126, v118 row_shl:4 row_mask:0xf bank_mask:0x5
	v_mov_b32_dpp v126, v118 row_shr:4 row_mask:0xf bank_mask:0xa
	v_cndmask_b32_e64 v120, v87, v75, s[38:39]
	s_waitcnt lgkmcnt(0)
	v_cndmask_b32_e64 v127, v121, -v121, s[40:41]
	s_waitcnt lgkmcnt(0)
	v_cndmask_b32_e64 v126, v126, -v126, s[40:41]
	v_pk_mul_f32 v[120:121], v[120:121], v[126:127] op_sel_hi:[0,1]
	v_pk_fma_f32 v[118:119], v[86:87], v[118:119], v[120:121] op_sel_hi:[0,1,1]
	v_and_b32_e32 v87, 0xffff0000, v112
	s_and_b64 vcc, exec, s[42:43]
	v_and_b32_e32 v86, 0xffff0000, v110
	s_cbranch_vccz .LBB0_717

; __device__ __forceinline__ float bfe2(const v2u& w, int c) { return (c & 1) ? bfhi(w[c >> 1]) : bflo(w[c >> 1]); }
; template <int DIR> __device__ __forceinline__ void prep_gla_k(const ScanBufs<64>& B, const bf16* P, const float* w2g, const float* b2g, const f32x2* RR, const LAS f32x2* RC  , int g, int half, int lane, LAS v4u* Wl, LAS v4u* Gl  ) {
;     ...
;                     float k = bfe2(kr[j], c), q = bfe2(qr2[j], c);
;                     if (lat) { const f32x2 cs = csc[c]; const float pt = __shfl_xor(k, 4), pq = __shfl_xor(q, 4); k = k * cs.x + (second ? pt : -pt) * cs.y; q = q * cs.x + (second ? pq : -pq) * cs.y; }
.LBB0_715:
	s_waitcnt lgkmcnt(0)
	v_cndmask_b32_e64 v82, v82, v70, s[38:39]
	s_nop 1
	v_mov_b32_dpp v112, v89 row_shl:4 row_mask:0xf bank_mask:0x5
	v_mov_b32_dpp v112, v89 row_shr:4 row_mask:0xf bank_mask:0xa
	v_mov_b32_dpp v120, v88 row_shl:4 row_mask:0xf bank_mask:0x5
	v_mov_b32_dpp v120, v88 row_shr:4 row_mask:0xf bank_mask:0xa
	v_cndmask_b32_e64 v110, v83, v71, s[38:39]
	s_waitcnt lgkmcnt(0)
	v_cndmask_b32_e64 v121, v112, -v112, s[40:41]
	s_waitcnt lgkmcnt(0)
	v_cndmask_b32_e64 v120, v120, -v120, s[40:41]
	v_pk_mul_f32 v[120:121], v[110:111], v[120:121] op_sel_hi:[0,1]
	v_pk_fma_f32 v[88:89], v[82:83], v[88:89], v[120:121] op_sel_hi:[0,1,1]
	v_and_b32_e32 v83, 0xffff0000, v113
	s_and_b64 vcc, exec, s[42:43]
	v_and_b32_e32 v82, 0xffff0000, v111
	s_cbranch_vccz .LBB0_719
	s_branch .LBB0_720

; __device__ __forceinline__ float bfe2(const v2u& w, int c) { return (c & 1) ? bfhi(w[c >> 1]) : bflo(w[c >> 1]); }
; template <int DIR> __device__ __forceinline__ void prep_gla_k(const ScanBufs<64>& B, const bf16* P, const float* w2g, const float* b2g, const f32x2* RR, const LAS f32x2* RC  , int g, int half, int lane, LAS v4u* Wl, LAS v4u* Gl  ) {
;     ...
;                     float k = bfe2(kr[j], c), q = bfe2(qr2[j], c);
;                     if (lat) { const f32x2 cs = csc[c]; const float pt = __shfl_xor(k, 4), pq = __shfl_xor(q, 4); k = k * cs.x + (second ? pt : -pt) * cs.y; q = q * cs.x + (second ? pq : -pq) * cs.y; }
.LBB0_717:
	v_cndmask_b32_e64 v88, v88, v76, s[38:39]
	s_nop 0
	s_nop 1
	v_mov_b32_dpp v112, v87 row_shl:4 row_mask:0xf bank_mask:0x5
	v_mov_b32_dpp v112, v87 row_shr:4 row_mask:0xf bank_mask:0xa
	v_mov_b32_dpp v120, v86 row_shl:4 row_mask:0xf bank_mask:0x5
	v_mov_b32_dpp v120, v86 row_shr:4 row_mask:0xf bank_mask:0xa
	v_cndmask_b32_e64 v110, v89, v77, s[38:39]
	s_waitcnt lgkmcnt(0)
	v_cndmask_b32_e64 v121, v112, -v112, s[40:41]
	s_waitcnt lgkmcnt(0)
	v_cndmask_b32_e64 v120, v120, -v120, s[40:41]
	v_pk_mul_f32 v[120:121], v[110:111], v[120:121] op_sel_hi:[0,1]
	v_pk_fma_f32 v[86:87], v[88:89], v[86:87], v[120:121] op_sel_hi:[0,1,1]
	v_lshlrev_b32_e32 v89, 16, v113
	s_and_b64 vcc, exec, s[42:43]
	v_lshlrev_b32_e32 v88, 16, v111
	s_cbranch_vccz .LBB0_715

; __device__ __forceinline__ float bfe2(const v2u& w, int c) { return (c & 1) ? bfhi(w[c >> 1]) : bflo(w[c >> 1]); }
; template <int DIR> __device__ __forceinline__ void prep_gla_k(const ScanBufs<64>& B, const bf16* P, const float* w2g, const float* b2g, const f32x2* RR, const LAS f32x2* RC  , int g, int half, int lane, LAS v4u* Wl, LAS v4u* Gl  ) {
;     ...
;                     float k = bfe2(kr[j], c), q = bfe2(qr2[j], c);
;                     if (lat) { const f32x2 cs = csc[c]; const float pt = __shfl_xor(k, 4), pq = __shfl_xor(q, 4); k = k * cs.x + (second ? pt : -pt) * cs.y; q = q * cs.x + (second ? pq : -pq) * cs.y; }
.LBB0_719:
	v_cndmask_b32_e64 v84, v84, v72, s[38:39]
	s_nop 0
	s_nop 1
	v_mov_b32_dpp v111, v83 row_shl:4 row_mask:0xf bank_mask:0x5
	v_mov_b32_dpp v111, v83 row_shr:4 row_mask:0xf bank_mask:0xa
	v_mov_b32_dpp v112, v82 row_shl:4 row_mask:0xf bank_mask:0x5
	v_mov_b32_dpp v112, v82 row_shr:4 row_mask:0xf bank_mask:0xa
	v_cndmask_b32_e64 v110, v85, v73, s[38:39]
	s_waitcnt lgkmcnt(0)
	v_cndmask_b32_e64 v113, v111, -v111, s[40:41]
	s_waitcnt lgkmcnt(0)
	v_cndmask_b32_e64 v112, v112, -v112, s[40:41]
	v_pk_mul_f32 v[110:111], v[110:111], v[112:113] op_sel_hi:[0,1]
	v_pk_fma_f32 v[82:83], v[84:85], v[82:83], v[110:111] op_sel_hi:[0,1,1]

; #define LAS __attribute__((address_space(3)))
; __device__ __forceinline__ float bfe(const v4u& w, int c) { return (c & 1) ? bfhi(w[c >> 1]) : bflo(w[c >> 1]); }
; __device__ __forceinline__ float bfe2(const v2u& w, int c) { return (c & 1) ? bfhi(w[c >> 1]) : bflo(w[c >> 1]); }
; template <int DIR> __device__ __forceinline__ void prep_gla_k(const ScanBufs<64>& B, const bf16* P, const float* w2g, const float* b2g, const f32x2* RR, const LAS f32x2* RC  , int g, int half, int lane, LAS v4u* Wl, LAS v4u* Gl  ) {
;     ...
;             for (int j = 0; j < 4; ++j) { const int tt_ = t8 * 8 + hf * 4 + j; l0[j] = Gl[2 * tt_]; l1[j] = Gl[2 * tt_ + 1]; }
; #pragma unroll
;             for (int jj = 0; jj < 4; ++jj) { const int j = DIR ? jj : 3 - jj; const int t = t8 * 8 + hf * 4 + j; float ev[4], kv[4];
;                 f32x2 csc[4];
;                 { const LAS f32x4* rc4 = (const LAS f32x4*)(RC + t * 16 + j0); const f32x4 ra = rc4[0], rb = rc4[1];
;                   csc[0] = isrow ? csr[0] : (f32x2){ra[0], ra[1]}; csc[1] = isrow ? csr[1] : (f32x2){ra[2], ra[3]}; csc[2] = isrow ? csr[2] : (f32x2){rb[0], rb[1]}; csc[3] = isrow ? csr[3] : (f32x2){rb[2], rb[3]}; }
; #pragma unroll
;                 for (int c = 0; c < 4; ++c) { float x = b2[c];
; #pragma unroll
;                     for (int r = 0; r < 8; ++r) { x += bfe(l0[j], r) * w2[r][c]; x += bfe(l1[j], r) * w2[8 + r][c]; }
;                     const float la = (fminf(x, 0.f) * 1.4426950408889634f - __log2f(1.f + __expf(-fabsf(x)))) * 0.0625f;
;                     float k = bfe2(kr[j], c), q = bfe2(qr2[j], c);
;                     if (lat) { const f32x2 cs = csc[c]; const float pt = __shfl_xor(k, 4), pq = __shfl_xor(q, 4); k = k * cs.x + (second ? pt : -pt) * cs.y; q = q * cs.x + (second ? pq : -pq) * cs.y; }
.LBB0_722:
	s_add_i32 s33, s31, 0x12080
	v_mov_b32_e32 v82, s33
	ds_read_b128 v[82:85], v82
	s_add_i32 s33, s31, 0x12090
	s_add_i32 s34, s31, 0x120b0
	s_add_i32 s46, s31, 0x120d0
	v_lshlrev_b32_e32 v151, 16, v148
	s_waitcnt lgkmcnt(0)
	v_readfirstlane_b32 s67, v82
	v_mov_b32_e32 v82, s33
	v_readfirstlane_b32 s66, v83
	v_readfirstlane_b32 s65, v84
	v_readfirstlane_b32 s64, v85
	ds_read_b128 v[82:85], v82
	s_add_i32 s33, s31, 0x120a0
	v_lshlrev_b32_e32 v150, 16, v146
	s_and_b64 vcc, exec, s[42:43]
	s_waitcnt lgkmcnt(0)
	v_readfirstlane_b32 s71, v82
	v_mov_b32_e32 v82, s33
	v_readfirstlane_b32 s70, v83
	v_readfirstlane_b32 s69, v84
	v_readfirstlane_b32 s68, v85
	ds_read_b128 v[82:85], v82
	s_waitcnt lgkmcnt(0)
	v_readfirstlane_b32 s59, v82
	v_mov_b32_e32 v82, s34
	v_readfirstlane_b32 s58, v83
	v_readfirstlane_b32 s57, v84
	v_readfirstlane_b32 s33, v85
	ds_read_b128 v[82:85], v82
	s_add_i32 s34, s31, 0x120c0
	s_waitcnt lgkmcnt(0)
	v_readfirstlane_b32 s63, v82
	v_mov_b32_e32 v82, s34
	v_readfirstlane_b32 s62, v83
	v_readfirstlane_b32 s61, v84
	v_readfirstlane_b32 s60, v85
	ds_read_b128 v[82:85], v82
	s_waitcnt lgkmcnt(0)
	v_readfirstlane_b32 s37, v82
	v_mov_b32_e32 v82, s46
	v_readfirstlane_b32 s36, v83
	v_readfirstlane_b32 s35, v84
	v_readfirstlane_b32 s34, v85
	ds_read_b128 v[82:85], v82
	s_add_i32 s46, s31, 0x120e0
	s_add_i32 s31, s31, 0x120f0
	s_waitcnt lgkmcnt(0)
	v_readfirstlane_b32 s53, v82
	v_mov_b32_e32 v82, s46
	v_readfirstlane_b32 s52, v83
	v_readfirstlane_b32 s50, v84
	v_readfirstlane_b32 s48, v85
	ds_read_b128 v[82:85], v82
	s_waitcnt lgkmcnt(0)
	v_readfirstlane_b32 s51, v82
	v_mov_b32_e32 v82, s31
	v_readfirstlane_b32 s49, v83
	v_readfirstlane_b32 s47, v84
	v_readfirstlane_b32 s46, v85
	ds_read_b128 v[82:85], v82
	s_waitcnt lgkmcnt(0)
	v_readfirstlane_b32 s56, v82
	v_add_u32_e32 v82, 0x10200, v180
	ds_read_b128 v[86:89], v82
	v_add_u32_e32 v82, 0x10210, v180
	v_readfirstlane_b32 s55, v83
	v_readfirstlane_b32 s54, v84
	v_readfirstlane_b32 s31, v85
	ds_read_b128 v[82:85], v82
	s_cbranch_vccnz .LBB0_745
	s_waitcnt lgkmcnt(1)
	v_cndmask_b32_e64 v86, v86, v74, s[38:39]
	s_nop 1
	v_mov_b32_dpp v153, v151 row_shl:4 row_mask:0xf bank_mask:0x5
	v_mov_b32_dpp v153, v151 row_shr:4 row_mask:0xf bank_mask:0xa
	v_mov_b32_dpp v187, v150 row_shl:4 row_mask:0xf bank_mask:0x5
	v_mov_b32_dpp v187, v150 row_shr:4 row_mask:0xf bank_mask:0xa
	v_cndmask_b32_e64 v152, v87, v75, s[38:39]
	s_waitcnt lgkmcnt(0)
	v_cndmask_b32_e64 v189, v153, -v153, s[40:41]
	s_waitcnt lgkmcnt(0)
	v_cndmask_b32_e64 v188, v187, -v187, s[40:41]
	v_pk_mul_f32 v[152:153], v[152:153], v[188:189] op_sel_hi:[0,1]
	v_pk_fma_f32 v[150:151], v[86:87], v[150:151], v[152:153] op_sel_hi:[0,1,1]
	v_and_b32_e32 v87, 0xffff0000, v148
	s_and_b64 vcc, exec, s[42:43]
	v_and_b32_e32 v86, 0xffff0000, v146
	s_cbranch_vccz .LBB0_746

; __device__ __forceinline__ float bfe2(const v2u& w, int c) { return (c & 1) ? bfhi(w[c >> 1]) : bflo(w[c >> 1]); }
; template <int DIR> __device__ __forceinline__ void prep_gla_k(const ScanBufs<64>& B, const bf16* P, const float* w2g, const float* b2g, const f32x2* RR, const LAS f32x2* RC  , int g, int half, int lane, LAS v4u* Wl, LAS v4u* Gl  ) {
;     ...
;                     float k = bfe2(kr[j], c), q = bfe2(qr2[j], c);
;                     if (lat) { const f32x2 cs = csc[c]; const float pt = __shfl_xor(k, 4), pq = __shfl_xor(q, 4); k = k * cs.x + (second ? pt : -pt) * cs.y; q = q * cs.x + (second ? pq : -pq) * cs.y; }
.LBB0_725:
	s_waitcnt lgkmcnt(0)
	v_cndmask_b32_e64 v82, v82, v70, s[38:39]
	s_nop 1
	v_mov_b32_dpp v148, v89 row_shl:4 row_mask:0xf bank_mask:0x5
	v_mov_b32_dpp v148, v89 row_shr:4 row_mask:0xf bank_mask:0xa
	v_mov_b32_dpp v152, v88 row_shl:4 row_mask:0xf bank_mask:0x5
	v_mov_b32_dpp v152, v88 row_shr:4 row_mask:0xf bank_mask:0xa
	v_cndmask_b32_e64 v146, v83, v71, s[38:39]
	s_waitcnt lgkmcnt(0)
	v_cndmask_b32_e64 v153, v148, -v148, s[40:41]
	s_waitcnt lgkmcnt(0)
	v_cndmask_b32_e64 v152, v152, -v152, s[40:41]
	v_pk_mul_f32 v[152:153], v[146:147], v[152:153] op_sel_hi:[0,1]
	v_pk_fma_f32 v[88:89], v[82:83], v[88:89], v[152:153] op_sel_hi:[0,1,1]
.LBB0_726:
	s_mov_b32 s87, s77
	s_waitcnt lgkmcnt(0)
	v_and_b32_e32 v83, 0xffff0000, v149
	s_and_b64 vcc, exec, s[42:43]
	v_and_b32_e32 v82, 0xffff0000, v147
	s_cbranch_vccnz .LBB0_728
	v_cndmask_b32_e64 v84, v84, v72, s[38:39]
	s_nop 0
	s_nop 1
	v_mov_b32_dpp v147, v83 row_shl:4 row_mask:0xf bank_mask:0x5
	v_mov_b32_dpp v147, v83 row_shr:4 row_mask:0xf bank_mask:0xa
	v_mov_b32_dpp v148, v82 row_shl:4 row_mask:0xf bank_mask:0x5
	v_mov_b32_dpp v148, v82 row_shr:4 row_mask:0xf bank_mask:0xa
	v_cndmask_b32_e64 v146, v85, v73, s[38:39]
	s_waitcnt lgkmcnt(0)
	v_cndmask_b32_e64 v149, v147, -v147, s[40:41]
	s_waitcnt lgkmcnt(0)
	v_cndmask_b32_e64 v148, v148, -v148, s[40:41]
	v_pk_mul_f32 v[146:147], v[146:147], v[148:149] op_sel_hi:[0,1]
	v_pk_fma_f32 v[82:83], v[84:85], v[82:83], v[146:147] op_sel_hi:[0,1,1]
; #define GAS __attribute__((address_space(1)))
; __device__ __forceinline__ unsigned pk2(float lo, float hi) { const f32x2_t v = {lo, hi}; const bf16x2_t b = __builtin_convertvector(v, bf16x2_t); return __builtin_bit_cast(unsigned, b); }
; __device__ __forceinline__ float ex2(float x) { return __builtin_amdgcn_exp2f(x); }
; __device__ __forceinline__ float bfe(const v4u& w, int c) { return (c & 1) ? bfhi(w[c >> 1]) : bflo(w[c >> 1]); }
; __device__ __forceinline__ float bfe2(const v2u& w, int c) { return (c & 1) ? bfhi(w[c >> 1]) : bflo(w[c >> 1]); }
; template <int DIR> __device__ __forceinline__ void prep_gla_k(const ScanBufs<64>& B, const bf16* P, const float* w2g, const float* b2g, const f32x2* RR, const LAS f32x2* RC  , int g, int half, int lane, LAS v4u* Wl, LAS v4u* Gl  ) {
;     ...
;                 for (int c = 0; c < 4; ++c) { float x = b2[c];
; #pragma unroll
;                     for (int r = 0; r < 8; ++r) { x += bfe(l0[j], r) * w2[r][c]; x += bfe(l1[j], r) * w2[8 + r][c]; }
;                     const float la = (fminf(x, 0.f) * 1.4426950408889634f - __log2f(1.f + __expf(-fabsf(x)))) * 0.0625f;
;                     float k = bfe2(kr[j], c), q = bfe2(qr2[j], c);
;                     if (lat) { const f32x2 cs = csc[c]; const float pt = __shfl_xor(k, 4), pq = __shfl_xor(q, 4); k = k * cs.x + (second ? pt : -pt) * cs.y; q = q * cs.x + (second ? pq : -pq) * cs.y; }
;                     const float e = cum[c]; cum[c] += la; kv[c] = k * ex2(e); kp[hf * 4 + j][c] = kv[c]; ev[c] = q * 0.125f * ex2(fminf(-e, 126.f)); }
;                 { v2u ew; ew.x = pk2(ev[0], ev[1]); ew.y = pk2(ev[2], ev[3]); *(GAS v2u*)(Ep + (size_t)t * 512) = ew; }
;                 { v2u kw; kw.x = pk2(kv[0], kv[1]); kw.y = pk2(kv[2], kv[3]); *(GAS v2u*)(Kp + (size_t)t * 512) = kw; } } }
.LBB0_728:
	s_lshl_b32 s80, s28, 16
	s_lshl_b32 s79, s30, 16
	v_fma_f32 v84, s80, v2, v68
	s_and_b32 s78, s28, 0xffff0000
	v_fmac_f32_e32 v84, s79, v30
	s_and_b32 s77, s30, 0xffff0000
	v_fmac_f32_e32 v84, s78, v6
	s_lshl_b32 s76, s26, 16
	v_fmac_f32_e32 v84, s77, v38
	s_lshl_b32 s75, s29, 16
	v_fmac_f32_e32 v84, s76, v10
	s_and_b32 s74, s26, 0xffff0000
	v_fmac_f32_e32 v84, s75, v42
	s_and_b32 s73, s29, 0xffff0000
	v_fmac_f32_e32 v84, s74, v14
	s_lshl_b32 s72, s24, 16
	v_fmac_f32_e32 v84, s73, v46
	s_lshl_b32 s30, s27, 16
	v_fmac_f32_e32 v84, s72, v18
	s_and_b32 s29, s24, 0xffff0000
	v_fmac_f32_e32 v84, s30, v54
	s_and_b32 s28, s27, 0xffff0000
	v_fmac_f32_e32 v84, s29, v34
	s_lshl_b32 s27, s23, 16
	v_fmac_f32_e32 v84, s28, v50
	s_lshl_b32 s26, s25, 16
	v_fmac_f32_e32 v84, s27, v22
	s_and_b32 s24, s23, 0xffff0000
	v_fmac_f32_e32 v84, s26, v58
	s_and_b32 s23, s25, 0xffff0000
	v_fmac_f32_e32 v84, s24, v26
	v_fmac_f32_e32 v84, s23, v62
	s_mov_b32 s86, 0xbfb8aa3b
	v_min_f32_e32 v85, 0, v84
	v_mul_f32_e64 v84, |v84|, s86
	v_exp_f32_e32 v84, v84
	s_mov_b32 s92, 0x3fb8aa3b
	s_mov_b32 s25, 0x42fc0000
	v_lshlrev_b32_e32 v153, 16, v144
	v_add_f32_e32 v84, 1.0, v84
	v_log_f32_e32 v84, v84
	v_lshlrev_b32_e32 v152, 16, v142
	v_fma_f32 v84, v85, s92, -v84
	v_fmac_f32_e32 v80, 0x3d800000, v84
	v_exp_f32_e32 v84, v80
	v_min_f32_e64 v85, -v80, s25
	v_exp_f32_e32 v85, v85
	v_mul_f32_e32 v146, v84, v88
	v_mul_f32_e32 v84, 0x3e000000, v89
	v_mul_f32_e32 v84, v85, v84
	v_fma_f32 v85, s80, v1, v67
	v_fmac_f32_e32 v85, s79, v29
	v_fmac_f32_e32 v85, s78, v5
	v_fmac_f32_e32 v85, s77, v37
	v_fmac_f32_e32 v85, s76, v9
	v_fmac_f32_e32 v85, s75, v41
	v_fmac_f32_e32 v85, s74, v13
	v_fmac_f32_e32 v85, s73, v45
	v_fmac_f32_e32 v85, s72, v17
	v_fmac_f32_e32 v85, s30, v53
	v_fmac_f32_e32 v85, s29, v33
	v_fmac_f32_e32 v85, s28, v49
	v_fmac_f32_e32 v85, s27, v21
	v_fmac_f32_e32 v85, s26, v57
	v_fmac_f32_e32 v85, s24, v25
	v_fmac_f32_e32 v85, s23, v61
	v_min_f32_e32 v88, 0, v85
	v_mul_f32_e64 v85, |v85|, s86
	v_exp_f32_e32 v85, v85
	s_nop 0
	v_add_f32_e32 v85, 1.0, v85
	v_log_f32_e32 v85, v85
	s_nop 0
	v_fma_f32 v85, v88, s92, -v85
	v_fmac_f32_e32 v79, 0x3d800000, v85
	v_exp_f32_e32 v85, v79
	s_nop 0
	v_mul_f32_e32 v147, v85, v86
	v_min_f32_e64 v86, -v79, s25
	v_exp_f32_e32 v86, v86
	v_mul_f32_e32 v85, 0x3e000000, v87
	v_mul_f32_e32 v85, v86, v85
	v_fma_f32 v86, s80, v0, v66
	v_fmac_f32_e32 v86, s79, v28
	v_fmac_f32_e32 v86, s78, v4
	v_fmac_f32_e32 v86, s77, v36
	v_fmac_f32_e32 v86, s76, v8
	v_fmac_f32_e32 v86, s75, v40
	v_fmac_f32_e32 v86, s74, v12
	v_fmac_f32_e32 v86, s73, v44
	v_fmac_f32_e32 v86, s72, v16
	v_fmac_f32_e32 v86, s30, v52
	v_fmac_f32_e32 v86, s29, v32
	v_fmac_f32_e32 v86, s28, v48
	v_fmac_f32_e32 v86, s27, v20
	v_fmac_f32_e32 v86, s26, v56
	v_fmac_f32_e32 v86, s24, v24
	v_fmac_f32_e32 v86, s23, v60
	v_min_f32_e32 v87, 0, v86
	v_mul_f32_e64 v86, |v86|, s86
	v_exp_f32_e32 v86, v86
	s_nop 0
	v_add_f32_e32 v86, 1.0, v86
	v_log_f32_e32 v86, v86
	s_nop 0
	v_fma_f32 v86, v87, s92, -v86
	v_fmac_f32_e32 v78, 0x3d800000, v86
	v_exp_f32_e32 v86, v78
	v_min_f32_e64 v87, -v78, s25
	v_exp_f32_e32 v87, v87
	v_mul_f32_e32 v148, v86, v150
	v_mul_f32_e32 v86, 0x3e000000, v151
	v_mul_f32_e32 v86, v87, v86
	v_fma_f32 v87, s80, v3, v69
	v_fmac_f32_e32 v87, s79, v31
	v_fmac_f32_e32 v87, s78, v7
	v_fmac_f32_e32 v87, s77, v39
	v_fmac_f32_e32 v87, s76, v11
	v_fmac_f32_e32 v87, s75, v43
	v_fmac_f32_e32 v87, s74, v15
	v_fmac_f32_e32 v87, s73, v47
	v_fmac_f32_e32 v87, s72, v19
	v_fmac_f32_e32 v87, s30, v55
	v_fmac_f32_e32 v87, s29, v35
	v_fmac_f32_e32 v87, s28, v51
	v_fmac_f32_e32 v87, s27, v23
	v_fmac_f32_e32 v87, s26, v59
	v_fmac_f32_e32 v87, s24, v27
	v_fmac_f32_e32 v87, s23, v63
	v_min_f32_e32 v88, 0, v87
	v_mul_f32_e64 v87, |v87|, s86
	v_exp_f32_e32 v87, v87
	s_mov_b32 s23, 0x66801000
	v_add_co_u32_e32 v150, vcc, s23, v116
	v_add_f32_e32 v87, 1.0, v87
	v_log_f32_e32 v87, v87
	v_addc_co_u32_e32 v151, vcc, 0, v117, vcc
	v_fma_f32 v87, v88, s92, -v87
	v_fmac_f32_e32 v81, 0x3d800000, v87
	v_exp_f32_e32 v87, v81
	s_nop 0
	v_mul_f32_e32 v149, v87, v82
	v_mul_f32_e32 v82, 0x3e000000, v83
	v_min_f32_e64 v83, -v81, s25
	v_exp_f32_e32 v83, v83
	s_nop 0
	v_mul_f32_e32 v83, v83, v82
	v_cvt_pk_bf16_f32 v82, v86, v85
	v_cvt_pk_bf16_f32 v83, v84, v83
	v_add_co_u32_e32 v84, vcc, 0x65601000, v116
	global_store_dwordx2 v[150:151], v[82:83], off
	v_cvt_pk_bf16_f32 v82, v148, v147
	v_cvt_pk_bf16_f32 v83, v146, v149
	v_addc_co_u32_e32 v85, vcc, 0, v117, vcc
	global_store_dwordx2 v[84:85], v[82:83], off
	v_add_u32_e32 v82, 0x10280, v180
	ds_read_b128 v[86:89], v82
	v_add_u32_e32 v82, 0x10290, v180
	ds_read_b128 v[82:85], v82
	s_and_b64 vcc, exec, s[42:43]
	s_cbranch_vccnz .LBB0_730
	s_waitcnt lgkmcnt(1)
	v_cndmask_b32_e64 v188, v87, v75, s[38:39]
	v_cndmask_b32_e64 v86, v86, v74, s[38:39]
	s_nop 1
	v_mov_b32_dpp v189, v153 row_shl:4 row_mask:0xf bank_mask:0x5
	v_mov_b32_dpp v189, v153 row_shr:4 row_mask:0xf bank_mask:0xa
	v_mov_b32_dpp v187, v152 row_shl:4 row_mask:0xf bank_mask:0x5
	v_mov_b32_dpp v187, v152 row_shr:4 row_mask:0xf bank_mask:0xa
	s_waitcnt lgkmcnt(0)
	v_cndmask_b32_e64 v193, v189, -v189, s[40:41]
	s_waitcnt lgkmcnt(0)
	v_cndmask_b32_e64 v192, v187, -v187, s[40:41]
	v_pk_mul_f32 v[188:189], v[188:189], v[192:193] op_sel_hi:[0,1]
	v_pk_fma_f32 v[152:153], v[86:87], v[152:153], v[188:189] op_sel_hi:[0,1,1]
.LBB0_730:
	v_readlane_b32 s78, v245, 39
	s_waitcnt lgkmcnt(1)
	v_and_b32_e32 v87, 0xffff0000, v144
	s_and_b64 vcc, exec, s[42:43]
	v_and_b32_e32 v86, 0xffff0000, v142
	v_readlane_b32 s79, v245, 40
	s_cbranch_vccnz .LBB0_747
	v_cndmask_b32_e64 v88, v88, v76, s[38:39]
	s_nop 0
	s_nop 1
	v_mov_b32_dpp v144, v87 row_shl:4 row_mask:0xf bank_mask:0x5
	v_mov_b32_dpp v144, v87 row_shr:4 row_mask:0xf bank_mask:0xa
	v_mov_b32_dpp v187, v86 row_shl:4 row_mask:0xf bank_mask:0x5
	v_mov_b32_dpp v187, v86 row_shr:4 row_mask:0xf bank_mask:0xa
	v_cndmask_b32_e64 v142, v89, v77, s[38:39]
	s_waitcnt lgkmcnt(0)
	v_cndmask_b32_e64 v189, v144, -v144, s[40:41]
	s_waitcnt lgkmcnt(0)
	v_cndmask_b32_e64 v188, v187, -v187, s[40:41]
	v_pk_mul_f32 v[188:189], v[142:143], v[188:189] op_sel_hi:[0,1]
	v_pk_fma_f32 v[86:87], v[88:89], v[86:87], v[188:189] op_sel_hi:[0,1,1]
	v_lshlrev_b32_e32 v89, 16, v145
	s_and_b64 vcc, exec, s[42:43]
	v_lshlrev_b32_e32 v88, 16, v143
	s_cbranch_vccz .LBB0_748

; #define GAS __attribute__((address_space(1)))
; __device__ __forceinline__ unsigned pk2(float lo, float hi) { const f32x2_t v = {lo, hi}; const bf16x2_t b = __builtin_convertvector(v, bf16x2_t); return __builtin_bit_cast(unsigned, b); }
; __device__ __forceinline__ float ex2(float x) { return __builtin_amdgcn_exp2f(x); }
; __device__ __forceinline__ float bfe(const v4u& w, int c) { return (c & 1) ? bfhi(w[c >> 1]) : bflo(w[c >> 1]); }
; __device__ __forceinline__ float bfe2(const v2u& w, int c) { return (c & 1) ? bfhi(w[c >> 1]) : bflo(w[c >> 1]); }
; template <int DIR> __device__ __forceinline__ void prep_gla_k(const ScanBufs<64>& B, const bf16* P, const float* w2g, const float* b2g, const f32x2* RR, const LAS f32x2* RC  , int g, int half, int lane, LAS v4u* Wl, LAS v4u* Gl  ) {
;     ...
;                 for (int c = 0; c < 4; ++c) { float x = b2[c];
; #pragma unroll
;                     for (int r = 0; r < 8; ++r) { x += bfe(l0[j], r) * w2[r][c]; x += bfe(l1[j], r) * w2[8 + r][c]; }
;                     const float la = (fminf(x, 0.f) * 1.4426950408889634f - __log2f(1.f + __expf(-fabsf(x)))) * 0.0625f;
;                     float k = bfe2(kr[j], c), q = bfe2(qr2[j], c);
;                     if (lat) { const f32x2 cs = csc[c]; const float pt = __shfl_xor(k, 4), pq = __shfl_xor(q, 4); k = k * cs.x + (second ? pt : -pt) * cs.y; q = q * cs.x + (second ? pq : -pq) * cs.y; }
;                     const float e = cum[c]; cum[c] += la; kv[c] = k * ex2(e); kp[hf * 4 + j][c] = kv[c]; ev[c] = q * 0.125f * ex2(fminf(-e, 126.f)); }
;                 { v2u ew; ew.x = pk2(ev[0], ev[1]); ew.y = pk2(ev[2], ev[3]); *(GAS v2u*)(Ep + (size_t)t * 512) = ew; }
;                 { v2u kw; kw.x = pk2(kv[0], kv[1]); kw.y = pk2(kv[2], kv[3]); *(GAS v2u*)(Kp + (size_t)t * 512) = kw; } } }
.LBB0_733:
	v_cndmask_b32_e64 v84, v84, v72, s[38:39]
	s_nop 0
	s_nop 1
	v_mov_b32_dpp v143, v83 row_shl:4 row_mask:0xf bank_mask:0x5
	v_mov_b32_dpp v143, v83 row_shr:4 row_mask:0xf bank_mask:0xa
	v_mov_b32_dpp v144, v82 row_shl:4 row_mask:0xf bank_mask:0x5
	v_mov_b32_dpp v144, v82 row_shr:4 row_mask:0xf bank_mask:0xa
	v_cndmask_b32_e64 v142, v85, v73, s[38:39]
	s_waitcnt lgkmcnt(0)
	v_cndmask_b32_e64 v145, v143, -v143, s[40:41]
	s_waitcnt lgkmcnt(0)
	v_cndmask_b32_e64 v144, v144, -v144, s[40:41]
	v_pk_mul_f32 v[142:143], v[142:143], v[144:145] op_sel_hi:[0,1]
	v_pk_fma_f32 v[82:83], v[84:85], v[82:83], v[142:143] op_sel_hi:[0,1,1]
.LBB0_734:
	s_lshl_b32 s76, s67, 16
	s_lshl_b32 s75, s71, 16
	v_fma_f32 v84, s76, v2, v68
	s_and_b32 s74, s67, 0xffff0000
	v_fmac_f32_e32 v84, s75, v30
	s_and_b32 s73, s71, 0xffff0000
	v_fmac_f32_e32 v84, s74, v6
	s_lshl_b32 s72, s66, 16
	v_fmac_f32_e32 v84, s73, v38
	s_lshl_b32 s71, s70, 16
	v_fmac_f32_e32 v84, s72, v10
	s_and_b32 s67, s66, 0xffff0000
	v_fmac_f32_e32 v84, s71, v42
	s_and_b32 s66, s70, 0xffff0000
	v_fmac_f32_e32 v84, s67, v14
	s_lshl_b32 s30, s65, 16
	v_fmac_f32_e32 v84, s66, v46
	s_lshl_b32 s29, s69, 16
	v_fmac_f32_e32 v84, s30, v18
	s_and_b32 s28, s65, 0xffff0000
	v_fmac_f32_e32 v84, s29, v54
	s_and_b32 s27, s69, 0xffff0000
	v_fmac_f32_e32 v84, s28, v34
	s_lshl_b32 s26, s64, 16
	v_fmac_f32_e32 v84, s27, v50
	s_lshl_b32 s25, s68, 16
	v_fmac_f32_e32 v84, s26, v22
	s_and_b32 s24, s64, 0xffff0000
	v_fmac_f32_e32 v84, s25, v58
	s_and_b32 s23, s68, 0xffff0000
	v_fmac_f32_e32 v84, s24, v26
	v_fmac_f32_e32 v84, s23, v62
	s_mov_b32 s65, 0xbfb8aa3b
	v_min_f32_e32 v85, 0, v84
	v_mul_f32_e64 v84, |v84|, s65
	v_exp_f32_e32 v84, v84
	s_mov_b32 s68, 0x3fb8aa3b
	s_mov_b32 s64, 0x42fc0000
	v_lshlrev_b32_e32 v143, 16, v134
	v_add_f32_e32 v84, 1.0, v84
	v_log_f32_e32 v84, v84
	v_lshlrev_b32_e32 v142, 16, v132
	v_fma_f32 v84, v85, s68, -v84
	v_fmac_f32_e32 v80, 0x3d800000, v84
	v_exp_f32_e32 v84, v80
	v_min_f32_e64 v85, -v80, s64
	v_exp_f32_e32 v85, v85
	v_mul_f32_e32 v144, v84, v88
	v_mul_f32_e32 v84, 0x3e000000, v89
	v_mul_f32_e32 v84, v85, v84
	v_fma_f32 v85, s76, v1, v67
	v_fmac_f32_e32 v85, s75, v29
	v_fmac_f32_e32 v85, s74, v5
	v_fmac_f32_e32 v85, s73, v37
	v_fmac_f32_e32 v85, s72, v9
	v_fmac_f32_e32 v85, s71, v41
	v_fmac_f32_e32 v85, s67, v13
	v_fmac_f32_e32 v85, s66, v45
	v_fmac_f32_e32 v85, s30, v17
	v_fmac_f32_e32 v85, s29, v53
	v_fmac_f32_e32 v85, s28, v33
	v_fmac_f32_e32 v85, s27, v49
	v_fmac_f32_e32 v85, s26, v21
	v_fmac_f32_e32 v85, s25, v57
	v_fmac_f32_e32 v85, s24, v25
	v_fmac_f32_e32 v85, s23, v61
	v_min_f32_e32 v88, 0, v85
	v_mul_f32_e64 v85, |v85|, s65
	v_exp_f32_e32 v85, v85
	s_nop 0
	v_add_f32_e32 v85, 1.0, v85
	v_log_f32_e32 v85, v85
	s_nop 0
	v_fma_f32 v85, v88, s68, -v85
	v_fmac_f32_e32 v79, 0x3d800000, v85
	v_exp_f32_e32 v85, v79
	s_nop 0
	v_mul_f32_e32 v145, v85, v86
	v_min_f32_e64 v86, -v79, s64
	v_exp_f32_e32 v86, v86
	v_mul_f32_e32 v85, 0x3e000000, v87
	v_mul_f32_e32 v85, v86, v85
	v_fma_f32 v86, s76, v0, v66
	v_fmac_f32_e32 v86, s75, v28
	v_fmac_f32_e32 v86, s74, v4
	v_fmac_f32_e32 v86, s73, v36
	v_fmac_f32_e32 v86, s72, v8
	v_fmac_f32_e32 v86, s71, v40
	v_fmac_f32_e32 v86, s67, v12
	v_fmac_f32_e32 v86, s66, v44
	v_fmac_f32_e32 v86, s30, v16
	v_fmac_f32_e32 v86, s29, v52
	v_fmac_f32_e32 v86, s28, v32
	v_fmac_f32_e32 v86, s27, v48
	v_fmac_f32_e32 v86, s26, v20
	v_fmac_f32_e32 v86, s25, v56
	v_fmac_f32_e32 v86, s24, v24
	v_fmac_f32_e32 v86, s23, v60
	v_min_f32_e32 v87, 0, v86
	v_mul_f32_e64 v86, |v86|, s65
	v_exp_f32_e32 v86, v86
	s_nop 0
	v_add_f32_e32 v86, 1.0, v86
	v_log_f32_e32 v86, v86
	s_nop 0
	v_fma_f32 v86, v87, s68, -v86
	v_fmac_f32_e32 v78, 0x3d800000, v86
	v_exp_f32_e32 v86, v78
	v_min_f32_e64 v87, -v78, s64
	v_exp_f32_e32 v87, v87
	v_mul_f32_e32 v152, v86, v152
	v_mul_f32_e32 v86, 0x3e000000, v153
	v_mul_f32_e32 v86, v87, v86
	v_fma_f32 v87, s76, v3, v69
	v_fmac_f32_e32 v87, s75, v31
	v_fmac_f32_e32 v87, s74, v7
	v_fmac_f32_e32 v87, s73, v39
	v_fmac_f32_e32 v87, s72, v11
	v_fmac_f32_e32 v87, s71, v43
	v_fmac_f32_e32 v87, s67, v15
	v_fmac_f32_e32 v87, s66, v47
	v_fmac_f32_e32 v87, s30, v19
	v_fmac_f32_e32 v87, s29, v55
	v_fmac_f32_e32 v87, s28, v35
	v_fmac_f32_e32 v87, s27, v51
	v_fmac_f32_e32 v87, s26, v23
	v_fmac_f32_e32 v87, s25, v59
	v_fmac_f32_e32 v87, s24, v27
	v_fmac_f32_e32 v87, s23, v63
	v_min_f32_e32 v88, 0, v87
	v_mul_f32_e64 v87, |v87|, s65
	v_exp_f32_e32 v87, v87
	s_nop 0
	v_add_f32_e32 v87, 1.0, v87
	v_log_f32_e32 v87, v87
	s_nop 0
	v_fma_f32 v87, v88, s68, -v87
	v_fmac_f32_e32 v81, 0x3d800000, v87
	v_exp_f32_e32 v87, v81
	s_nop 0
	v_mul_f32_e32 v153, v87, v82
	v_mul_f32_e32 v82, 0x3e000000, v83
	v_min_f32_e64 v83, -v81, s64
	v_exp_f32_e32 v83, v83
	s_nop 0
	v_mul_f32_e32 v83, v83, v82
	v_cvt_pk_bf16_f32 v82, v86, v85
	v_cvt_pk_bf16_f32 v83, v84, v83
	v_add_co_u32_e32 v84, vcc, 0x65601000, v116
	global_store_dwordx2 v[150:151], v[82:83], off offset:1024
	v_cvt_pk_bf16_f32 v82, v152, v145
	v_cvt_pk_bf16_f32 v83, v144, v153
	v_addc_co_u32_e32 v85, vcc, 0, v117, vcc
	global_store_dwordx2 v[84:85], v[82:83], off offset:1024
	v_add_u32_e32 v82, 0x10300, v180
	ds_read_b128 v[86:89], v82
	v_add_u32_e32 v82, 0x10310, v180
	ds_read_b128 v[82:85], v82
	s_and_b64 vcc, exec, s[42:43]
	s_cbranch_vccnz .LBB0_736
	s_waitcnt lgkmcnt(1)
	v_cndmask_b32_e64 v188, v87, v75, s[38:39]
	v_cndmask_b32_e64 v86, v86, v74, s[38:39]
	s_nop 1
	v_mov_b32_dpp v189, v143 row_shl:4 row_mask:0xf bank_mask:0x5
	v_mov_b32_dpp v189, v143 row_shr:4 row_mask:0xf bank_mask:0xa
	v_mov_b32_dpp v187, v142 row_shl:4 row_mask:0xf bank_mask:0x5
	v_mov_b32_dpp v187, v142 row_shr:4 row_mask:0xf bank_mask:0xa
	s_waitcnt lgkmcnt(0)
	v_cndmask_b32_e64 v193, v189, -v189, s[40:41]
	s_waitcnt lgkmcnt(0)
	v_cndmask_b32_e64 v192, v187, -v187, s[40:41]
	v_pk_mul_f32 v[188:189], v[188:189], v[192:193] op_sel_hi:[0,1]
	v_pk_fma_f32 v[142:143], v[86:87], v[142:143], v[188:189] op_sel_hi:[0,1,1]
.LBB0_736:
	s_waitcnt lgkmcnt(1)
	v_and_b32_e32 v87, 0xffff0000, v134
	s_and_b64 vcc, exec, s[42:43]
	v_and_b32_e32 v86, 0xffff0000, v132
	s_mov_b32 s77, s87
	s_cbranch_vccnz .LBB0_749
	v_cndmask_b32_e64 v88, v88, v76, s[38:39]
	s_nop 0
	s_nop 1
	v_mov_b32_dpp v134, v87 row_shl:4 row_mask:0xf bank_mask:0x5
	v_mov_b32_dpp v134, v87 row_shr:4 row_mask:0xf bank_mask:0xa
	v_mov_b32_dpp v187, v86 row_shl:4 row_mask:0xf bank_mask:0x5
	v_mov_b32_dpp v187, v86 row_shr:4 row_mask:0xf bank_mask:0xa
	v_cndmask_b32_e64 v132, v89, v77, s[38:39]
	s_waitcnt lgkmcnt(0)
	v_cndmask_b32_e64 v189, v134, -v134, s[40:41]
	s_waitcnt lgkmcnt(0)
	v_cndmask_b32_e64 v188, v187, -v187, s[40:41]
	v_pk_mul_f32 v[188:189], v[132:133], v[188:189] op_sel_hi:[0,1]
	v_pk_fma_f32 v[86:87], v[88:89], v[86:87], v[188:189] op_sel_hi:[0,1,1]
	v_lshlrev_b32_e32 v89, 16, v135
	s_and_b64 vcc, exec, s[42:43]
	v_lshlrev_b32_e32 v88, 16, v133
	s_cbranch_vccz .LBB0_750

; #define GAS __attribute__((address_space(1)))
; __device__ __forceinline__ unsigned pk2(float lo, float hi) { const f32x2_t v = {lo, hi}; const bf16x2_t b = __builtin_convertvector(v, bf16x2_t); return __builtin_bit_cast(unsigned, b); }
; __device__ __forceinline__ float ex2(float x) { return __builtin_amdgcn_exp2f(x); }
; __device__ __forceinline__ float bfe(const v4u& w, int c) { return (c & 1) ? bfhi(w[c >> 1]) : bflo(w[c >> 1]); }
; __device__ __forceinline__ float bfe2(const v2u& w, int c) { return (c & 1) ? bfhi(w[c >> 1]) : bflo(w[c >> 1]); }
; template <int DIR> __device__ __forceinline__ void prep_gla_k(const ScanBufs<64>& B, const bf16* P, const float* w2g, const float* b2g, const f32x2* RR, const LAS f32x2* RC  , int g, int half, int lane, LAS v4u* Wl, LAS v4u* Gl  ) {
;     ...
;                 for (int c = 0; c < 4; ++c) { float x = b2[c];
; #pragma unroll
;                     for (int r = 0; r < 8; ++r) { x += bfe(l0[j], r) * w2[r][c]; x += bfe(l1[j], r) * w2[8 + r][c]; }
;                     const float la = (fminf(x, 0.f) * 1.4426950408889634f - __log2f(1.f + __expf(-fabsf(x)))) * 0.0625f;
;                     float k = bfe2(kr[j], c), q = bfe2(qr2[j], c);
;                     if (lat) { const f32x2 cs = csc[c]; const float pt = __shfl_xor(k, 4), pq = __shfl_xor(q, 4); k = k * cs.x + (second ? pt : -pt) * cs.y; q = q * cs.x + (second ? pq : -pq) * cs.y; }
;                     const float e = cum[c]; cum[c] += la; kv[c] = k * ex2(e); kp[hf * 4 + j][c] = kv[c]; ev[c] = q * 0.125f * ex2(fminf(-e, 126.f)); }
;                 { v2u ew; ew.x = pk2(ev[0], ev[1]); ew.y = pk2(ev[2], ev[3]); *(GAS v2u*)(Ep + (size_t)t * 512) = ew; }
;                 { v2u kw; kw.x = pk2(kv[0], kv[1]); kw.y = pk2(kv[2], kv[3]); *(GAS v2u*)(Kp + (size_t)t * 512) = kw; } } }
.LBB0_739:
	v_cndmask_b32_e64 v84, v84, v72, s[38:39]
	s_nop 0
	s_nop 1
	v_mov_b32_dpp v133, v83 row_shl:4 row_mask:0xf bank_mask:0x5
	v_mov_b32_dpp v133, v83 row_shr:4 row_mask:0xf bank_mask:0xa
	v_mov_b32_dpp v134, v82 row_shl:4 row_mask:0xf bank_mask:0x5
	v_mov_b32_dpp v134, v82 row_shr:4 row_mask:0xf bank_mask:0xa
	v_cndmask_b32_e64 v132, v85, v73, s[38:39]
	s_waitcnt lgkmcnt(0)
	v_cndmask_b32_e64 v135, v133, -v133, s[40:41]
	s_waitcnt lgkmcnt(0)
	v_cndmask_b32_e64 v134, v134, -v134, s[40:41]
	v_pk_mul_f32 v[132:133], v[132:133], v[134:135] op_sel_hi:[0,1]
	v_pk_fma_f32 v[82:83], v[84:85], v[82:83], v[132:133] op_sel_hi:[0,1,1]
.LBB0_740:
	s_lshl_b32 s68, s59, 16
	s_lshl_b32 s67, s63, 16
	v_fma_f32 v84, s68, v2, v68
	s_and_b32 s66, s59, 0xffff0000
	v_fmac_f32_e32 v84, s67, v30
	s_and_b32 s65, s63, 0xffff0000
	v_fmac_f32_e32 v84, s66, v6
	s_lshl_b32 s64, s58, 16
	v_fmac_f32_e32 v84, s65, v38
	s_lshl_b32 s63, s62, 16
	v_fmac_f32_e32 v84, s64, v10
	s_and_b32 s59, s58, 0xffff0000
	v_fmac_f32_e32 v84, s63, v42
	s_and_b32 s58, s62, 0xffff0000
	v_fmac_f32_e32 v84, s59, v14
	s_lshl_b32 s30, s57, 16
	v_fmac_f32_e32 v84, s58, v46
	s_lshl_b32 s29, s61, 16
	v_fmac_f32_e32 v84, s30, v18
	s_and_b32 s28, s57, 0xffff0000
	v_fmac_f32_e32 v84, s29, v54
	s_and_b32 s27, s61, 0xffff0000
	v_fmac_f32_e32 v84, s28, v34
	s_lshl_b32 s26, s33, 16
	v_fmac_f32_e32 v84, s27, v50
	s_lshl_b32 s25, s60, 16
	v_fmac_f32_e32 v84, s26, v22
	s_and_b32 s24, s33, 0xffff0000
	v_fmac_f32_e32 v84, s25, v58
	s_and_b32 s23, s60, 0xffff0000
	v_fmac_f32_e32 v84, s24, v26
	v_fmac_f32_e32 v84, s23, v62
	s_mov_b32 s57, 0xbfb8aa3b
	v_min_f32_e32 v85, 0, v84
	v_mul_f32_e64 v84, |v84|, s57
	v_exp_f32_e32 v84, v84
	s_mov_b32 s60, 0x3fb8aa3b
	s_mov_b32 s33, 0x42fc0000
	v_add_f32_e32 v84, 1.0, v84
	v_log_f32_e32 v84, v84
	s_nop 0
	v_fma_f32 v84, v85, s60, -v84
	v_fmac_f32_e32 v80, 0x3d800000, v84
	v_exp_f32_e32 v84, v80
	v_min_f32_e64 v85, -v80, s33
	v_exp_f32_e32 v85, v85
	v_mul_f32_e32 v132, v84, v88
	v_mul_f32_e32 v84, 0x3e000000, v89
	v_mul_f32_e32 v84, v85, v84
	v_fma_f32 v85, s68, v1, v67
	v_fmac_f32_e32 v85, s67, v29
	v_fmac_f32_e32 v85, s66, v5
	v_fmac_f32_e32 v85, s65, v37
	v_fmac_f32_e32 v85, s64, v9
	v_fmac_f32_e32 v85, s63, v41
	v_fmac_f32_e32 v85, s59, v13
	v_fmac_f32_e32 v85, s58, v45
	v_fmac_f32_e32 v85, s30, v17
	v_fmac_f32_e32 v85, s29, v53
	v_fmac_f32_e32 v85, s28, v33
	v_fmac_f32_e32 v85, s27, v49
	v_fmac_f32_e32 v85, s26, v21
	v_fmac_f32_e32 v85, s25, v57
	v_fmac_f32_e32 v85, s24, v25
	v_fmac_f32_e32 v85, s23, v61
	v_min_f32_e32 v88, 0, v85
	v_mul_f32_e64 v85, |v85|, s57
	v_exp_f32_e32 v85, v85
	s_nop 0
	v_add_f32_e32 v85, 1.0, v85
	v_log_f32_e32 v85, v85
	s_nop 0
	v_fma_f32 v85, v88, s60, -v85
	v_fmac_f32_e32 v79, 0x3d800000, v85
	v_exp_f32_e32 v85, v79
	s_nop 0
	v_mul_f32_e32 v133, v85, v86
	v_min_f32_e64 v86, -v79, s33
	v_exp_f32_e32 v86, v86
	v_mul_f32_e32 v85, 0x3e000000, v87
	v_mul_f32_e32 v85, v86, v85
	v_fma_f32 v86, s68, v0, v66
	v_fmac_f32_e32 v86, s67, v28
	v_fmac_f32_e32 v86, s66, v4
	v_fmac_f32_e32 v86, s65, v36
	v_fmac_f32_e32 v86, s64, v8
	v_fmac_f32_e32 v86, s63, v40
	v_fmac_f32_e32 v86, s59, v12
	v_fmac_f32_e32 v86, s58, v44
	v_fmac_f32_e32 v86, s30, v16
	v_fmac_f32_e32 v86, s29, v52
	v_fmac_f32_e32 v86, s28, v32
	v_fmac_f32_e32 v86, s27, v48
	v_fmac_f32_e32 v86, s26, v20
	v_fmac_f32_e32 v86, s25, v56
	v_fmac_f32_e32 v86, s24, v24
	v_fmac_f32_e32 v86, s23, v60
	v_min_f32_e32 v87, 0, v86
	v_mul_f32_e64 v86, |v86|, s57
	v_exp_f32_e32 v86, v86
	s_nop 0
	v_add_f32_e32 v86, 1.0, v86
	v_log_f32_e32 v86, v86
	s_nop 0
	v_fma_f32 v86, v87, s60, -v86
	v_fmac_f32_e32 v78, 0x3d800000, v86
	v_exp_f32_e32 v86, v78
	v_min_f32_e64 v87, -v78, s33
	v_exp_f32_e32 v87, v87
	v_mul_f32_e32 v134, v86, v142
	v_mul_f32_e32 v86, 0x3e000000, v143
	v_mul_f32_e32 v86, v87, v86
	v_fma_f32 v87, s68, v3, v69
	v_fmac_f32_e32 v87, s67, v31
	v_fmac_f32_e32 v87, s66, v7
	v_fmac_f32_e32 v87, s65, v39
	v_fmac_f32_e32 v87, s64, v11
	v_fmac_f32_e32 v87, s63, v43
	v_fmac_f32_e32 v87, s59, v15
	v_fmac_f32_e32 v87, s58, v47
	v_fmac_f32_e32 v87, s30, v19
	v_fmac_f32_e32 v87, s29, v55
	v_fmac_f32_e32 v87, s28, v35
	v_fmac_f32_e32 v87, s27, v51
	v_fmac_f32_e32 v87, s26, v23
	v_fmac_f32_e32 v87, s25, v59
	v_fmac_f32_e32 v87, s24, v27
	v_fmac_f32_e32 v87, s23, v63
	v_min_f32_e32 v88, 0, v87
	v_mul_f32_e64 v87, |v87|, s57
	v_exp_f32_e32 v87, v87
	v_lshlrev_b32_e32 v143, 16, v124
	v_lshlrev_b32_e32 v142, 16, v122
	v_add_f32_e32 v87, 1.0, v87
	v_log_f32_e32 v87, v87
	s_nop 0
	v_fma_f32 v87, v88, s60, -v87
	v_fmac_f32_e32 v81, 0x3d800000, v87
	v_exp_f32_e32 v87, v81
	s_nop 0
	v_mul_f32_e32 v135, v87, v82
	v_mul_f32_e32 v82, 0x3e000000, v83
	v_min_f32_e64 v83, -v81, s33
	v_exp_f32_e32 v83, v83
	s_nop 0
	v_mul_f32_e32 v83, v83, v82
	v_cvt_pk_bf16_f32 v82, v86, v85
	v_cvt_pk_bf16_f32 v83, v84, v83
	v_add_co_u32_e32 v84, vcc, 0x65601000, v116
	global_store_dwordx2 v[150:151], v[82:83], off offset:2048
	v_cvt_pk_bf16_f32 v82, v134, v133
	v_cvt_pk_bf16_f32 v83, v132, v135
	v_addc_co_u32_e32 v85, vcc, 0, v117, vcc
	global_store_dwordx2 v[84:85], v[82:83], off offset:2048
	v_add_u32_e32 v82, 0x10380, v180
	ds_read_b128 v[86:89], v82
	v_add_u32_e32 v82, 0x10390, v180
	ds_read_b128 v[82:85], v82
	s_and_b64 vcc, exec, s[42:43]
	s_cbranch_vccnz .LBB0_742
	s_waitcnt lgkmcnt(1)
	v_cndmask_b32_e64 v86, v86, v74, s[38:39]
	s_nop 1
	v_mov_b32_dpp v187, v143 row_shl:4 row_mask:0xf bank_mask:0x5
	v_mov_b32_dpp v187, v143 row_shr:4 row_mask:0xf bank_mask:0xa
	v_mov_b32_dpp v188, v142 row_shl:4 row_mask:0xf bank_mask:0x5
	v_mov_b32_dpp v188, v142 row_shr:4 row_mask:0xf bank_mask:0xa
	v_cndmask_b32_e64 v180, v87, v75, s[38:39]
	s_waitcnt lgkmcnt(0)
	v_cndmask_b32_e64 v189, v187, -v187, s[40:41]
	s_waitcnt lgkmcnt(0)
	v_cndmask_b32_e64 v188, v188, -v188, s[40:41]
	v_pk_mul_f32 v[188:189], v[180:181], v[188:189] op_sel_hi:[0,1]
	v_pk_fma_f32 v[142:143], v[86:87], v[142:143], v[188:189] op_sel_hi:[0,1,1]
.LBB0_742:
	v_readlane_b32 s68, v245, 33
	s_waitcnt lgkmcnt(1)
	v_and_b32_e32 v87, 0xffff0000, v124
	s_and_b64 vcc, exec, s[42:43]
	v_and_b32_e32 v86, 0xffff0000, v122
	v_readlane_b32 s69, v245, 34
	v_readlane_b32 s70, v245, 35
	v_readlane_b32 s71, v245, 36
	s_mov_b32 s66, 0xffff0000
	s_movk_i32 s67, 0x1000
	s_cbranch_vccnz .LBB0_751
	v_cndmask_b32_e64 v88, v88, v76, s[38:39]
	s_nop 0
	s_nop 1
	v_mov_b32_dpp v124, v87 row_shl:4 row_mask:0xf bank_mask:0x5
	v_mov_b32_dpp v124, v87 row_shr:4 row_mask:0xf bank_mask:0xa
	v_mov_b32_dpp v180, v86 row_shl:4 row_mask:0xf bank_mask:0x5
	v_mov_b32_dpp v180, v86 row_shr:4 row_mask:0xf bank_mask:0xa
	v_cndmask_b32_e64 v122, v89, v77, s[38:39]
	s_waitcnt lgkmcnt(0)
	v_cndmask_b32_e64 v189, v124, -v124, s[40:41]
	s_waitcnt lgkmcnt(0)
	v_cndmask_b32_e64 v188, v180, -v180, s[40:41]
	v_pk_mul_f32 v[188:189], v[122:123], v[188:189] op_sel_hi:[0,1]
	v_pk_fma_f32 v[86:87], v[88:89], v[86:87], v[188:189] op_sel_hi:[0,1,1]
	v_lshlrev_b32_e32 v89, 16, v125
	s_and_b64 vcc, exec, s[42:43]
	v_lshlrev_b32_e32 v88, 16, v123
	s_cbranch_vccz .LBB0_752

; __device__ __forceinline__ float bfe2(const v2u& w, int c) { return (c & 1) ? bfhi(w[c >> 1]) : bflo(w[c >> 1]); }
; template <int DIR> __device__ __forceinline__ void prep_gla_k(const ScanBufs<64>& B, const bf16* P, const float* w2g, const float* b2g, const f32x2* RR, const LAS f32x2* RC  , int g, int half, int lane, LAS v4u* Wl, LAS v4u* Gl  ) {
;     ...
;                     float k = bfe2(kr[j], c), q = bfe2(qr2[j], c);
;                     if (lat) { const f32x2 cs = csc[c]; const float pt = __shfl_xor(k, 4), pq = __shfl_xor(q, 4); k = k * cs.x + (second ? pt : -pt) * cs.y; q = q * cs.x + (second ? pq : -pq) * cs.y; }
.LBB0_746:
	v_cndmask_b32_e64 v88, v88, v76, s[38:39]
	s_nop 0
	s_nop 1
	v_mov_b32_dpp v148, v87 row_shl:4 row_mask:0xf bank_mask:0x5
	v_mov_b32_dpp v148, v87 row_shr:4 row_mask:0xf bank_mask:0xa
	v_mov_b32_dpp v152, v86 row_shl:4 row_mask:0xf bank_mask:0x5
	v_mov_b32_dpp v152, v86 row_shr:4 row_mask:0xf bank_mask:0xa
	v_cndmask_b32_e64 v146, v89, v77, s[38:39]
	s_waitcnt lgkmcnt(0)
	v_cndmask_b32_e64 v153, v148, -v148, s[40:41]
	s_waitcnt lgkmcnt(0)
	v_cndmask_b32_e64 v152, v152, -v152, s[40:41]
	v_pk_mul_f32 v[152:153], v[146:147], v[152:153] op_sel_hi:[0,1]
	v_pk_fma_f32 v[86:87], v[88:89], v[86:87], v[152:153] op_sel_hi:[0,1,1]
	v_lshlrev_b32_e32 v89, 16, v149
	s_and_b64 vcc, exec, s[42:43]
	v_lshlrev_b32_e32 v88, 16, v147
	s_cbranch_vccz .LBB0_725
	s_branch .LBB0_726

; __device__ __forceinline__ float bfe2(const v2u& w, int c) { return (c & 1) ? bfhi(w[c >> 1]) : bflo(w[c >> 1]); }
; template <int DIR> __device__ __forceinline__ void prep_gla_k(const ScanBufs<64>& B, const bf16* P, const float* w2g, const float* b2g, const f32x2* RR, const LAS f32x2* RC  , int g, int half, int lane, LAS v4u* Wl, LAS v4u* Gl  ) {
;     ...
;                     float k = bfe2(kr[j], c), q = bfe2(qr2[j], c);
;                     if (lat) { const f32x2 cs = csc[c]; const float pt = __shfl_xor(k, 4), pq = __shfl_xor(q, 4); k = k * cs.x + (second ? pt : -pt) * cs.y; q = q * cs.x + (second ? pq : -pq) * cs.y; }
.LBB0_748:
	s_waitcnt lgkmcnt(0)
	v_cndmask_b32_e64 v82, v82, v70, s[38:39]
	s_nop 1
	v_mov_b32_dpp v144, v89 row_shl:4 row_mask:0xf bank_mask:0x5
	v_mov_b32_dpp v144, v89 row_shr:4 row_mask:0xf bank_mask:0xa
	v_mov_b32_dpp v187, v88 row_shl:4 row_mask:0xf bank_mask:0x5
	v_mov_b32_dpp v187, v88 row_shr:4 row_mask:0xf bank_mask:0xa
	v_cndmask_b32_e64 v142, v83, v71, s[38:39]
	s_waitcnt lgkmcnt(0)
	v_cndmask_b32_e64 v189, v144, -v144, s[40:41]
	s_waitcnt lgkmcnt(0)
	v_cndmask_b32_e64 v188, v187, -v187, s[40:41]
	v_pk_mul_f32 v[188:189], v[142:143], v[188:189] op_sel_hi:[0,1]
	v_pk_fma_f32 v[88:89], v[82:83], v[88:89], v[188:189] op_sel_hi:[0,1,1]
	v_and_b32_e32 v83, 0xffff0000, v145
	s_and_b64 vcc, exec, s[42:43]
	v_and_b32_e32 v82, 0xffff0000, v143
	s_cbranch_vccz .LBB0_733
	s_branch .LBB0_734

; __device__ __forceinline__ float bfe2(const v2u& w, int c) { return (c & 1) ? bfhi(w[c >> 1]) : bflo(w[c >> 1]); }
; template <int DIR> __device__ __forceinline__ void prep_gla_k(const ScanBufs<64>& B, const bf16* P, const float* w2g, const float* b2g, const f32x2* RR, const LAS f32x2* RC  , int g, int half, int lane, LAS v4u* Wl, LAS v4u* Gl  ) {
;     ...
;                     float k = bfe2(kr[j], c), q = bfe2(qr2[j], c);
;                     if (lat) { const f32x2 cs = csc[c]; const float pt = __shfl_xor(k, 4), pq = __shfl_xor(q, 4); k = k * cs.x + (second ? pt : -pt) * cs.y; q = q * cs.x + (second ? pq : -pq) * cs.y; }
.LBB0_750:
	s_waitcnt lgkmcnt(0)
	v_cndmask_b32_e64 v82, v82, v70, s[38:39]
	s_nop 1
	v_mov_b32_dpp v134, v89 row_shl:4 row_mask:0xf bank_mask:0x5
	v_mov_b32_dpp v134, v89 row_shr:4 row_mask:0xf bank_mask:0xa
	v_mov_b32_dpp v187, v88 row_shl:4 row_mask:0xf bank_mask:0x5
	v_mov_b32_dpp v187, v88 row_shr:4 row_mask:0xf bank_mask:0xa
	v_cndmask_b32_e64 v132, v83, v71, s[38:39]
	s_waitcnt lgkmcnt(0)
	v_cndmask_b32_e64 v189, v134, -v134, s[40:41]
	s_waitcnt lgkmcnt(0)
	v_cndmask_b32_e64 v188, v187, -v187, s[40:41]
	v_pk_mul_f32 v[188:189], v[132:133], v[188:189] op_sel_hi:[0,1]
	v_pk_fma_f32 v[88:89], v[82:83], v[88:89], v[188:189] op_sel_hi:[0,1,1]
	v_and_b32_e32 v83, 0xffff0000, v135
	s_and_b64 vcc, exec, s[42:43]
	v_and_b32_e32 v82, 0xffff0000, v133
	s_cbranch_vccz .LBB0_739
	s_branch .LBB0_740

; __device__ __forceinline__ float bfe2(const v2u& w, int c) { return (c & 1) ? bfhi(w[c >> 1]) : bflo(w[c >> 1]); }
; template <int DIR> __device__ __forceinline__ void prep_gla_k(const ScanBufs<64>& B, const bf16* P, const float* w2g, const float* b2g, const f32x2* RR, const LAS f32x2* RC  , int g, int half, int lane, LAS v4u* Wl, LAS v4u* Gl  ) {
;     ...
;                     float k = bfe2(kr[j], c), q = bfe2(qr2[j], c);
;                     if (lat) { const f32x2 cs = csc[c]; const float pt = __shfl_xor(k, 4), pq = __shfl_xor(q, 4); k = k * cs.x + (second ? pt : -pt) * cs.y; q = q * cs.x + (second ? pq : -pq) * cs.y; }
.LBB0_752:
	s_waitcnt lgkmcnt(0)
	v_cndmask_b32_e64 v82, v82, v70, s[38:39]
	s_nop 1
	v_mov_b32_dpp v124, v89 row_shl:4 row_mask:0xf bank_mask:0x5
	v_mov_b32_dpp v124, v89 row_shr:4 row_mask:0xf bank_mask:0xa
	v_mov_b32_dpp v180, v88 row_shl:4 row_mask:0xf bank_mask:0x5
	v_mov_b32_dpp v180, v88 row_shr:4 row_mask:0xf bank_mask:0xa
	v_cndmask_b32_e64 v122, v83, v71, s[38:39]
	s_waitcnt lgkmcnt(0)
	v_cndmask_b32_e64 v189, v124, -v124, s[40:41]
	s_waitcnt lgkmcnt(0)
	v_cndmask_b32_e64 v188, v180, -v180, s[40:41]
	v_pk_mul_f32 v[188:189], v[122:123], v[188:189] op_sel_hi:[0,1]
	v_pk_fma_f32 v[88:89], v[82:83], v[88:89], v[188:189] op_sel_hi:[0,1,1]
	v_and_b32_e32 v83, 0xffff0000, v125
	s_and_b64 vcc, exec, s[42:43]
	v_and_b32_e32 v82, 0xffff0000, v123
	s_cbranch_vccnz .LBB0_687
.LBB0_753:
	v_cndmask_b32_e64 v84, v84, v72, s[38:39]
	s_nop 0
	s_nop 1
	v_mov_b32_dpp v123, v83 row_shl:4 row_mask:0xf bank_mask:0x5
	v_mov_b32_dpp v123, v83 row_shr:4 row_mask:0xf bank_mask:0xa
	v_mov_b32_dpp v124, v82 row_shl:4 row_mask:0xf bank_mask:0x5
	v_mov_b32_dpp v124, v82 row_shr:4 row_mask:0xf bank_mask:0xa
	v_cndmask_b32_e64 v122, v85, v73, s[38:39]
	s_waitcnt lgkmcnt(0)
	v_cndmask_b32_e64 v125, v123, -v123, s[40:41]
	s_waitcnt lgkmcnt(0)
	v_cndmask_b32_e64 v124, v124, -v124, s[40:41]
	v_pk_mul_f32 v[122:123], v[122:123], v[124:125] op_sel_hi:[0,1]
	v_pk_fma_f32 v[82:83], v[84:85], v[82:83], v[122:123] op_sel_hi:[0,1,1]
	s_branch .LBB0_687

; #define GAS __attribute__((address_space(1)))
; #define LAS __attribute__((address_space(3)))
; __device__ __forceinline__ float bfe(const v4u& w, int c) { return (c & 1) ? bfhi(w[c >> 1]) : bflo(w[c >> 1]); }
; __device__ __forceinline__ float bfe2(const v2u& w, int c) { return (c & 1) ? bfhi(w[c >> 1]) : bflo(w[c >> 1]); }
; template <int DIR> __device__ __forceinline__ void prep_gla_k(const ScanBufs<64>& B, const bf16* P, const float* w2g, const float* b2g, const f32x2* RR, const LAS f32x2* RC  , int g, int half, int lane, LAS v4u* Wl, LAS v4u* Gl  ) {
;     ...
;             { const int hgn = 2 * i8 + hh + 1; if (hgn < 16) { const int tb = DIR ? 4 * hgn : 60 - 4 * hgn;
; #pragma unroll
;                 for (int j = 0; j < 4; ++j) { const size_t ro = (size_t)(tb + j) * NINP; krn[j] = *(const GAS v2u*)(kp0 + ro); qrn[j] = *(const GAS v2u*)(qp0 + ro); } } }
; #pragma unroll
;             for (int j = 0; j < 4; ++j) { const int tt_ = t8 * 8 + hf * 4 + j; l0[j] = Gl[2 * tt_]; l1[j] = Gl[2 * tt_ + 1]; }
; #pragma unroll
;             for (int jj = 0; jj < 4; ++jj) { const int j = DIR ? jj : 3 - jj; const int t = t8 * 8 + hf * 4 + j; float ev[4], kv[4];
;                 f32x2 csc[4];
;                 { const LAS f32x4* rc4 = (const LAS f32x4*)(RC + t * 16 + j0); const f32x4 ra = rc4[0], rb = rc4[1];
;                   csc[0] = isrow ? csr[0] : (f32x2){ra[0], ra[1]}; csc[1] = isrow ? csr[1] : (f32x2){ra[2], ra[3]}; csc[2] = isrow ? csr[2] : (f32x2){rb[0], rb[1]}; csc[3] = isrow ? csr[3] : (f32x2){rb[2], rb[3]}; }
; #pragma unroll
;                 for (int c = 0; c < 4; ++c) { float x = b2[c];
; #pragma unroll
;                     for (int r = 0; r < 8; ++r) { x += bfe(l0[j], r) * w2[r][c]; x += bfe(l1[j], r) * w2[8 + r][c]; }
;                     const float la = (fminf(x, 0.f) * 1.4426950408889634f - __log2f(1.f + __expf(-fabsf(x)))) * 0.0625f;
;                     float k = bfe2(kr[j], c), q = bfe2(qr2[j], c);
;                     if (lat) { const f32x2 cs = csc[c]; const float pt = __shfl_xor(k, 4), pq = __shfl_xor(q, 4); k = k * cs.x + (second ? pt : -pt) * cs.y; q = q * cs.x + (second ? pq : -pq) * cs.y; }
.LBB0_773:
	v_lshl_add_u64 v[82:83], s[70:71], 0, v[98:99]
	s_mov_b32 s19, 0x2e5e5000
	v_add_co_u32_e32 v84, vcc, s19, v82
	s_mov_b32 s19, 0x2e5ee000
	s_nop 0
	v_addc_co_u32_e32 v85, vcc, 0, v83, vcc
	v_add_co_u32_e32 v86, vcc, s19, v82
	s_mov_b32 s19, 0x2e5f7000
	s_nop 0
	v_addc_co_u32_e32 v87, vcc, 0, v83, vcc
	global_load_dwordx2 v[118:119], v[84:85], off offset:3072
	global_load_dwordx2 v[128:129], v[86:87], off offset:1536
	global_load_dwordx2 v[130:131], v[86:87], off offset:512
	global_load_dwordx2 v[120:121], v[84:85], off offset:2048
	v_add_co_u32_e32 v84, vcc, s19, v82
	s_mov_b32 s19, 0x2e5f6000
	s_nop 0
	v_addc_co_u32_e32 v85, vcc, 0, v83, vcc
	v_add_co_u32_e32 v86, vcc, s19, v82
	s_mov_b32 s19, 0x2e5ff000
	s_nop 0
	v_addc_co_u32_e32 v87, vcc, 0, v83, vcc
	v_add_co_u32_e32 v82, vcc, s19, v82
	s_add_i32 s27, s1, 0
	s_nop 0
	v_addc_co_u32_e32 v83, vcc, 0, v83, vcc
	global_load_dwordx2 v[138:139], v[84:85], off
	global_load_dwordx2 v[142:143], v[86:87], off offset:3072
	global_load_dwordx2 v[144:145], v[82:83], off offset:2560
	global_load_dwordx2 v[146:147], v[82:83], off offset:1536
	s_add_i32 s19, s27, 0x12780
	v_mov_b32_e32 v64, s19
	s_add_i32 s19, s27, 0x12790
	ds_read_b128 v[82:85], v64
	v_mov_b32_e32 v64, s19
	ds_read_b128 v[86:89], v64
	s_add_i32 s23, s27, 0x127a0
	v_mov_b32_e32 v64, s23
	s_add_i32 s28, s27, 0x127b0
	s_waitcnt lgkmcnt(1)
	v_readfirstlane_b32 s24, v82
	v_readfirstlane_b32 s21, v83
	v_readfirstlane_b32 s20, v84
	v_readfirstlane_b32 s19, v85
	ds_read_b128 v[82:85], v64
	v_mov_b32_e32 v64, s28
	s_waitcnt lgkmcnt(1)
	v_readfirstlane_b32 s26, v86
	v_readfirstlane_b32 s25, v87
	v_readfirstlane_b32 s22, v88
	v_readfirstlane_b32 s23, v89
	ds_read_b128 v[86:89], v64
	s_add_i32 s33, s27, 0x127c0
	v_mov_b32_e32 v64, s33
	s_add_i32 s33, s27, 0x127d0
	s_waitcnt lgkmcnt(1)
	v_readfirstlane_b32 s35, v82
	v_readfirstlane_b32 s30, v83
	v_readfirstlane_b32 s29, v84
	v_readfirstlane_b32 s28, v85
	ds_read_b128 v[82:85], v64
	v_mov_b32_e32 v64, s33
	s_waitcnt lgkmcnt(1)
	v_readfirstlane_b32 s37, v86
	v_readfirstlane_b32 s36, v87
	v_readfirstlane_b32 s31, v88
	v_readfirstlane_b32 s34, v89
	ds_read_b128 v[86:89], v64
	s_add_i32 s42, s27, 0x127e0
	v_mov_b32_e32 v64, s42
	s_add_i32 s42, s27, 0x127f0
	s_waitcnt lgkmcnt(1)
	v_readfirstlane_b32 s50, v82
	v_readfirstlane_b32 s47, v83
	v_readfirstlane_b32 s46, v84
	v_readfirstlane_b32 s33, v85
	ds_read_b128 v[82:85], v64
	v_mov_b32_e32 v64, s42
	s_waitcnt lgkmcnt(1)
	v_readfirstlane_b32 s52, v86
	v_readfirstlane_b32 s51, v87
	v_readfirstlane_b32 s48, v88
	v_readfirstlane_b32 s49, v89
	ds_read_b128 v[86:89], v64
	v_add_u32_e32 v156, 0, v91
	s_waitcnt lgkmcnt(1)
	v_readfirstlane_b32 s58, v82
	v_add_u32_e32 v64, 0x11f80, v156
	v_add_u32_e32 v82, 0x11f90, v156
	v_readfirstlane_b32 s56, v83
	v_readfirstlane_b32 s54, v84
	v_readfirstlane_b32 s53, v85
	s_waitcnt lgkmcnt(0)
	v_readfirstlane_b32 s60, v86
	v_readfirstlane_b32 s59, v87
	v_readfirstlane_b32 s57, v88
	v_readfirstlane_b32 s55, v89
	ds_read_b128 v[86:89], v64
	ds_read_b128 v[82:85], v82
	v_cndmask_b32_e64 v64, 0, 1, s[44:45]
	s_waitcnt vmcnt(9)
	v_lshlrev_b32_e32 v113, 16, v134
	v_cmp_ne_u32_e64 s[42:43], 1, v64
	s_andn2_b64 vcc, exec, s[44:45]
	v_lshlrev_b32_e32 v112, 16, v132
	s_cbranch_vccnz .LBB0_777
	s_waitcnt lgkmcnt(1)
	v_cndmask_b32_e64 v86, v86, v74, s[38:39]
	s_nop 1
	v_mov_b32_dpp v122, v113 row_shl:4 row_mask:0xf bank_mask:0x5
	v_mov_b32_dpp v122, v113 row_shr:4 row_mask:0xf bank_mask:0xa
	v_mov_b32_dpp v136, v112 row_shl:4 row_mask:0xf bank_mask:0x5
	v_mov_b32_dpp v136, v112 row_shr:4 row_mask:0xf bank_mask:0xa
	v_cndmask_b32_e64 v64, v87, v75, s[38:39]
	s_waitcnt lgkmcnt(0)
	v_cndmask_b32_e64 v123, v122, -v122, s[40:41]
	s_waitcnt lgkmcnt(0)
	v_cndmask_b32_e64 v122, v136, -v136, s[40:41]
	v_pk_mul_f32 v[122:123], v[64:65], v[122:123] op_sel_hi:[0,1]
	v_pk_fma_f32 v[112:113], v[86:87], v[112:113], v[122:123] op_sel_hi:[0,1,1]
	v_and_b32_e32 v87, 0xffff0000, v134
	s_and_b64 vcc, exec, s[42:43]
	v_and_b32_e32 v86, 0xffff0000, v132
	s_cbranch_vccz .LBB0_778

; __device__ __forceinline__ float bfe2(const v2u& w, int c) { return (c & 1) ? bfhi(w[c >> 1]) : bflo(w[c >> 1]); }
; template <int DIR> __device__ __forceinline__ void prep_gla_k(const ScanBufs<64>& B, const bf16* P, const float* w2g, const float* b2g, const f32x2* RR, const LAS f32x2* RC  , int g, int half, int lane, LAS v4u* Wl, LAS v4u* Gl  ) {
;     ...
;                     float k = bfe2(kr[j], c), q = bfe2(qr2[j], c);
;                     if (lat) { const f32x2 cs = csc[c]; const float pt = __shfl_xor(k, 4), pq = __shfl_xor(q, 4); k = k * cs.x + (second ? pt : -pt) * cs.y; q = q * cs.x + (second ? pq : -pq) * cs.y; }
.LBB0_776:
	s_waitcnt lgkmcnt(0)
	v_cndmask_b32_e64 v82, v82, v70, s[38:39]
	s_nop 1
	v_mov_b32_dpp v122, v89 row_shl:4 row_mask:0xf bank_mask:0x5
	v_mov_b32_dpp v122, v89 row_shr:4 row_mask:0xf bank_mask:0xa
	v_mov_b32_dpp v132, v88 row_shl:4 row_mask:0xf bank_mask:0x5
	v_mov_b32_dpp v132, v88 row_shr:4 row_mask:0xf bank_mask:0xa
	v_cndmask_b32_e64 v64, v83, v71, s[38:39]
	s_waitcnt lgkmcnt(0)
	v_cndmask_b32_e64 v123, v122, -v122, s[40:41]
	s_waitcnt lgkmcnt(0)
	v_cndmask_b32_e64 v122, v132, -v132, s[40:41]
	v_pk_mul_f32 v[122:123], v[64:65], v[122:123] op_sel_hi:[0,1]
	v_pk_fma_f32 v[88:89], v[82:83], v[88:89], v[122:123] op_sel_hi:[0,1,1]
	v_and_b32_e32 v83, 0xffff0000, v135
	s_and_b64 vcc, exec, s[42:43]
	v_and_b32_e32 v82, 0xffff0000, v133
	s_cbranch_vccz .LBB0_780
	s_branch .LBB0_781

; __device__ __forceinline__ float bfe2(const v2u& w, int c) { return (c & 1) ? bfhi(w[c >> 1]) : bflo(w[c >> 1]); }
; template <int DIR> __device__ __forceinline__ void prep_gla_k(const ScanBufs<64>& B, const bf16* P, const float* w2g, const float* b2g, const f32x2* RR, const LAS f32x2* RC  , int g, int half, int lane, LAS v4u* Wl, LAS v4u* Gl  ) {
;     ...
;                     float k = bfe2(kr[j], c), q = bfe2(qr2[j], c);
;                     if (lat) { const f32x2 cs = csc[c]; const float pt = __shfl_xor(k, 4), pq = __shfl_xor(q, 4); k = k * cs.x + (second ? pt : -pt) * cs.y; q = q * cs.x + (second ? pq : -pq) * cs.y; }
.LBB0_778:
	v_cndmask_b32_e64 v88, v88, v76, s[38:39]
	s_nop 0
	s_nop 1
	v_mov_b32_dpp v122, v87 row_shl:4 row_mask:0xf bank_mask:0x5
	v_mov_b32_dpp v122, v87 row_shr:4 row_mask:0xf bank_mask:0xa
	v_mov_b32_dpp v132, v86 row_shl:4 row_mask:0xf bank_mask:0x5
	v_mov_b32_dpp v132, v86 row_shr:4 row_mask:0xf bank_mask:0xa
	v_cndmask_b32_e64 v64, v89, v77, s[38:39]
	s_waitcnt lgkmcnt(0)
	v_cndmask_b32_e64 v123, v122, -v122, s[40:41]
	s_waitcnt lgkmcnt(0)
	v_cndmask_b32_e64 v122, v132, -v132, s[40:41]
	v_pk_mul_f32 v[122:123], v[64:65], v[122:123] op_sel_hi:[0,1]
	v_pk_fma_f32 v[86:87], v[88:89], v[86:87], v[122:123] op_sel_hi:[0,1,1]
	v_lshlrev_b32_e32 v89, 16, v135
	s_and_b64 vcc, exec, s[42:43]
	v_lshlrev_b32_e32 v88, 16, v133
	s_cbranch_vccz .LBB0_776

; #define GAS __attribute__((address_space(1)))
; __device__ __forceinline__ unsigned pk2(float lo, float hi) { const f32x2_t v = {lo, hi}; const bf16x2_t b = __builtin_convertvector(v, bf16x2_t); return __builtin_bit_cast(unsigned, b); }
; __device__ __forceinline__ float ex2(float x) { return __builtin_amdgcn_exp2f(x); }
; __device__ __forceinline__ float bfe2(const v2u& w, int c) { return (c & 1) ? bfhi(w[c >> 1]) : bflo(w[c >> 1]); }
; template <int DIR> __device__ __forceinline__ void prep_gla_k(const ScanBufs<64>& B, const bf16* P, const float* w2g, const float* b2g, const f32x2* RR, const LAS f32x2* RC  , int g, int half, int lane, LAS v4u* Wl, LAS v4u* Gl  ) {
;     ...
;                     float k = bfe2(kr[j], c), q = bfe2(qr2[j], c);
;                     if (lat) { const f32x2 cs = csc[c]; const float pt = __shfl_xor(k, 4), pq = __shfl_xor(q, 4); k = k * cs.x + (second ? pt : -pt) * cs.y; q = q * cs.x + (second ? pq : -pq) * cs.y; }
;                     const float e = cum[c]; cum[c] += la; kv[c] = k * ex2(e); kp[hf * 4 + j][c] = kv[c]; ev[c] = q * 0.125f * ex2(fminf(-e, 126.f)); }
;                 { v2u ew; ew.x = pk2(ev[0], ev[1]); ew.y = pk2(ev[2], ev[3]); *(GAS v2u*)(Ep + (size_t)t * 512) = ew; }
;                 { v2u kw; kw.x = pk2(kv[0], kv[1]); kw.y = pk2(kv[2], kv[3]); *(GAS v2u*)(Kp + (size_t)t * 512) = kw; } } }
.LBB0_780:
	v_cndmask_b32_e64 v84, v84, v72, s[38:39]
	s_nop 0
	s_nop 1
	v_mov_b32_dpp v122, v83 row_shl:4 row_mask:0xf bank_mask:0x5
	v_mov_b32_dpp v122, v83 row_shr:4 row_mask:0xf bank_mask:0xa
	v_mov_b32_dpp v132, v82 row_shl:4 row_mask:0xf bank_mask:0x5
	v_mov_b32_dpp v132, v82 row_shr:4 row_mask:0xf bank_mask:0xa
	v_cndmask_b32_e64 v64, v85, v73, s[38:39]
	s_waitcnt lgkmcnt(0)
	v_cndmask_b32_e64 v123, v122, -v122, s[40:41]
	s_waitcnt lgkmcnt(0)
	v_cndmask_b32_e64 v122, v132, -v132, s[40:41]
	v_pk_mul_f32 v[122:123], v[64:65], v[122:123] op_sel_hi:[0,1]
	v_pk_fma_f32 v[82:83], v[84:85], v[82:83], v[122:123] op_sel_hi:[0,1,1]
.LBB0_781:
	v_max_f32_e64 v84, -v80, -v80
	v_exp_f32_e32 v64, v80
	v_min_f32_e32 v84, 0x42fc0000, v84
	v_exp_f32_e32 v84, v84
	v_max_f32_e64 v85, -v79, -v79
	v_mul_f32_e32 v150, v64, v88
	v_mul_f32_e32 v64, 0x3e000000, v89
	v_mul_f32_e32 v64, v84, v64
	v_exp_f32_e32 v84, v79
	v_min_f32_e32 v85, 0x42fc0000, v85
	v_exp_f32_e32 v85, v85
	s_mov_b32 s61, 0x65f0f000
	v_mul_f32_e32 v151, v84, v86
	v_mul_f32_e32 v84, 0x3e000000, v87
	v_max_f32_e64 v86, -v78, -v78
	v_mul_f32_e32 v84, v85, v84
	v_exp_f32_e32 v85, v78
	v_min_f32_e32 v86, 0x42fc0000, v86
	v_exp_f32_e32 v86, v86
	s_waitcnt vmcnt(8)
	v_lshlrev_b32_e32 v123, 16, v126
	v_mul_f32_e32 v153, v85, v112
	v_mul_f32_e32 v85, 0x3e000000, v113
	v_mul_f32_e32 v85, v86, v85
	v_exp_f32_e32 v86, v81
	v_lshl_add_u64 v[112:113], s[70:71], 0, v[92:93]
	v_add_co_u32_e32 v132, vcc, s61, v112
	v_mul_f32_e32 v152, v86, v82
	v_mul_f32_e32 v82, 0x3e000000, v83
	v_max_f32_e64 v83, -v81, -v81
	v_min_f32_e32 v83, 0x42fc0000, v83
	v_exp_f32_e32 v83, v83
	v_addc_co_u32_e32 v133, vcc, 0, v113, vcc
	v_lshlrev_b32_e32 v122, 16, v124
	v_mul_f32_e32 v83, v83, v82
	v_cvt_pk_bf16_f32 v82, v85, v84
	v_cvt_pk_bf16_f32 v83, v64, v83
	v_add_co_u32_e32 v84, vcc, 0x64d0f000, v112
	v_add_u32_e32 v64, 0x11f00, v156
	global_store_dwordx2 v[132:133], v[82:83], off offset:3072
	v_cvt_pk_bf16_f32 v82, v153, v151
	v_cvt_pk_bf16_f32 v83, v150, v152
	v_addc_co_u32_e32 v85, vcc, 0, v113, vcc
	ds_read_b128 v[86:89], v64
	v_add_u32_e32 v64, 0x11f10, v156
	global_store_dwordx2 v[84:85], v[82:83], off offset:3072
	ds_read_b128 v[82:85], v64
	s_and_b64 vcc, exec, s[42:43]
	s_cbranch_vccnz .LBB0_785
	s_waitcnt lgkmcnt(1)
	v_cndmask_b32_e64 v86, v86, v74, s[38:39]
	s_nop 1
	v_mov_b32_dpp v134, v123 row_shl:4 row_mask:0xf bank_mask:0x5
	v_mov_b32_dpp v134, v123 row_shr:4 row_mask:0xf bank_mask:0xa
	v_mov_b32_dpp v136, v122 row_shl:4 row_mask:0xf bank_mask:0x5
	v_mov_b32_dpp v136, v122 row_shr:4 row_mask:0xf bank_mask:0xa
	v_cndmask_b32_e64 v64, v87, v75, s[38:39]
	s_waitcnt lgkmcnt(0)
	v_cndmask_b32_e64 v135, v134, -v134, s[40:41]
	s_waitcnt lgkmcnt(0)
	v_cndmask_b32_e64 v134, v136, -v136, s[40:41]
	v_pk_mul_f32 v[134:135], v[64:65], v[134:135] op_sel_hi:[0,1]
	v_pk_fma_f32 v[122:123], v[86:87], v[122:123], v[134:135] op_sel_hi:[0,1,1]
	v_and_b32_e32 v87, 0xffff0000, v126
	s_and_b64 vcc, exec, s[42:43]
	v_and_b32_e32 v86, 0xffff0000, v124
	s_cbranch_vccz .LBB0_786

; __device__ __forceinline__ float bfe2(const v2u& w, int c) { return (c & 1) ? bfhi(w[c >> 1]) : bflo(w[c >> 1]); }
; template <int DIR> __device__ __forceinline__ void prep_gla_k(const ScanBufs<64>& B, const bf16* P, const float* w2g, const float* b2g, const f32x2* RR, const LAS f32x2* RC  , int g, int half, int lane, LAS v4u* Wl, LAS v4u* Gl  ) {
;     ...
;                     float k = bfe2(kr[j], c), q = bfe2(qr2[j], c);
;                     if (lat) { const f32x2 cs = csc[c]; const float pt = __shfl_xor(k, 4), pq = __shfl_xor(q, 4); k = k * cs.x + (second ? pt : -pt) * cs.y; q = q * cs.x + (second ? pq : -pq) * cs.y; }
.LBB0_784:
	s_waitcnt lgkmcnt(0)
	v_cndmask_b32_e64 v82, v82, v70, s[38:39]
	s_nop 1
	v_mov_b32_dpp v124, v89 row_shl:4 row_mask:0xf bank_mask:0x5
	v_mov_b32_dpp v124, v89 row_shr:4 row_mask:0xf bank_mask:0xa
	v_mov_b32_dpp v126, v88 row_shl:4 row_mask:0xf bank_mask:0x5
	v_mov_b32_dpp v126, v88 row_shr:4 row_mask:0xf bank_mask:0xa
	v_cndmask_b32_e64 v64, v83, v71, s[38:39]
	s_waitcnt lgkmcnt(0)
	v_cndmask_b32_e64 v135, v124, -v124, s[40:41]
	s_waitcnt lgkmcnt(0)
	v_cndmask_b32_e64 v134, v126, -v126, s[40:41]
	v_pk_mul_f32 v[134:135], v[64:65], v[134:135] op_sel_hi:[0,1]
	v_pk_fma_f32 v[88:89], v[82:83], v[88:89], v[134:135] op_sel_hi:[0,1,1]
	v_and_b32_e32 v83, 0xffff0000, v127
	s_and_b64 vcc, exec, s[42:43]
	v_and_b32_e32 v82, 0xffff0000, v125
	s_cbranch_vccz .LBB0_788
	s_branch .LBB0_789

; __device__ __forceinline__ float bfe2(const v2u& w, int c) { return (c & 1) ? bfhi(w[c >> 1]) : bflo(w[c >> 1]); }
; template <int DIR> __device__ __forceinline__ void prep_gla_k(const ScanBufs<64>& B, const bf16* P, const float* w2g, const float* b2g, const f32x2* RR, const LAS f32x2* RC  , int g, int half, int lane, LAS v4u* Wl, LAS v4u* Gl  ) {
;     ...
;                     float k = bfe2(kr[j], c), q = bfe2(qr2[j], c);
;                     if (lat) { const f32x2 cs = csc[c]; const float pt = __shfl_xor(k, 4), pq = __shfl_xor(q, 4); k = k * cs.x + (second ? pt : -pt) * cs.y; q = q * cs.x + (second ? pq : -pq) * cs.y; }
.LBB0_786:
	v_cndmask_b32_e64 v88, v88, v76, s[38:39]
	s_nop 0
	s_nop 1
	v_mov_b32_dpp v124, v87 row_shl:4 row_mask:0xf bank_mask:0x5
	v_mov_b32_dpp v124, v87 row_shr:4 row_mask:0xf bank_mask:0xa
	v_mov_b32_dpp v126, v86 row_shl:4 row_mask:0xf bank_mask:0x5
	v_mov_b32_dpp v126, v86 row_shr:4 row_mask:0xf bank_mask:0xa
	v_cndmask_b32_e64 v64, v89, v77, s[38:39]
	s_waitcnt lgkmcnt(0)
	v_cndmask_b32_e64 v135, v124, -v124, s[40:41]
	s_waitcnt lgkmcnt(0)
	v_cndmask_b32_e64 v134, v126, -v126, s[40:41]
	v_pk_mul_f32 v[134:135], v[64:65], v[134:135] op_sel_hi:[0,1]
	v_pk_fma_f32 v[86:87], v[88:89], v[86:87], v[134:135] op_sel_hi:[0,1,1]
	v_lshlrev_b32_e32 v89, 16, v127
	s_and_b64 vcc, exec, s[42:43]
	v_lshlrev_b32_e32 v88, 16, v125
	s_cbranch_vccz .LBB0_784

; #define GAS __attribute__((address_space(1)))
; __device__ __forceinline__ unsigned pk2(float lo, float hi) { const f32x2_t v = {lo, hi}; const bf16x2_t b = __builtin_convertvector(v, bf16x2_t); return __builtin_bit_cast(unsigned, b); }
; __device__ __forceinline__ float ex2(float x) { return __builtin_amdgcn_exp2f(x); }
; __device__ __forceinline__ float bfe(const v4u& w, int c) { return (c & 1) ? bfhi(w[c >> 1]) : bflo(w[c >> 1]); }
; __device__ __forceinline__ float bfe2(const v2u& w, int c) { return (c & 1) ? bfhi(w[c >> 1]) : bflo(w[c >> 1]); }
; template <int DIR> __device__ __forceinline__ void prep_gla_k(const ScanBufs<64>& B, const bf16* P, const float* w2g, const float* b2g, const f32x2* RR, const LAS f32x2* RC  , int g, int half, int lane, LAS v4u* Wl, LAS v4u* Gl  ) {
;     ...
;                 for (int c = 0; c < 4; ++c) { float x = b2[c];
; #pragma unroll
;                     for (int r = 0; r < 8; ++r) { x += bfe(l0[j], r) * w2[r][c]; x += bfe(l1[j], r) * w2[8 + r][c]; }
;                     const float la = (fminf(x, 0.f) * 1.4426950408889634f - __log2f(1.f + __expf(-fabsf(x)))) * 0.0625f;
;                     float k = bfe2(kr[j], c), q = bfe2(qr2[j], c);
;                     if (lat) { const f32x2 cs = csc[c]; const float pt = __shfl_xor(k, 4), pq = __shfl_xor(q, 4); k = k * cs.x + (second ? pt : -pt) * cs.y; q = q * cs.x + (second ? pq : -pq) * cs.y; }
;                     const float e = cum[c]; cum[c] += la; kv[c] = k * ex2(e); kp[hf * 4 + j][c] = kv[c]; ev[c] = q * 0.125f * ex2(fminf(-e, 126.f)); }
;                 { v2u ew; ew.x = pk2(ev[0], ev[1]); ew.y = pk2(ev[2], ev[3]); *(GAS v2u*)(Ep + (size_t)t * 512) = ew; }
;                 { v2u kw; kw.x = pk2(kv[0], kv[1]); kw.y = pk2(kv[2], kv[3]); *(GAS v2u*)(Kp + (size_t)t * 512) = kw; } } }
.LBB0_788:
	v_cndmask_b32_e64 v84, v84, v72, s[38:39]
	s_nop 0
	s_nop 1
	v_mov_b32_dpp v124, v83 row_shl:4 row_mask:0xf bank_mask:0x5
	v_mov_b32_dpp v124, v83 row_shr:4 row_mask:0xf bank_mask:0xa
	v_mov_b32_dpp v126, v82 row_shl:4 row_mask:0xf bank_mask:0x5
	v_mov_b32_dpp v126, v82 row_shr:4 row_mask:0xf bank_mask:0xa
	v_cndmask_b32_e64 v64, v85, v73, s[38:39]
	s_waitcnt lgkmcnt(0)
	v_cndmask_b32_e64 v125, v124, -v124, s[40:41]
	s_waitcnt lgkmcnt(0)
	v_cndmask_b32_e64 v124, v126, -v126, s[40:41]
	v_pk_mul_f32 v[124:125], v[64:65], v[124:125] op_sel_hi:[0,1]
	v_pk_fma_f32 v[82:83], v[84:85], v[82:83], v[124:125] op_sel_hi:[0,1,1]
.LBB0_789:
	s_lshl_b32 s69, s58, 16
	s_lshl_b32 s68, s60, 16
	v_fma_f32 v64, s69, v58, v68
	s_and_b32 s67, s58, 0xffff0000
	v_fmac_f32_e32 v64, s68, v26
	s_and_b32 s66, s60, 0xffff0000
	v_fmac_f32_e32 v64, s67, v2
	s_lshl_b32 s65, s56, 16
	v_fmac_f32_e32 v64, s66, v34
	s_lshl_b32 s64, s59, 16
	v_fmac_f32_e32 v64, s65, v6
	s_and_b32 s63, s56, 0xffff0000
	v_fmac_f32_e32 v64, s64, v38
	s_and_b32 s62, s59, 0xffff0000
	v_fmac_f32_e32 v64, s63, v10
	s_lshl_b32 s61, s54, 16
	v_fmac_f32_e32 v64, s62, v42
	s_lshl_b32 s60, s57, 16
	v_fmac_f32_e32 v64, s61, v14
	s_and_b32 s59, s54, 0xffff0000
	v_fmac_f32_e32 v64, s60, v50
	s_and_b32 s58, s57, 0xffff0000
	v_fmac_f32_e32 v64, s59, v30
	s_lshl_b32 s57, s53, 16
	v_fmac_f32_e32 v64, s58, v46
	s_lshl_b32 s56, s55, 16
	v_fmac_f32_e32 v64, s57, v18
	s_and_b32 s54, s53, 0xffff0000
	v_fmac_f32_e32 v64, s56, v54
	s_and_b32 s53, s55, 0xffff0000
	v_fmac_f32_e32 v64, s54, v22
	v_fmac_f32_e32 v64, s53, v62
	s_mov_b32 s70, 0xbfb8aa3b
	v_min_f32_e32 v84, 0, v64
	v_mul_f32_e64 v64, |v64|, s70
	v_exp_f32_e32 v64, v64
	s_mov_b32 s71, 0x3fb8aa3b
	s_mov_b32 s55, 0x42fc0000
	v_lshlrev_b32_e32 v125, 16, v116
	v_add_f32_e32 v64, 1.0, v64
	v_log_f32_e32 v64, v64
	v_lshlrev_b32_e32 v124, 16, v114
	v_fma_f32 v64, v84, s71, -v64
	v_fmac_f32_e32 v80, 0x3d800000, v64
	v_min_f32_e64 v85, -v80, s55
	v_exp_f32_e32 v85, v85
	v_mul_f32_e32 v84, 0x3e000000, v89
	v_exp_f32_e32 v64, v80
	v_mul_f32_e32 v84, v85, v84
	v_fma_f32 v85, s69, v57, v67
	v_fmac_f32_e32 v85, s68, v25
	v_fmac_f32_e32 v85, s67, v1
	v_fmac_f32_e32 v85, s66, v33
	v_fmac_f32_e32 v85, s65, v5
	v_fmac_f32_e32 v85, s64, v37
	v_fmac_f32_e32 v85, s63, v9
	v_fmac_f32_e32 v85, s62, v41
	v_fmac_f32_e32 v85, s61, v13
	v_fmac_f32_e32 v85, s60, v49
	v_fmac_f32_e32 v85, s59, v29
	v_fmac_f32_e32 v85, s58, v45
	v_fmac_f32_e32 v85, s57, v17
	v_fmac_f32_e32 v85, s56, v53
	v_fmac_f32_e32 v85, s54, v21
	v_fmac_f32_e32 v85, s53, v61
	v_mul_f32_e32 v64, v64, v88
	v_min_f32_e32 v88, 0, v85
	v_mul_f32_e64 v85, |v85|, s70
	v_exp_f32_e32 v85, v85
	s_nop 0
	v_add_f32_e32 v85, 1.0, v85
	v_log_f32_e32 v85, v85
	s_nop 0
	v_fma_f32 v85, v88, s71, -v85
	v_fmac_f32_e32 v79, 0x3d800000, v85
	v_exp_f32_e32 v85, v79
	s_nop 0
	v_mul_f32_e32 v155, v85, v86
	v_min_f32_e64 v86, -v79, s55
	v_exp_f32_e32 v86, v86
	v_mul_f32_e32 v85, 0x3e000000, v87
	v_mul_f32_e32 v85, v86, v85
	v_fma_f32 v86, s69, v56, v66
	v_fmac_f32_e32 v86, s68, v24
	v_fmac_f32_e32 v86, s67, v0
	v_fmac_f32_e32 v86, s66, v32
	v_fmac_f32_e32 v86, s65, v4
	v_fmac_f32_e32 v86, s64, v36
	v_fmac_f32_e32 v86, s63, v8
	v_fmac_f32_e32 v86, s62, v40
	v_fmac_f32_e32 v86, s61, v12
	v_fmac_f32_e32 v86, s60, v48
	v_fmac_f32_e32 v86, s59, v28
	v_fmac_f32_e32 v86, s58, v44
	v_fmac_f32_e32 v86, s57, v16
	v_fmac_f32_e32 v86, s56, v52
	v_fmac_f32_e32 v86, s54, v20
	v_fmac_f32_e32 v86, s53, v60
	v_min_f32_e32 v87, 0, v86
	v_mul_f32_e64 v86, |v86|, s70
	v_exp_f32_e32 v86, v86
	s_nop 0
	v_add_f32_e32 v86, 1.0, v86
	v_log_f32_e32 v86, v86
	s_nop 0
	v_fma_f32 v86, v87, s71, -v86
	v_fmac_f32_e32 v78, 0x3d800000, v86
	v_exp_f32_e32 v86, v78
	v_min_f32_e64 v87, -v78, s55
	v_exp_f32_e32 v87, v87
	v_mul_f32_e32 v122, v86, v122
	v_mul_f32_e32 v86, 0x3e000000, v123
	v_mul_f32_e32 v86, v87, v86
	v_fma_f32 v87, s69, v59, v69
	v_fmac_f32_e32 v87, s68, v27
	v_fmac_f32_e32 v87, s67, v3
	v_fmac_f32_e32 v87, s66, v35
	v_fmac_f32_e32 v87, s65, v7
	v_fmac_f32_e32 v87, s64, v39
	v_fmac_f32_e32 v87, s63, v11
	v_fmac_f32_e32 v87, s62, v43
	v_fmac_f32_e32 v87, s61, v15
	v_fmac_f32_e32 v87, s60, v51
	v_fmac_f32_e32 v87, s59, v31
	v_fmac_f32_e32 v87, s58, v47
	v_fmac_f32_e32 v87, s57, v19
	v_fmac_f32_e32 v87, s56, v55
	v_fmac_f32_e32 v87, s54, v23
	v_fmac_f32_e32 v87, s53, v63
	v_min_f32_e32 v88, 0, v87
	v_mul_f32_e64 v87, |v87|, s70
	v_exp_f32_e32 v87, v87
	s_nop 0
	v_add_f32_e32 v87, 1.0, v87
	v_log_f32_e32 v87, v87
	s_nop 0
	v_fma_f32 v87, v88, s71, -v87
	v_fmac_f32_e32 v81, 0x3d800000, v87
	v_exp_f32_e32 v87, v81
	s_nop 0
	v_mul_f32_e32 v123, v87, v82
	v_mul_f32_e32 v82, 0x3e000000, v83
	v_min_f32_e64 v83, -v81, s55
	v_exp_f32_e32 v83, v83
	s_nop 0
	v_mul_f32_e32 v83, v83, v82
	v_cvt_pk_bf16_f32 v82, v86, v85
	v_cvt_pk_bf16_f32 v83, v84, v83
	v_add_co_u32_e32 v84, vcc, 0x64d0f000, v112
	global_store_dwordx2 v[132:133], v[82:83], off offset:2048
	v_cvt_pk_bf16_f32 v82, v122, v155
	v_cvt_pk_bf16_f32 v83, v64, v123
	v_addc_co_u32_e32 v85, vcc, 0, v113, vcc
	global_store_dwordx2 v[84:85], v[82:83], off offset:2048
	v_add_u32_e32 v82, 0x11e80, v156
	ds_read_b128 v[86:89], v82
	v_add_u32_e32 v82, 0x11e90, v156
	ds_read_b128 v[82:85], v82
	s_and_b64 vcc, exec, s[42:43]
	s_cbranch_vccnz .LBB0_793
	s_waitcnt lgkmcnt(1)
	v_cndmask_b32_e64 v86, v86, v74, s[38:39]
	s_nop 1
	v_mov_b32_dpp v127, v125 row_shl:4 row_mask:0xf bank_mask:0x5
	v_mov_b32_dpp v127, v125 row_shr:4 row_mask:0xf bank_mask:0xa
	v_mov_b32_dpp v134, v124 row_shl:4 row_mask:0xf bank_mask:0x5
	v_mov_b32_dpp v134, v124 row_shr:4 row_mask:0xf bank_mask:0xa
	v_cndmask_b32_e64 v126, v87, v75, s[38:39]
	s_waitcnt lgkmcnt(0)
	v_cndmask_b32_e64 v135, v127, -v127, s[40:41]
	s_waitcnt lgkmcnt(0)
	v_cndmask_b32_e64 v134, v134, -v134, s[40:41]
	v_pk_mul_f32 v[126:127], v[126:127], v[134:135] op_sel_hi:[0,1]
	v_pk_fma_f32 v[124:125], v[86:87], v[124:125], v[126:127] op_sel_hi:[0,1,1]
	v_and_b32_e32 v87, 0xffff0000, v116
	s_and_b64 vcc, exec, s[42:43]
	v_and_b32_e32 v86, 0xffff0000, v114
	s_cbranch_vccz .LBB0_794

; __device__ __forceinline__ float bfe2(const v2u& w, int c) { return (c & 1) ? bfhi(w[c >> 1]) : bflo(w[c >> 1]); }
; template <int DIR> __device__ __forceinline__ void prep_gla_k(const ScanBufs<64>& B, const bf16* P, const float* w2g, const float* b2g, const f32x2* RR, const LAS f32x2* RC  , int g, int half, int lane, LAS v4u* Wl, LAS v4u* Gl  ) {
;     ...
;                     float k = bfe2(kr[j], c), q = bfe2(qr2[j], c);
;                     if (lat) { const f32x2 cs = csc[c]; const float pt = __shfl_xor(k, 4), pq = __shfl_xor(q, 4); k = k * cs.x + (second ? pt : -pt) * cs.y; q = q * cs.x + (second ? pq : -pq) * cs.y; }
.LBB0_792:
	s_waitcnt lgkmcnt(0)
	v_cndmask_b32_e64 v82, v82, v70, s[38:39]
	s_nop 1
	v_mov_b32_dpp v116, v89 row_shl:4 row_mask:0xf bank_mask:0x5
	v_mov_b32_dpp v116, v89 row_shr:4 row_mask:0xf bank_mask:0xa
	v_mov_b32_dpp v126, v88 row_shl:4 row_mask:0xf bank_mask:0x5
	v_mov_b32_dpp v126, v88 row_shr:4 row_mask:0xf bank_mask:0xa
	v_cndmask_b32_e64 v114, v83, v71, s[38:39]
	s_waitcnt lgkmcnt(0)
	v_cndmask_b32_e64 v127, v116, -v116, s[40:41]
	s_waitcnt lgkmcnt(0)
	v_cndmask_b32_e64 v126, v126, -v126, s[40:41]
	v_pk_mul_f32 v[126:127], v[114:115], v[126:127] op_sel_hi:[0,1]
	v_pk_fma_f32 v[88:89], v[82:83], v[88:89], v[126:127] op_sel_hi:[0,1,1]
	v_and_b32_e32 v83, 0xffff0000, v117
	s_and_b64 vcc, exec, s[42:43]
	v_and_b32_e32 v82, 0xffff0000, v115
	s_cbranch_vccz .LBB0_796
	s_branch .LBB0_797

; __device__ __forceinline__ float bfe2(const v2u& w, int c) { return (c & 1) ? bfhi(w[c >> 1]) : bflo(w[c >> 1]); }
; template <int DIR> __device__ __forceinline__ void prep_gla_k(const ScanBufs<64>& B, const bf16* P, const float* w2g, const float* b2g, const f32x2* RR, const LAS f32x2* RC  , int g, int half, int lane, LAS v4u* Wl, LAS v4u* Gl  ) {
;     ...
;                     float k = bfe2(kr[j], c), q = bfe2(qr2[j], c);
;                     if (lat) { const f32x2 cs = csc[c]; const float pt = __shfl_xor(k, 4), pq = __shfl_xor(q, 4); k = k * cs.x + (second ? pt : -pt) * cs.y; q = q * cs.x + (second ? pq : -pq) * cs.y; }
.LBB0_794:
	v_cndmask_b32_e64 v88, v88, v76, s[38:39]
	s_nop 0
	s_nop 1
	v_mov_b32_dpp v116, v87 row_shl:4 row_mask:0xf bank_mask:0x5
	v_mov_b32_dpp v116, v87 row_shr:4 row_mask:0xf bank_mask:0xa
	v_mov_b32_dpp v126, v86 row_shl:4 row_mask:0xf bank_mask:0x5
	v_mov_b32_dpp v126, v86 row_shr:4 row_mask:0xf bank_mask:0xa
	v_cndmask_b32_e64 v114, v89, v77, s[38:39]
	s_waitcnt lgkmcnt(0)
	v_cndmask_b32_e64 v127, v116, -v116, s[40:41]
	s_waitcnt lgkmcnt(0)
	v_cndmask_b32_e64 v126, v126, -v126, s[40:41]
	v_pk_mul_f32 v[126:127], v[114:115], v[126:127] op_sel_hi:[0,1]
	v_pk_fma_f32 v[86:87], v[88:89], v[86:87], v[126:127] op_sel_hi:[0,1,1]
	v_lshlrev_b32_e32 v89, 16, v117
	s_and_b64 vcc, exec, s[42:43]
	v_lshlrev_b32_e32 v88, 16, v115
	s_cbranch_vccz .LBB0_792

; #define GAS __attribute__((address_space(1)))
; __device__ __forceinline__ unsigned pk2(float lo, float hi) { const f32x2_t v = {lo, hi}; const bf16x2_t b = __builtin_convertvector(v, bf16x2_t); return __builtin_bit_cast(unsigned, b); }
; __device__ __forceinline__ float ex2(float x) { return __builtin_amdgcn_exp2f(x); }
; __device__ __forceinline__ float bfe(const v4u& w, int c) { return (c & 1) ? bfhi(w[c >> 1]) : bflo(w[c >> 1]); }
; __device__ __forceinline__ float bfe2(const v2u& w, int c) { return (c & 1) ? bfhi(w[c >> 1]) : bflo(w[c >> 1]); }
; template <int DIR> __device__ __forceinline__ void prep_gla_k(const ScanBufs<64>& B, const bf16* P, const float* w2g, const float* b2g, const f32x2* RR, const LAS f32x2* RC  , int g, int half, int lane, LAS v4u* Wl, LAS v4u* Gl  ) {
;     ...
;                 for (int c = 0; c < 4; ++c) { float x = b2[c];
; #pragma unroll
;                     for (int r = 0; r < 8; ++r) { x += bfe(l0[j], r) * w2[r][c]; x += bfe(l1[j], r) * w2[8 + r][c]; }
;                     const float la = (fminf(x, 0.f) * 1.4426950408889634f - __log2f(1.f + __expf(-fabsf(x)))) * 0.0625f;
;                     float k = bfe2(kr[j], c), q = bfe2(qr2[j], c);
;                     if (lat) { const f32x2 cs = csc[c]; const float pt = __shfl_xor(k, 4), pq = __shfl_xor(q, 4); k = k * cs.x + (second ? pt : -pt) * cs.y; q = q * cs.x + (second ? pq : -pq) * cs.y; }
;                     const float e = cum[c]; cum[c] += la; kv[c] = k * ex2(e); kp[hf * 4 + j][c] = kv[c]; ev[c] = q * 0.125f * ex2(fminf(-e, 126.f)); }
;                 { v2u ew; ew.x = pk2(ev[0], ev[1]); ew.y = pk2(ev[2], ev[3]); *(GAS v2u*)(Ep + (size_t)t * 512) = ew; }
;                 { v2u kw; kw.x = pk2(kv[0], kv[1]); kw.y = pk2(kv[2], kv[3]); *(GAS v2u*)(Kp + (size_t)t * 512) = kw; } } }
.LBB0_796:
	v_cndmask_b32_e64 v84, v84, v72, s[38:39]
	s_nop 0
	s_nop 1
	v_mov_b32_dpp v115, v83 row_shl:4 row_mask:0xf bank_mask:0x5
	v_mov_b32_dpp v115, v83 row_shr:4 row_mask:0xf bank_mask:0xa
	v_mov_b32_dpp v116, v82 row_shl:4 row_mask:0xf bank_mask:0x5
	v_mov_b32_dpp v116, v82 row_shr:4 row_mask:0xf bank_mask:0xa
	v_cndmask_b32_e64 v114, v85, v73, s[38:39]
	s_waitcnt lgkmcnt(0)
	v_cndmask_b32_e64 v117, v115, -v115, s[40:41]
	s_waitcnt lgkmcnt(0)
	v_cndmask_b32_e64 v116, v116, -v116, s[40:41]
	v_pk_mul_f32 v[114:115], v[114:115], v[116:117] op_sel_hi:[0,1]
	v_pk_fma_f32 v[82:83], v[84:85], v[82:83], v[114:115] op_sel_hi:[0,1,1]
.LBB0_797:
	s_lshl_b32 s61, s50, 16
	s_lshl_b32 s60, s52, 16
	v_fma_f32 v84, s61, v58, v68
	s_and_b32 s59, s50, 0xffff0000
	v_fmac_f32_e32 v84, s60, v26
	s_and_b32 s58, s52, 0xffff0000
	v_fmac_f32_e32 v84, s59, v2
	s_lshl_b32 s57, s47, 16
	v_fmac_f32_e32 v84, s58, v34
	s_lshl_b32 s56, s51, 16
	v_fmac_f32_e32 v84, s57, v6
	s_and_b32 s55, s47, 0xffff0000
	v_fmac_f32_e32 v84, s56, v38
	s_and_b32 s54, s51, 0xffff0000
	v_fmac_f32_e32 v84, s55, v10
	s_lshl_b32 s53, s46, 16
	v_fmac_f32_e32 v84, s54, v42
	s_lshl_b32 s52, s48, 16
	v_fmac_f32_e32 v84, s53, v14
	s_and_b32 s51, s46, 0xffff0000
	v_fmac_f32_e32 v84, s52, v50
	s_and_b32 s50, s48, 0xffff0000
	v_fmac_f32_e32 v84, s51, v30
	s_lshl_b32 s48, s33, 16
	v_fmac_f32_e32 v84, s50, v46
	s_lshl_b32 s47, s49, 16
	v_fmac_f32_e32 v84, s48, v18
	s_and_b32 s46, s33, 0xffff0000
	v_fmac_f32_e32 v84, s47, v54
	s_and_b32 s33, s49, 0xffff0000
	v_fmac_f32_e32 v84, s46, v22
	v_fmac_f32_e32 v84, s33, v62
	s_mov_b32 s62, 0xbfb8aa3b
	v_min_f32_e32 v85, 0, v84
	v_mul_f32_e64 v84, |v84|, s62
	v_exp_f32_e32 v84, v84
	s_mov_b32 s63, 0x3fb8aa3b
	s_mov_b32 s49, 0x42fc0000
	v_lshlrev_b32_e32 v115, 16, v110
	v_add_f32_e32 v84, 1.0, v84
	v_log_f32_e32 v84, v84
	v_lshlrev_b32_e32 v114, 16, v108
	v_fma_f32 v84, v85, s63, -v84
	v_fmac_f32_e32 v80, 0x3d800000, v84
	v_exp_f32_e32 v84, v80
	v_min_f32_e64 v85, -v80, s49
	v_exp_f32_e32 v85, v85
	v_mul_f32_e32 v157, v84, v88
	v_mul_f32_e32 v84, 0x3e000000, v89
	v_mul_f32_e32 v84, v85, v84
	v_fma_f32 v85, s61, v57, v67
	v_fmac_f32_e32 v85, s60, v25
	v_fmac_f32_e32 v85, s59, v1
	v_fmac_f32_e32 v85, s58, v33
	v_fmac_f32_e32 v85, s57, v5
	v_fmac_f32_e32 v85, s56, v37
	v_fmac_f32_e32 v85, s55, v9
	v_fmac_f32_e32 v85, s54, v41
	v_fmac_f32_e32 v85, s53, v13
	v_fmac_f32_e32 v85, s52, v49
	v_fmac_f32_e32 v85, s51, v29
	v_fmac_f32_e32 v85, s50, v45
	v_fmac_f32_e32 v85, s48, v17
	v_fmac_f32_e32 v85, s47, v53
	v_fmac_f32_e32 v85, s46, v21
	v_fmac_f32_e32 v85, s33, v61
	v_min_f32_e32 v88, 0, v85
	v_mul_f32_e64 v85, |v85|, s62
	v_exp_f32_e32 v85, v85
	s_nop 0
	v_add_f32_e32 v85, 1.0, v85
	v_log_f32_e32 v85, v85
	s_nop 0
	v_fma_f32 v85, v88, s63, -v85
	v_fmac_f32_e32 v79, 0x3d800000, v85
	v_exp_f32_e32 v85, v79
	s_nop 0
	v_mul_f32_e32 v158, v85, v86
	v_min_f32_e64 v86, -v79, s49
	v_exp_f32_e32 v86, v86
	v_mul_f32_e32 v85, 0x3e000000, v87
	v_mul_f32_e32 v85, v86, v85
	v_fma_f32 v86, s61, v56, v66
	v_fmac_f32_e32 v86, s60, v24
	v_fmac_f32_e32 v86, s59, v0
	v_fmac_f32_e32 v86, s58, v32
	v_fmac_f32_e32 v86, s57, v4
	v_fmac_f32_e32 v86, s56, v36
	v_fmac_f32_e32 v86, s55, v8
	v_fmac_f32_e32 v86, s54, v40
	v_fmac_f32_e32 v86, s53, v12
	v_fmac_f32_e32 v86, s52, v48
	v_fmac_f32_e32 v86, s51, v28
	v_fmac_f32_e32 v86, s50, v44
	v_fmac_f32_e32 v86, s48, v16
	v_fmac_f32_e32 v86, s47, v52
	v_fmac_f32_e32 v86, s46, v20
	v_fmac_f32_e32 v86, s33, v60
	v_min_f32_e32 v87, 0, v86
	v_mul_f32_e64 v86, |v86|, s62
	v_exp_f32_e32 v86, v86
	s_nop 0
	v_add_f32_e32 v86, 1.0, v86
	v_log_f32_e32 v86, v86
	s_nop 0
	v_fma_f32 v86, v87, s63, -v86
	v_fmac_f32_e32 v78, 0x3d800000, v86
	v_exp_f32_e32 v86, v78
	v_min_f32_e64 v87, -v78, s49
	v_exp_f32_e32 v87, v87
	v_mul_f32_e32 v159, v86, v124
	v_mul_f32_e32 v86, 0x3e000000, v125
	v_mul_f32_e32 v86, v87, v86
	v_fma_f32 v87, s61, v59, v69
	v_fmac_f32_e32 v87, s60, v27
	v_fmac_f32_e32 v87, s59, v3
	v_fmac_f32_e32 v87, s58, v35
	v_fmac_f32_e32 v87, s57, v7
	v_fmac_f32_e32 v87, s56, v39
	v_fmac_f32_e32 v87, s55, v11
	v_fmac_f32_e32 v87, s54, v43
	v_fmac_f32_e32 v87, s53, v15
	v_fmac_f32_e32 v87, s52, v51
	v_fmac_f32_e32 v87, s51, v31
	v_fmac_f32_e32 v87, s50, v47
	v_fmac_f32_e32 v87, s48, v19
	v_fmac_f32_e32 v87, s47, v55
	v_fmac_f32_e32 v87, s46, v23
	v_fmac_f32_e32 v87, s33, v63
	v_min_f32_e32 v88, 0, v87
	v_mul_f32_e64 v87, |v87|, s62
	v_exp_f32_e32 v87, v87
	s_nop 0
	v_add_f32_e32 v87, 1.0, v87
	v_log_f32_e32 v87, v87
	s_nop 0
	v_fma_f32 v87, v88, s63, -v87
	v_fmac_f32_e32 v81, 0x3d800000, v87
	v_exp_f32_e32 v87, v81
	s_nop 0
	v_mul_f32_e32 v160, v87, v82
	v_mul_f32_e32 v82, 0x3e000000, v83
	v_min_f32_e64 v83, -v81, s49
	v_exp_f32_e32 v83, v83
	s_nop 0
	v_mul_f32_e32 v83, v83, v82
	v_cvt_pk_bf16_f32 v82, v86, v85
	v_cvt_pk_bf16_f32 v83, v84, v83
	v_add_co_u32_e32 v84, vcc, 0x64d0f000, v112
	global_store_dwordx2 v[132:133], v[82:83], off offset:1024
	v_cvt_pk_bf16_f32 v82, v159, v158
	v_cvt_pk_bf16_f32 v83, v157, v160
	v_addc_co_u32_e32 v85, vcc, 0, v113, vcc
	global_store_dwordx2 v[84:85], v[82:83], off offset:1024
	v_add_u32_e32 v82, 0x11e00, v156
	ds_read_b128 v[86:89], v82
	v_add_u32_e32 v82, 0x11e10, v156
	ds_read_b128 v[82:85], v82
	s_and_b64 vcc, exec, s[42:43]
	s_cbranch_vccnz .LBB0_801
	s_waitcnt lgkmcnt(1)
	v_cndmask_b32_e64 v86, v86, v74, s[38:39]
	s_nop 1
	v_mov_b32_dpp v117, v115 row_shl:4 row_mask:0xf bank_mask:0x5
	v_mov_b32_dpp v117, v115 row_shr:4 row_mask:0xf bank_mask:0xa
	v_mov_b32_dpp v124, v114 row_shl:4 row_mask:0xf bank_mask:0x5
	v_mov_b32_dpp v124, v114 row_shr:4 row_mask:0xf bank_mask:0xa
	v_cndmask_b32_e64 v116, v87, v75, s[38:39]
	s_waitcnt lgkmcnt(0)
	v_cndmask_b32_e64 v125, v117, -v117, s[40:41]
	s_waitcnt lgkmcnt(0)
	v_cndmask_b32_e64 v124, v124, -v124, s[40:41]
	v_pk_mul_f32 v[116:117], v[116:117], v[124:125] op_sel_hi:[0,1]
	v_pk_fma_f32 v[114:115], v[86:87], v[114:115], v[116:117] op_sel_hi:[0,1,1]
	v_and_b32_e32 v87, 0xffff0000, v110
	s_and_b64 vcc, exec, s[42:43]
	v_and_b32_e32 v86, 0xffff0000, v108
	s_cbranch_vccz .LBB0_802

; __device__ __forceinline__ float bfe2(const v2u& w, int c) { return (c & 1) ? bfhi(w[c >> 1]) : bflo(w[c >> 1]); }
; template <int DIR> __device__ __forceinline__ void prep_gla_k(const ScanBufs<64>& B, const bf16* P, const float* w2g, const float* b2g, const f32x2* RR, const LAS f32x2* RC  , int g, int half, int lane, LAS v4u* Wl, LAS v4u* Gl  ) {
;     ...
;                     float k = bfe2(kr[j], c), q = bfe2(qr2[j], c);
;                     if (lat) { const f32x2 cs = csc[c]; const float pt = __shfl_xor(k, 4), pq = __shfl_xor(q, 4); k = k * cs.x + (second ? pt : -pt) * cs.y; q = q * cs.x + (second ? pq : -pq) * cs.y; }
.LBB0_800:
	s_waitcnt lgkmcnt(0)
	v_cndmask_b32_e64 v82, v82, v70, s[38:39]
	s_nop 1
	v_mov_b32_dpp v110, v89 row_shl:4 row_mask:0xf bank_mask:0x5
	v_mov_b32_dpp v110, v89 row_shr:4 row_mask:0xf bank_mask:0xa
	v_mov_b32_dpp v116, v88 row_shl:4 row_mask:0xf bank_mask:0x5
	v_mov_b32_dpp v116, v88 row_shr:4 row_mask:0xf bank_mask:0xa
	v_cndmask_b32_e64 v108, v83, v71, s[38:39]
	s_waitcnt lgkmcnt(0)
	v_cndmask_b32_e64 v117, v110, -v110, s[40:41]
	s_waitcnt lgkmcnt(0)
	v_cndmask_b32_e64 v116, v116, -v116, s[40:41]
	v_pk_mul_f32 v[116:117], v[108:109], v[116:117] op_sel_hi:[0,1]
	v_pk_fma_f32 v[88:89], v[82:83], v[88:89], v[116:117] op_sel_hi:[0,1,1]
	v_and_b32_e32 v83, 0xffff0000, v111
	s_and_b64 vcc, exec, s[42:43]
	v_and_b32_e32 v82, 0xffff0000, v109
	s_cbranch_vccz .LBB0_804
	s_branch .LBB0_805

; __device__ __forceinline__ float bfe2(const v2u& w, int c) { return (c & 1) ? bfhi(w[c >> 1]) : bflo(w[c >> 1]); }
; template <int DIR> __device__ __forceinline__ void prep_gla_k(const ScanBufs<64>& B, const bf16* P, const float* w2g, const float* b2g, const f32x2* RR, const LAS f32x2* RC  , int g, int half, int lane, LAS v4u* Wl, LAS v4u* Gl  ) {
;     ...
;                     float k = bfe2(kr[j], c), q = bfe2(qr2[j], c);
;                     if (lat) { const f32x2 cs = csc[c]; const float pt = __shfl_xor(k, 4), pq = __shfl_xor(q, 4); k = k * cs.x + (second ? pt : -pt) * cs.y; q = q * cs.x + (second ? pq : -pq) * cs.y; }
.LBB0_802:
	v_cndmask_b32_e64 v88, v88, v76, s[38:39]
	s_nop 0
	s_nop 1
	v_mov_b32_dpp v110, v87 row_shl:4 row_mask:0xf bank_mask:0x5
	v_mov_b32_dpp v110, v87 row_shr:4 row_mask:0xf bank_mask:0xa
	v_mov_b32_dpp v116, v86 row_shl:4 row_mask:0xf bank_mask:0x5
	v_mov_b32_dpp v116, v86 row_shr:4 row_mask:0xf bank_mask:0xa
	v_cndmask_b32_e64 v108, v89, v77, s[38:39]
	s_waitcnt lgkmcnt(0)
	v_cndmask_b32_e64 v117, v110, -v110, s[40:41]
	s_waitcnt lgkmcnt(0)
	v_cndmask_b32_e64 v116, v116, -v116, s[40:41]
	v_pk_mul_f32 v[116:117], v[108:109], v[116:117] op_sel_hi:[0,1]
	v_pk_fma_f32 v[86:87], v[88:89], v[86:87], v[116:117] op_sel_hi:[0,1,1]
	v_lshlrev_b32_e32 v89, 16, v111
	s_and_b64 vcc, exec, s[42:43]
	v_lshlrev_b32_e32 v88, 16, v109
	s_cbranch_vccz .LBB0_800

; __device__ __forceinline__ float bfe2(const v2u& w, int c) { return (c & 1) ? bfhi(w[c >> 1]) : bflo(w[c >> 1]); }
; template <int DIR> __device__ __forceinline__ void prep_gla_k(const ScanBufs<64>& B, const bf16* P, const float* w2g, const float* b2g, const f32x2* RR, const LAS f32x2* RC  , int g, int half, int lane, LAS v4u* Wl, LAS v4u* Gl  ) {
;     ...
;                     float k = bfe2(kr[j], c), q = bfe2(qr2[j], c);
;                     if (lat) { const f32x2 cs = csc[c]; const float pt = __shfl_xor(k, 4), pq = __shfl_xor(q, 4); k = k * cs.x + (second ? pt : -pt) * cs.y; q = q * cs.x + (second ? pq : -pq) * cs.y; }
.LBB0_804:
	v_cndmask_b32_e64 v84, v84, v72, s[38:39]
	s_nop 0
	s_nop 1
	v_mov_b32_dpp v109, v83 row_shl:4 row_mask:0xf bank_mask:0x5
	v_mov_b32_dpp v109, v83 row_shr:4 row_mask:0xf bank_mask:0xa
	v_mov_b32_dpp v110, v82 row_shl:4 row_mask:0xf bank_mask:0x5
	v_mov_b32_dpp v110, v82 row_shr:4 row_mask:0xf bank_mask:0xa
	v_cndmask_b32_e64 v108, v85, v73, s[38:39]
	s_waitcnt lgkmcnt(0)
	v_cndmask_b32_e64 v111, v109, -v109, s[40:41]
	s_waitcnt lgkmcnt(0)
	v_cndmask_b32_e64 v110, v110, -v110, s[40:41]
	v_pk_mul_f32 v[108:109], v[108:109], v[110:111] op_sel_hi:[0,1]
	v_pk_fma_f32 v[82:83], v[84:85], v[82:83], v[108:109] op_sel_hi:[0,1,1]

; #define LAS __attribute__((address_space(3)))
; __device__ __forceinline__ float bfe(const v4u& w, int c) { return (c & 1) ? bfhi(w[c >> 1]) : bflo(w[c >> 1]); }
; __device__ __forceinline__ float bfe2(const v2u& w, int c) { return (c & 1) ? bfhi(w[c >> 1]) : bflo(w[c >> 1]); }
; template <int DIR> __device__ __forceinline__ void prep_gla_k(const ScanBufs<64>& B, const bf16* P, const float* w2g, const float* b2g, const f32x2* RR, const LAS f32x2* RC  , int g, int half, int lane, LAS v4u* Wl, LAS v4u* Gl  ) {
;     ...
;             for (int j = 0; j < 4; ++j) { const int tt_ = t8 * 8 + hf * 4 + j; l0[j] = Gl[2 * tt_]; l1[j] = Gl[2 * tt_ + 1]; }
; #pragma unroll
;             for (int jj = 0; jj < 4; ++jj) { const int j = DIR ? jj : 3 - jj; const int t = t8 * 8 + hf * 4 + j; float ev[4], kv[4];
;                 f32x2 csc[4];
;                 { const LAS f32x4* rc4 = (const LAS f32x4*)(RC + t * 16 + j0); const f32x4 ra = rc4[0], rb = rc4[1];
;                   csc[0] = isrow ? csr[0] : (f32x2){ra[0], ra[1]}; csc[1] = isrow ? csr[1] : (f32x2){ra[2], ra[3]}; csc[2] = isrow ? csr[2] : (f32x2){rb[0], rb[1]}; csc[3] = isrow ? csr[3] : (f32x2){rb[2], rb[3]}; }
; #pragma unroll
;                 for (int c = 0; c < 4; ++c) { float x = b2[c];
; #pragma unroll
;                     for (int r = 0; r < 8; ++r) { x += bfe(l0[j], r) * w2[r][c]; x += bfe(l1[j], r) * w2[8 + r][c]; }
;                     const float la = (fminf(x, 0.f) * 1.4426950408889634f - __log2f(1.f + __expf(-fabsf(x)))) * 0.0625f;
;                     float k = bfe2(kr[j], c), q = bfe2(qr2[j], c);
;                     if (lat) { const f32x2 cs = csc[c]; const float pt = __shfl_xor(k, 4), pq = __shfl_xor(q, 4); k = k * cs.x + (second ? pt : -pt) * cs.y; q = q * cs.x + (second ? pq : -pq) * cs.y; }
.LBB0_807:
	s_add_i32 s28, s27, 0x12700
	v_mov_b32_e32 v82, s28
	ds_read_b128 v[82:85], v82
	s_add_i32 s33, s27, 0x12710
	s_add_i32 s57, s27, 0x12750
	s_add_i32 s61, s27, 0x12760
	v_lshlrev_b32_e32 v149, 16, v146
	s_waitcnt lgkmcnt(0)
	v_readfirstlane_b32 s31, v82
	v_mov_b32_e32 v82, s33
	v_readfirstlane_b32 s30, v83
	v_readfirstlane_b32 s29, v84
	v_readfirstlane_b32 s28, v85
	ds_read_b128 v[82:85], v82
	s_add_i32 s33, s27, 0x12720
	v_lshlrev_b32_e32 v148, 16, v144
	s_and_b64 vcc, exec, s[42:43]
	s_waitcnt lgkmcnt(0)
	v_readfirstlane_b32 s37, v82
	v_mov_b32_e32 v82, s33
	v_readfirstlane_b32 s36, v83
	v_readfirstlane_b32 s35, v84
	v_readfirstlane_b32 s34, v85
	ds_read_b128 v[82:85], v82
	s_add_i32 s33, s27, 0x12730
	s_waitcnt lgkmcnt(0)
	v_readfirstlane_b32 s49, v82
	v_mov_b32_e32 v82, s33
	v_readfirstlane_b32 s48, v83
	v_readfirstlane_b32 s47, v84
	v_readfirstlane_b32 s46, v85
	ds_read_b128 v[82:85], v82
	s_add_i32 s33, s27, 0x12740
	s_add_i32 s27, s27, 0x12770
	s_waitcnt lgkmcnt(0)
	v_readfirstlane_b32 s53, v82
	v_mov_b32_e32 v82, s33
	v_readfirstlane_b32 s52, v83
	v_readfirstlane_b32 s51, v84
	v_readfirstlane_b32 s50, v85
	ds_read_b128 v[82:85], v82
	s_waitcnt lgkmcnt(0)
	v_readfirstlane_b32 s56, v82
	v_mov_b32_e32 v82, s57
	v_readfirstlane_b32 s55, v83
	v_readfirstlane_b32 s54, v84
	v_readfirstlane_b32 s33, v85
	ds_read_b128 v[82:85], v82
	s_waitcnt lgkmcnt(0)
	v_readfirstlane_b32 s60, v82
	v_mov_b32_e32 v82, s61
	v_readfirstlane_b32 s59, v83
	v_readfirstlane_b32 s58, v84
	v_readfirstlane_b32 s57, v85
	ds_read_b128 v[82:85], v82
	s_waitcnt lgkmcnt(0)
	v_readfirstlane_b32 s64, v82
	v_mov_b32_e32 v82, s27
	v_readfirstlane_b32 s63, v83
	v_readfirstlane_b32 s62, v84
	v_readfirstlane_b32 s61, v85
	ds_read_b128 v[82:85], v82
	s_waitcnt lgkmcnt(0)
	v_readfirstlane_b32 s67, v82
	v_add_u32_e32 v82, 0x11d80, v156
	ds_read_b128 v[86:89], v82
	v_add_u32_e32 v82, 0x11d90, v156
	v_readfirstlane_b32 s66, v83
	v_readfirstlane_b32 s65, v84
	v_readfirstlane_b32 s27, v85
	ds_read_b128 v[82:85], v82
	s_cbranch_vccnz .LBB0_832
	s_waitcnt lgkmcnt(1)
	v_cndmask_b32_e64 v180, v87, v75, s[38:39]
	v_cndmask_b32_e64 v86, v86, v74, s[38:39]
	s_nop 1
	v_mov_b32_dpp v181, v149 row_shl:4 row_mask:0xf bank_mask:0x5
	v_mov_b32_dpp v181, v149 row_shr:4 row_mask:0xf bank_mask:0xa
	v_mov_b32_dpp v179, v148 row_shl:4 row_mask:0xf bank_mask:0x5
	v_mov_b32_dpp v179, v148 row_shr:4 row_mask:0xf bank_mask:0xa
	s_waitcnt lgkmcnt(0)
	v_cndmask_b32_e64 v183, v181, -v181, s[40:41]
	s_waitcnt lgkmcnt(0)
	v_cndmask_b32_e64 v182, v179, -v179, s[40:41]
	v_pk_mul_f32 v[180:181], v[180:181], v[182:183] op_sel_hi:[0,1]
	v_pk_fma_f32 v[148:149], v[86:87], v[148:149], v[180:181] op_sel_hi:[0,1,1]
	v_and_b32_e32 v87, 0xffff0000, v146
	s_and_b64 vcc, exec, s[42:43]
	v_and_b32_e32 v86, 0xffff0000, v144
	s_cbranch_vccz .LBB0_833

; #define GAS __attribute__((address_space(1)))
; __device__ __forceinline__ unsigned pk2(float lo, float hi) { const f32x2_t v = {lo, hi}; const bf16x2_t b = __builtin_convertvector(v, bf16x2_t); return __builtin_bit_cast(unsigned, b); }
; __device__ __forceinline__ float ex2(float x) { return __builtin_amdgcn_exp2f(x); }
; __device__ __forceinline__ float bfe(const v4u& w, int c) { return (c & 1) ? bfhi(w[c >> 1]) : bflo(w[c >> 1]); }
; __device__ __forceinline__ float bfe2(const v2u& w, int c) { return (c & 1) ? bfhi(w[c >> 1]) : bflo(w[c >> 1]); }
; template <int DIR> __device__ __forceinline__ void prep_gla_k(const ScanBufs<64>& B, const bf16* P, const float* w2g, const float* b2g, const f32x2* RR, const LAS f32x2* RC  , int g, int half, int lane, LAS v4u* Wl, LAS v4u* Gl  ) {
;     ...
;                 for (int c = 0; c < 4; ++c) { float x = b2[c];
; #pragma unroll
;                     for (int r = 0; r < 8; ++r) { x += bfe(l0[j], r) * w2[r][c]; x += bfe(l1[j], r) * w2[8 + r][c]; }
;                     const float la = (fminf(x, 0.f) * 1.4426950408889634f - __log2f(1.f + __expf(-fabsf(x)))) * 0.0625f;
;                     float k = bfe2(kr[j], c), q = bfe2(qr2[j], c);
;                     if (lat) { const f32x2 cs = csc[c]; const float pt = __shfl_xor(k, 4), pq = __shfl_xor(q, 4); k = k * cs.x + (second ? pt : -pt) * cs.y; q = q * cs.x + (second ? pq : -pq) * cs.y; }
;                     const float e = cum[c]; cum[c] += la; kv[c] = k * ex2(e); kp[hf * 4 + j][c] = kv[c]; ev[c] = q * 0.125f * ex2(fminf(-e, 126.f)); }
;                 { v2u ew; ew.x = pk2(ev[0], ev[1]); ew.y = pk2(ev[2], ev[3]); *(GAS v2u*)(Ep + (size_t)t * 512) = ew; }
;                 { v2u kw; kw.x = pk2(kv[0], kv[1]); kw.y = pk2(kv[2], kv[3]); *(GAS v2u*)(Kp + (size_t)t * 512) = kw; } } }
.LBB0_810:
	s_waitcnt lgkmcnt(0)
	v_cndmask_b32_e64 v82, v82, v70, s[38:39]
	s_nop 1
	v_mov_b32_dpp v146, v89 row_shl:4 row_mask:0xf bank_mask:0x5
	v_mov_b32_dpp v146, v89 row_shr:4 row_mask:0xf bank_mask:0xa
	v_mov_b32_dpp v179, v88 row_shl:4 row_mask:0xf bank_mask:0x5
	v_mov_b32_dpp v179, v88 row_shr:4 row_mask:0xf bank_mask:0xa
	v_cndmask_b32_e64 v144, v83, v71, s[38:39]
	s_waitcnt lgkmcnt(0)
	v_cndmask_b32_e64 v181, v146, -v146, s[40:41]
	s_waitcnt lgkmcnt(0)
	v_cndmask_b32_e64 v180, v179, -v179, s[40:41]
	v_pk_mul_f32 v[180:181], v[144:145], v[180:181] op_sel_hi:[0,1]
	v_pk_fma_f32 v[88:89], v[82:83], v[88:89], v[180:181] op_sel_hi:[0,1,1]
.LBB0_811:
	s_mov_b64 s[86:87], s[76:77]
	s_waitcnt lgkmcnt(0)
	v_and_b32_e32 v83, 0xffff0000, v147
	s_and_b64 vcc, exec, s[42:43]
	v_and_b32_e32 v82, 0xffff0000, v145
	s_cbranch_vccnz .LBB0_813
	v_cndmask_b32_e64 v84, v84, v72, s[38:39]
	s_nop 0
	s_nop 1
	v_mov_b32_dpp v145, v83 row_shl:4 row_mask:0xf bank_mask:0x5
	v_mov_b32_dpp v145, v83 row_shr:4 row_mask:0xf bank_mask:0xa
	v_mov_b32_dpp v146, v82 row_shl:4 row_mask:0xf bank_mask:0x5
	v_mov_b32_dpp v146, v82 row_shr:4 row_mask:0xf bank_mask:0xa
	v_cndmask_b32_e64 v144, v85, v73, s[38:39]
	s_waitcnt lgkmcnt(0)
	v_cndmask_b32_e64 v147, v145, -v145, s[40:41]
	s_waitcnt lgkmcnt(0)
	v_cndmask_b32_e64 v146, v146, -v146, s[40:41]
	v_pk_mul_f32 v[144:145], v[144:145], v[146:147] op_sel_hi:[0,1]
	v_pk_fma_f32 v[82:83], v[84:85], v[82:83], v[144:145] op_sel_hi:[0,1,1]
.LBB0_813:
	s_lshl_b32 s76, s24, 16
	s_lshl_b32 s75, s26, 16
	v_fma_f32 v84, s76, v58, v68
	s_and_b32 s74, s24, 0xffff0000
	v_fmac_f32_e32 v84, s75, v26
	s_and_b32 s73, s26, 0xffff0000
	v_fmac_f32_e32 v84, s74, v2
	s_lshl_b32 s72, s21, 16
	v_fmac_f32_e32 v84, s73, v34
	s_lshl_b32 s71, s25, 16
	v_fmac_f32_e32 v84, s72, v6
	s_and_b32 s70, s21, 0xffff0000
	v_fmac_f32_e32 v84, s71, v38
	s_and_b32 s69, s25, 0xffff0000
	v_fmac_f32_e32 v84, s70, v10
	s_lshl_b32 s68, s20, 16
	v_fmac_f32_e32 v84, s69, v42
	s_lshl_b32 s26, s22, 16
	v_fmac_f32_e32 v84, s68, v14
	s_and_b32 s25, s20, 0xffff0000
	v_fmac_f32_e32 v84, s26, v50
	s_and_b32 s24, s22, 0xffff0000
	v_fmac_f32_e32 v84, s25, v30
	s_lshl_b32 s22, s19, 16
	v_fmac_f32_e32 v84, s24, v46
	s_lshl_b32 s21, s23, 16
	v_fmac_f32_e32 v84, s22, v18
	s_and_b32 s20, s19, 0xffff0000
	v_fmac_f32_e32 v84, s21, v54
	s_and_b32 s19, s23, 0xffff0000
	v_fmac_f32_e32 v84, s20, v22
	v_fmac_f32_e32 v84, s19, v62
	s_mov_b32 s77, 0xbfb8aa3b
	v_min_f32_e32 v85, 0, v84
	v_mul_f32_e64 v84, |v84|, s77
	v_exp_f32_e32 v84, v84
	s_mov_b32 s80, 0x3fb8aa3b
	s_mov_b32 s23, 0x42fc0000
	v_lshlrev_b32_e32 v147, 16, v142
	v_add_f32_e32 v84, 1.0, v84
	v_log_f32_e32 v84, v84
	v_lshlrev_b32_e32 v146, 16, v138
	v_fma_f32 v84, v85, s80, -v84
	v_fmac_f32_e32 v80, 0x3d800000, v84
	v_exp_f32_e32 v84, v80
	v_min_f32_e64 v85, -v80, s23
	v_exp_f32_e32 v85, v85
	v_mul_f32_e32 v179, v84, v88
	v_mul_f32_e32 v84, 0x3e000000, v89
	v_mul_f32_e32 v84, v85, v84
	v_fma_f32 v85, s76, v57, v67
	v_fmac_f32_e32 v85, s75, v25
	v_fmac_f32_e32 v85, s74, v1
	v_fmac_f32_e32 v85, s73, v33
	v_fmac_f32_e32 v85, s72, v5
	v_fmac_f32_e32 v85, s71, v37
	v_fmac_f32_e32 v85, s70, v9
	v_fmac_f32_e32 v85, s69, v41
	v_fmac_f32_e32 v85, s68, v13
	v_fmac_f32_e32 v85, s26, v49
	v_fmac_f32_e32 v85, s25, v29
	v_fmac_f32_e32 v85, s24, v45
	v_fmac_f32_e32 v85, s22, v17
	v_fmac_f32_e32 v85, s21, v53
	v_fmac_f32_e32 v85, s20, v21
	v_fmac_f32_e32 v85, s19, v61
	v_min_f32_e32 v88, 0, v85
	v_mul_f32_e64 v85, |v85|, s77
	v_exp_f32_e32 v85, v85
	s_nop 0
	v_add_f32_e32 v85, 1.0, v85
	v_log_f32_e32 v85, v85
	s_nop 0
	v_fma_f32 v85, v88, s80, -v85
	v_fmac_f32_e32 v79, 0x3d800000, v85
	v_exp_f32_e32 v85, v79
	s_nop 0
	v_mul_f32_e32 v180, v85, v86
	v_min_f32_e64 v86, -v79, s23
	v_exp_f32_e32 v86, v86
	v_mul_f32_e32 v85, 0x3e000000, v87
	v_mul_f32_e32 v85, v86, v85
	v_fma_f32 v86, s76, v56, v66
	v_fmac_f32_e32 v86, s75, v24
	v_fmac_f32_e32 v86, s74, v0
	v_fmac_f32_e32 v86, s73, v32
	v_fmac_f32_e32 v86, s72, v4
	v_fmac_f32_e32 v86, s71, v36
	v_fmac_f32_e32 v86, s70, v8
	v_fmac_f32_e32 v86, s69, v40
	v_fmac_f32_e32 v86, s68, v12
	v_fmac_f32_e32 v86, s26, v48
	v_fmac_f32_e32 v86, s25, v28
	v_fmac_f32_e32 v86, s24, v44
	v_fmac_f32_e32 v86, s22, v16
	v_fmac_f32_e32 v86, s21, v52
	v_fmac_f32_e32 v86, s20, v20
	v_fmac_f32_e32 v86, s19, v60
	v_min_f32_e32 v87, 0, v86
	v_mul_f32_e64 v86, |v86|, s77
	v_exp_f32_e32 v86, v86
	s_nop 0
	v_add_f32_e32 v86, 1.0, v86
	v_log_f32_e32 v86, v86
	s_nop 0
	v_fma_f32 v86, v87, s80, -v86
	v_fmac_f32_e32 v78, 0x3d800000, v86
	v_exp_f32_e32 v86, v78
	v_min_f32_e64 v87, -v78, s23
	v_exp_f32_e32 v87, v87
	v_mul_f32_e32 v148, v86, v148
	v_mul_f32_e32 v86, 0x3e000000, v149
	v_mul_f32_e32 v86, v87, v86
	v_fma_f32 v87, s76, v59, v69
	v_fmac_f32_e32 v87, s75, v27
	v_fmac_f32_e32 v87, s74, v3
	v_fmac_f32_e32 v87, s73, v35
	v_fmac_f32_e32 v87, s72, v7
	v_fmac_f32_e32 v87, s71, v39
	v_fmac_f32_e32 v87, s70, v11
	v_fmac_f32_e32 v87, s69, v43
	v_fmac_f32_e32 v87, s68, v15
	v_fmac_f32_e32 v87, s26, v51
	v_fmac_f32_e32 v87, s25, v31
	v_fmac_f32_e32 v87, s24, v47
	v_fmac_f32_e32 v87, s22, v19
	v_fmac_f32_e32 v87, s21, v55
	v_fmac_f32_e32 v87, s20, v23
	v_fmac_f32_e32 v87, s19, v63
	v_min_f32_e32 v88, 0, v87
	v_mul_f32_e64 v87, |v87|, s77
	v_exp_f32_e32 v87, v87
	s_mov_b32 s19, 0x65f0e000
	v_add_co_u32_e32 v144, vcc, s19, v112
	v_add_f32_e32 v87, 1.0, v87
	v_log_f32_e32 v87, v87
	v_addc_co_u32_e32 v145, vcc, 0, v113, vcc
	v_fma_f32 v87, v88, s80, -v87
	v_fmac_f32_e32 v81, 0x3d800000, v87
	v_exp_f32_e32 v87, v81
	s_nop 0
	v_mul_f32_e32 v149, v87, v82
	v_mul_f32_e32 v82, 0x3e000000, v83
	v_min_f32_e64 v83, -v81, s23
	v_exp_f32_e32 v83, v83
	s_nop 0
	v_mul_f32_e32 v83, v83, v82
	v_cvt_pk_bf16_f32 v82, v86, v85
	v_cvt_pk_bf16_f32 v83, v84, v83
	v_add_co_u32_e32 v84, vcc, 0x64d0e000, v112
	global_store_dwordx2 v[144:145], v[82:83], off offset:3072
	v_cvt_pk_bf16_f32 v82, v148, v180
	v_cvt_pk_bf16_f32 v83, v179, v149
	v_addc_co_u32_e32 v85, vcc, 0, v113, vcc
	global_store_dwordx2 v[84:85], v[82:83], off offset:3072
	v_add_u32_e32 v82, 0x11d00, v156
	ds_read_b128 v[86:89], v82
	v_add_u32_e32 v82, 0x11d10, v156
	ds_read_b128 v[82:85], v82
	s_and_b64 vcc, exec, s[42:43]
	s_cbranch_vccnz .LBB0_815
	s_waitcnt lgkmcnt(1)
	v_cndmask_b32_e64 v182, v87, v75, s[38:39]
	v_cndmask_b32_e64 v86, v86, v74, s[38:39]
	s_nop 1
	v_mov_b32_dpp v183, v147 row_shl:4 row_mask:0xf bank_mask:0x5
	v_mov_b32_dpp v183, v147 row_shr:4 row_mask:0xf bank_mask:0xa
	v_mov_b32_dpp v181, v146 row_shl:4 row_mask:0xf bank_mask:0x5
	v_mov_b32_dpp v181, v146 row_shr:4 row_mask:0xf bank_mask:0xa
	s_waitcnt lgkmcnt(0)
	v_cndmask_b32_e64 v185, v183, -v183, s[40:41]
	s_waitcnt lgkmcnt(0)
	v_cndmask_b32_e64 v184, v181, -v181, s[40:41]
	v_pk_mul_f32 v[182:183], v[182:183], v[184:185] op_sel_hi:[0,1]
	v_pk_fma_f32 v[146:147], v[86:87], v[146:147], v[182:183] op_sel_hi:[0,1,1]
; __device__ __forceinline__ float bfe2(const v2u& w, int c) { return (c & 1) ? bfhi(w[c >> 1]) : bflo(w[c >> 1]); }
; template <int DIR> __device__ __forceinline__ void prep_gla_k(const ScanBufs<64>& B, const bf16* P, const float* w2g, const float* b2g, const f32x2* RR, const LAS f32x2* RC  , int g, int half, int lane, LAS v4u* Wl, LAS v4u* Gl  ) {
;     ...
;                     float k = bfe2(kr[j], c), q = bfe2(qr2[j], c);
;                     if (lat) { const f32x2 cs = csc[c]; const float pt = __shfl_xor(k, 4), pq = __shfl_xor(q, 4); k = k * cs.x + (second ? pt : -pt) * cs.y; q = q * cs.x + (second ? pq : -pq) * cs.y; }
.LBB0_815:
	s_waitcnt lgkmcnt(1)
	v_and_b32_e32 v87, 0xffff0000, v142
	s_and_b64 vcc, exec, s[42:43]
	v_and_b32_e32 v86, 0xffff0000, v138
	s_cbranch_vccnz .LBB0_817
	v_cndmask_b32_e64 v88, v88, v76, s[38:39]
	s_nop 0
	s_nop 1
	v_mov_b32_dpp v142, v87 row_shl:4 row_mask:0xf bank_mask:0x5
	v_mov_b32_dpp v142, v87 row_shr:4 row_mask:0xf bank_mask:0xa
	v_mov_b32_dpp v181, v86 row_shl:4 row_mask:0xf bank_mask:0x5
	v_mov_b32_dpp v181, v86 row_shr:4 row_mask:0xf bank_mask:0xa
	v_cndmask_b32_e64 v138, v89, v77, s[38:39]
	s_waitcnt lgkmcnt(0)
	v_cndmask_b32_e64 v183, v142, -v142, s[40:41]
	s_waitcnt lgkmcnt(0)
	v_cndmask_b32_e64 v182, v181, -v181, s[40:41]
	v_pk_mul_f32 v[182:183], v[138:139], v[182:183] op_sel_hi:[0,1]
	v_pk_fma_f32 v[86:87], v[88:89], v[86:87], v[182:183] op_sel_hi:[0,1,1]
.LBB0_817:
	v_lshlrev_b32_e32 v89, 16, v143
	s_and_b64 vcc, exec, s[42:43]
	v_lshlrev_b32_e32 v88, 16, v139
	s_mov_b64 s[76:77], s[86:87]
	s_cbranch_vccnz .LBB0_819
	s_waitcnt lgkmcnt(0)
	v_cndmask_b32_e64 v82, v82, v70, s[38:39]
	s_nop 1
	v_mov_b32_dpp v142, v89 row_shl:4 row_mask:0xf bank_mask:0x5
	v_mov_b32_dpp v142, v89 row_shr:4 row_mask:0xf bank_mask:0xa
	v_mov_b32_dpp v181, v88 row_shl:4 row_mask:0xf bank_mask:0x5
	v_mov_b32_dpp v181, v88 row_shr:4 row_mask:0xf bank_mask:0xa
	v_cndmask_b32_e64 v138, v83, v71, s[38:39]
	s_waitcnt lgkmcnt(0)
	v_cndmask_b32_e64 v183, v142, -v142, s[40:41]
	s_waitcnt lgkmcnt(0)
	v_cndmask_b32_e64 v182, v181, -v181, s[40:41]
	v_pk_mul_f32 v[182:183], v[138:139], v[182:183] op_sel_hi:[0,1]
	v_pk_fma_f32 v[88:89], v[82:83], v[88:89], v[182:183] op_sel_hi:[0,1,1]
.LBB0_819:
	s_waitcnt lgkmcnt(0)
	v_and_b32_e32 v83, 0xffff0000, v143
	s_and_b64 vcc, exec, s[42:43]
	v_and_b32_e32 v82, 0xffff0000, v139
	s_cbranch_vccnz .LBB0_821
	v_cndmask_b32_e64 v84, v84, v72, s[38:39]
	s_nop 0
	s_nop 1
	v_mov_b32_dpp v139, v83 row_shl:4 row_mask:0xf bank_mask:0x5
	v_mov_b32_dpp v139, v83 row_shr:4 row_mask:0xf bank_mask:0xa
	v_mov_b32_dpp v142, v82 row_shl:4 row_mask:0xf bank_mask:0x5
	v_mov_b32_dpp v142, v82 row_shr:4 row_mask:0xf bank_mask:0xa
	v_cndmask_b32_e64 v138, v85, v73, s[38:39]
	s_waitcnt lgkmcnt(0)
	v_cndmask_b32_e64 v143, v139, -v139, s[40:41]
	s_waitcnt lgkmcnt(0)
	v_cndmask_b32_e64 v142, v142, -v142, s[40:41]
	v_pk_mul_f32 v[138:139], v[138:139], v[142:143] op_sel_hi:[0,1]
	v_pk_fma_f32 v[82:83], v[84:85], v[82:83], v[138:139] op_sel_hi:[0,1,1]
; #define GAS __attribute__((address_space(1)))
; __device__ __forceinline__ unsigned pk2(float lo, float hi) { const f32x2_t v = {lo, hi}; const bf16x2_t b = __builtin_convertvector(v, bf16x2_t); return __builtin_bit_cast(unsigned, b); }
; __device__ __forceinline__ float ex2(float x) { return __builtin_amdgcn_exp2f(x); }
; __device__ __forceinline__ float bfe(const v4u& w, int c) { return (c & 1) ? bfhi(w[c >> 1]) : bflo(w[c >> 1]); }
; __device__ __forceinline__ float bfe2(const v2u& w, int c) { return (c & 1) ? bfhi(w[c >> 1]) : bflo(w[c >> 1]); }
; template <int DIR> __device__ __forceinline__ void prep_gla_k(const ScanBufs<64>& B, const bf16* P, const float* w2g, const float* b2g, const f32x2* RR, const LAS f32x2* RC  , int g, int half, int lane, LAS v4u* Wl, LAS v4u* Gl  ) {
;     ...
;                 for (int c = 0; c < 4; ++c) { float x = b2[c];
; #pragma unroll
;                     for (int r = 0; r < 8; ++r) { x += bfe(l0[j], r) * w2[r][c]; x += bfe(l1[j], r) * w2[8 + r][c]; }
;                     const float la = (fminf(x, 0.f) * 1.4426950408889634f - __log2f(1.f + __expf(-fabsf(x)))) * 0.0625f;
;                     float k = bfe2(kr[j], c), q = bfe2(qr2[j], c);
;                     if (lat) { const f32x2 cs = csc[c]; const float pt = __shfl_xor(k, 4), pq = __shfl_xor(q, 4); k = k * cs.x + (second ? pt : -pt) * cs.y; q = q * cs.x + (second ? pq : -pq) * cs.y; }
;                     const float e = cum[c]; cum[c] += la; kv[c] = k * ex2(e); kp[hf * 4 + j][c] = kv[c]; ev[c] = q * 0.125f * ex2(fminf(-e, 126.f)); }
;                 { v2u ew; ew.x = pk2(ev[0], ev[1]); ew.y = pk2(ev[2], ev[3]); *(GAS v2u*)(Ep + (size_t)t * 512) = ew; }
;                 { v2u kw; kw.x = pk2(kv[0], kv[1]); kw.y = pk2(kv[2], kv[3]); *(GAS v2u*)(Kp + (size_t)t * 512) = kw; } } }
.LBB0_821:
	s_lshl_b32 s72, s64, 16
	s_lshl_b32 s71, s67, 16
	v_fma_f32 v84, s72, v58, v68
	s_and_b32 s70, s64, 0xffff0000
	v_fmac_f32_e32 v84, s71, v26
	s_and_b32 s69, s67, 0xffff0000
	v_fmac_f32_e32 v84, s70, v2
	s_lshl_b32 s68, s63, 16
	v_fmac_f32_e32 v84, s69, v34
	s_lshl_b32 s67, s66, 16
	v_fmac_f32_e32 v84, s68, v6
	s_and_b32 s64, s63, 0xffff0000
	v_fmac_f32_e32 v84, s67, v38
	s_and_b32 s63, s66, 0xffff0000
	v_fmac_f32_e32 v84, s64, v10
	s_lshl_b32 s26, s62, 16
	v_fmac_f32_e32 v84, s63, v42
	s_lshl_b32 s25, s65, 16
	v_fmac_f32_e32 v84, s26, v14
	s_and_b32 s24, s62, 0xffff0000
	v_fmac_f32_e32 v84, s25, v50
	s_and_b32 s23, s65, 0xffff0000
	v_fmac_f32_e32 v84, s24, v30
	s_lshl_b32 s22, s61, 16
	v_fmac_f32_e32 v84, s23, v46
	s_lshl_b32 s21, s27, 16
	v_fmac_f32_e32 v84, s22, v18
	s_and_b32 s20, s61, 0xffff0000
	v_fmac_f32_e32 v84, s21, v54
	s_and_b32 s19, s27, 0xffff0000
	v_fmac_f32_e32 v84, s20, v22
	v_fmac_f32_e32 v84, s19, v62
	s_mov_b32 s61, 0xbfb8aa3b
	v_min_f32_e32 v85, 0, v84
	v_mul_f32_e64 v84, |v84|, s61
	v_exp_f32_e32 v84, v84
	s_mov_b32 s62, 0x3fb8aa3b
	s_mov_b32 s27, 0x42fc0000
	v_add_f32_e32 v84, 1.0, v84
	v_log_f32_e32 v84, v84
	s_nop 0
	v_fma_f32 v84, v85, s62, -v84
	v_fmac_f32_e32 v80, 0x3d800000, v84
	v_exp_f32_e32 v84, v80
	v_min_f32_e64 v85, -v80, s27
	v_exp_f32_e32 v85, v85
	v_mul_f32_e32 v138, v84, v88
	v_mul_f32_e32 v84, 0x3e000000, v89
	v_mul_f32_e32 v84, v85, v84
	v_fma_f32 v85, s72, v57, v67
	v_fmac_f32_e32 v85, s71, v25
	v_fmac_f32_e32 v85, s70, v1
	v_fmac_f32_e32 v85, s69, v33
	v_fmac_f32_e32 v85, s68, v5
	v_fmac_f32_e32 v85, s67, v37
	v_fmac_f32_e32 v85, s64, v9
	v_fmac_f32_e32 v85, s63, v41
	v_fmac_f32_e32 v85, s26, v13
	v_fmac_f32_e32 v85, s25, v49
	v_fmac_f32_e32 v85, s24, v29
	v_fmac_f32_e32 v85, s23, v45
	v_fmac_f32_e32 v85, s22, v17
	v_fmac_f32_e32 v85, s21, v53
	v_fmac_f32_e32 v85, s20, v21
	v_fmac_f32_e32 v85, s19, v61
	v_min_f32_e32 v88, 0, v85
	v_mul_f32_e64 v85, |v85|, s61
	v_exp_f32_e32 v85, v85
	s_nop 0
	v_add_f32_e32 v85, 1.0, v85
	v_log_f32_e32 v85, v85
	s_nop 0
	v_fma_f32 v85, v88, s62, -v85
	v_fmac_f32_e32 v79, 0x3d800000, v85
	v_exp_f32_e32 v85, v79
	s_nop 0
	v_mul_f32_e32 v139, v85, v86
	v_min_f32_e64 v86, -v79, s27
	v_exp_f32_e32 v86, v86
	v_mul_f32_e32 v85, 0x3e000000, v87
	v_mul_f32_e32 v85, v86, v85
	v_fma_f32 v86, s72, v56, v66
	v_fmac_f32_e32 v86, s71, v24
	v_fmac_f32_e32 v86, s70, v0
	v_fmac_f32_e32 v86, s69, v32
	v_fmac_f32_e32 v86, s68, v4
	v_fmac_f32_e32 v86, s67, v36
	v_fmac_f32_e32 v86, s64, v8
	v_fmac_f32_e32 v86, s63, v40
	v_fmac_f32_e32 v86, s26, v12
	v_fmac_f32_e32 v86, s25, v48
	v_fmac_f32_e32 v86, s24, v28
	v_fmac_f32_e32 v86, s23, v44
	v_fmac_f32_e32 v86, s22, v16
	v_fmac_f32_e32 v86, s21, v52
	v_fmac_f32_e32 v86, s20, v20
	v_fmac_f32_e32 v86, s19, v60
	v_min_f32_e32 v87, 0, v86
	v_mul_f32_e64 v86, |v86|, s61
	v_exp_f32_e32 v86, v86
	s_nop 0
	v_add_f32_e32 v86, 1.0, v86
	v_log_f32_e32 v86, v86
	s_nop 0
	v_fma_f32 v86, v87, s62, -v86
	v_fmac_f32_e32 v78, 0x3d800000, v86
	v_exp_f32_e32 v86, v78
	v_min_f32_e64 v87, -v78, s27
	v_exp_f32_e32 v87, v87
	v_mul_f32_e32 v142, v86, v146
	v_mul_f32_e32 v86, 0x3e000000, v147
	v_mul_f32_e32 v86, v87, v86
	v_fma_f32 v87, s72, v59, v69
	v_fmac_f32_e32 v87, s71, v27
	v_fmac_f32_e32 v87, s70, v3
	v_fmac_f32_e32 v87, s69, v35
	v_fmac_f32_e32 v87, s68, v7
	v_fmac_f32_e32 v87, s67, v39
	v_fmac_f32_e32 v87, s64, v11
	v_fmac_f32_e32 v87, s63, v43
	v_fmac_f32_e32 v87, s26, v15
	v_fmac_f32_e32 v87, s25, v51
	v_fmac_f32_e32 v87, s24, v31
	v_fmac_f32_e32 v87, s23, v47
	v_fmac_f32_e32 v87, s22, v19
	v_fmac_f32_e32 v87, s21, v55
	v_fmac_f32_e32 v87, s20, v23
	v_fmac_f32_e32 v87, s19, v63
	v_min_f32_e32 v88, 0, v87
	v_mul_f32_e64 v87, |v87|, s61
	v_exp_f32_e32 v87, v87
	v_lshlrev_b32_e32 v147, 16, v130
	v_lshlrev_b32_e32 v146, 16, v128
	v_add_f32_e32 v87, 1.0, v87
	v_log_f32_e32 v87, v87
	s_nop 0
	v_fma_f32 v87, v88, s62, -v87
	v_fmac_f32_e32 v81, 0x3d800000, v87
	v_exp_f32_e32 v87, v81
	s_nop 0
	v_mul_f32_e32 v143, v87, v82
	v_mul_f32_e32 v82, 0x3e000000, v83
	v_min_f32_e64 v83, -v81, s27
	v_exp_f32_e32 v83, v83
	s_nop 0
	v_mul_f32_e32 v83, v83, v82
	v_cvt_pk_bf16_f32 v82, v86, v85
	v_cvt_pk_bf16_f32 v83, v84, v83
	v_add_co_u32_e32 v84, vcc, 0x64d0e000, v112
	global_store_dwordx2 v[144:145], v[82:83], off offset:2048
	v_cvt_pk_bf16_f32 v82, v142, v139
	v_cvt_pk_bf16_f32 v83, v138, v143
	v_addc_co_u32_e32 v85, vcc, 0, v113, vcc
	global_store_dwordx2 v[84:85], v[82:83], off offset:2048
	v_add_u32_e32 v82, 0x11c80, v156
	ds_read_b128 v[86:89], v82
	v_add_u32_e32 v82, 0x11c90, v156
	ds_read_b128 v[82:85], v82
	s_and_b64 vcc, exec, s[42:43]
	s_cbranch_vccnz .LBB0_823
	s_waitcnt lgkmcnt(1)
	v_cndmask_b32_e64 v182, v87, v75, s[38:39]
	v_cndmask_b32_e64 v86, v86, v74, s[38:39]
	s_nop 1
	v_mov_b32_dpp v183, v147 row_shl:4 row_mask:0xf bank_mask:0x5
	v_mov_b32_dpp v183, v147 row_shr:4 row_mask:0xf bank_mask:0xa
	v_mov_b32_dpp v181, v146 row_shl:4 row_mask:0xf bank_mask:0x5
	v_mov_b32_dpp v181, v146 row_shr:4 row_mask:0xf bank_mask:0xa
	s_waitcnt lgkmcnt(0)
	v_cndmask_b32_e64 v185, v183, -v183, s[40:41]
	s_waitcnt lgkmcnt(0)
	v_cndmask_b32_e64 v184, v181, -v181, s[40:41]
	v_pk_mul_f32 v[182:183], v[182:183], v[184:185] op_sel_hi:[0,1]
	v_pk_fma_f32 v[146:147], v[86:87], v[146:147], v[182:183] op_sel_hi:[0,1,1]
.LBB0_823:
	v_readlane_b32 s68, v245, 33
	s_waitcnt lgkmcnt(1)
	v_and_b32_e32 v87, 0xffff0000, v130
	s_and_b64 vcc, exec, s[42:43]
	v_and_b32_e32 v86, 0xffff0000, v128
	v_readlane_b32 s69, v245, 34
	v_readlane_b32 s70, v245, 35
	v_readlane_b32 s71, v245, 36
	s_mov_b32 s66, 0xffff0000
	s_cbranch_vccnz .LBB0_834
	v_cndmask_b32_e64 v88, v88, v76, s[38:39]
	s_nop 0
	s_nop 1
	v_mov_b32_dpp v130, v87 row_shl:4 row_mask:0xf bank_mask:0x5
	v_mov_b32_dpp v130, v87 row_shr:4 row_mask:0xf bank_mask:0xa
	v_mov_b32_dpp v181, v86 row_shl:4 row_mask:0xf bank_mask:0x5
	v_mov_b32_dpp v181, v86 row_shr:4 row_mask:0xf bank_mask:0xa
	v_cndmask_b32_e64 v128, v89, v77, s[38:39]
	s_waitcnt lgkmcnt(0)
	v_cndmask_b32_e64 v183, v130, -v130, s[40:41]
	s_waitcnt lgkmcnt(0)
	v_cndmask_b32_e64 v182, v181, -v181, s[40:41]
	v_pk_mul_f32 v[182:183], v[128:129], v[182:183] op_sel_hi:[0,1]
	v_pk_fma_f32 v[86:87], v[88:89], v[86:87], v[182:183] op_sel_hi:[0,1,1]
	v_lshlrev_b32_e32 v89, 16, v131
	s_and_b64 vcc, exec, s[42:43]
	v_lshlrev_b32_e32 v88, 16, v129
	s_cbranch_vccz .LBB0_835

; #define GAS __attribute__((address_space(1)))
; #define LAS __attribute__((address_space(3)))
; __device__ __forceinline__ unsigned pk2(float lo, float hi) { const f32x2_t v = {lo, hi}; const bf16x2_t b = __builtin_convertvector(v, bf16x2_t); return __builtin_bit_cast(unsigned, b); }
; __device__ __forceinline__ float ex2(float x) { return __builtin_amdgcn_exp2f(x); }
; __device__ __forceinline__ float bfe(const v4u& w, int c) { return (c & 1) ? bfhi(w[c >> 1]) : bflo(w[c >> 1]); }
; __device__ __forceinline__ float bfe2(const v2u& w, int c) { return (c & 1) ? bfhi(w[c >> 1]) : bflo(w[c >> 1]); }
; template <int DIR> __device__ __forceinline__ void prep_gla_k(const ScanBufs<64>& B, const bf16* P, const float* w2g, const float* b2g, const f32x2* RR, const LAS f32x2* RC  , int g, int half, int lane, LAS v4u* Wl, LAS v4u* Gl  ) {
;     ...
;                 { const LAS f32x4* rc4 = (const LAS f32x4*)(RC + t * 16 + j0); const f32x4 ra = rc4[0], rb = rc4[1];
;                   csc[0] = isrow ? csr[0] : (f32x2){ra[0], ra[1]}; csc[1] = isrow ? csr[1] : (f32x2){ra[2], ra[3]}; csc[2] = isrow ? csr[2] : (f32x2){rb[0], rb[1]}; csc[3] = isrow ? csr[3] : (f32x2){rb[2], rb[3]}; }
; #pragma unroll
;                 for (int c = 0; c < 4; ++c) { float x = b2[c];
; #pragma unroll
;                     for (int r = 0; r < 8; ++r) { x += bfe(l0[j], r) * w2[r][c]; x += bfe(l1[j], r) * w2[8 + r][c]; }
;                     const float la = (fminf(x, 0.f) * 1.4426950408889634f - __log2f(1.f + __expf(-fabsf(x)))) * 0.0625f;
;                     float k = bfe2(kr[j], c), q = bfe2(qr2[j], c);
;                     if (lat) { const f32x2 cs = csc[c]; const float pt = __shfl_xor(k, 4), pq = __shfl_xor(q, 4); k = k * cs.x + (second ? pt : -pt) * cs.y; q = q * cs.x + (second ? pq : -pq) * cs.y; }
;                     const float e = cum[c]; cum[c] += la; kv[c] = k * ex2(e); kp[hf * 4 + j][c] = kv[c]; ev[c] = q * 0.125f * ex2(fminf(-e, 126.f)); }
;                 { v2u ew; ew.x = pk2(ev[0], ev[1]); ew.y = pk2(ev[2], ev[3]); *(GAS v2u*)(Ep + (size_t)t * 512) = ew; }
;                 { v2u kw; kw.x = pk2(kv[0], kv[1]); kw.y = pk2(kv[2], kv[3]); *(GAS v2u*)(Kp + (size_t)t * 512) = kw; } } }
.LBB0_826:
	v_cndmask_b32_e64 v84, v84, v72, s[38:39]
	s_nop 0
	s_nop 1
	v_mov_b32_dpp v129, v83 row_shl:4 row_mask:0xf bank_mask:0x5
	v_mov_b32_dpp v129, v83 row_shr:4 row_mask:0xf bank_mask:0xa
	v_mov_b32_dpp v130, v82 row_shl:4 row_mask:0xf bank_mask:0x5
	v_mov_b32_dpp v130, v82 row_shr:4 row_mask:0xf bank_mask:0xa
	v_cndmask_b32_e64 v128, v85, v73, s[38:39]
	s_waitcnt lgkmcnt(0)
	v_cndmask_b32_e64 v131, v129, -v129, s[40:41]
	s_waitcnt lgkmcnt(0)
	v_cndmask_b32_e64 v130, v130, -v130, s[40:41]
	v_pk_mul_f32 v[128:129], v[128:129], v[130:131] op_sel_hi:[0,1]
	v_pk_fma_f32 v[82:83], v[84:85], v[82:83], v[128:129] op_sel_hi:[0,1,1]
.LBB0_827:
	s_lshl_b32 s64, s56, 16
	s_lshl_b32 s63, s60, 16
	v_fma_f32 v84, s64, v58, v68
	s_and_b32 s62, s56, 0xffff0000
	v_fmac_f32_e32 v84, s63, v26
	s_and_b32 s61, s60, 0xffff0000
	v_fmac_f32_e32 v84, s62, v2
	s_lshl_b32 s60, s55, 16
	v_fmac_f32_e32 v84, s61, v34
	s_lshl_b32 s56, s59, 16
	v_fmac_f32_e32 v84, s60, v6
	s_and_b32 s55, s55, 0xffff0000
	v_fmac_f32_e32 v84, s56, v38
	s_and_b32 s27, s59, 0xffff0000
	v_fmac_f32_e32 v84, s55, v10
	s_lshl_b32 s26, s54, 16
	v_fmac_f32_e32 v84, s27, v42
	s_lshl_b32 s25, s58, 16
	v_fmac_f32_e32 v84, s26, v14
	s_and_b32 s24, s54, 0xffff0000
	v_fmac_f32_e32 v84, s25, v50
	s_and_b32 s23, s58, 0xffff0000
	v_fmac_f32_e32 v84, s24, v30
	s_lshl_b32 s22, s33, 16
	v_fmac_f32_e32 v84, s23, v46
	s_lshl_b32 s21, s57, 16
	v_fmac_f32_e32 v84, s22, v18
	s_and_b32 s20, s33, 0xffff0000
	v_fmac_f32_e32 v84, s21, v54
	s_and_b32 s19, s57, 0xffff0000
	v_fmac_f32_e32 v84, s20, v22
	v_fmac_f32_e32 v84, s19, v62
	s_mov_b32 s54, 0xbfb8aa3b
	v_min_f32_e32 v85, 0, v84
	v_mul_f32_e64 v84, |v84|, s54
	v_exp_f32_e32 v84, v84
	s_mov_b32 s57, 0x3fb8aa3b
	s_mov_b32 s33, 0x42fc0000
	v_lshlrev_b32_e32 v129, 16, v120
	v_add_f32_e32 v84, 1.0, v84
	v_log_f32_e32 v84, v84
	v_lshlrev_b32_e32 v128, 16, v118
	v_fma_f32 v84, v85, s57, -v84
	v_fmac_f32_e32 v80, 0x3d800000, v84
	v_exp_f32_e32 v84, v80
	v_min_f32_e64 v85, -v80, s33
	v_exp_f32_e32 v85, v85
	v_mul_f32_e32 v130, v84, v88
	v_mul_f32_e32 v84, 0x3e000000, v89
	v_mul_f32_e32 v84, v85, v84
	v_fma_f32 v85, s64, v57, v67
	v_fmac_f32_e32 v85, s63, v25
	v_fmac_f32_e32 v85, s62, v1
	v_fmac_f32_e32 v85, s61, v33
	v_fmac_f32_e32 v85, s60, v5
	v_fmac_f32_e32 v85, s56, v37
	v_fmac_f32_e32 v85, s55, v9
	v_fmac_f32_e32 v85, s27, v41
	v_fmac_f32_e32 v85, s26, v13
	v_fmac_f32_e32 v85, s25, v49
	v_fmac_f32_e32 v85, s24, v29
	v_fmac_f32_e32 v85, s23, v45
	v_fmac_f32_e32 v85, s22, v17
	v_fmac_f32_e32 v85, s21, v53
	v_fmac_f32_e32 v85, s20, v21
	v_fmac_f32_e32 v85, s19, v61
	v_min_f32_e32 v88, 0, v85
	v_mul_f32_e64 v85, |v85|, s54
	v_exp_f32_e32 v85, v85
	s_nop 0
	v_add_f32_e32 v85, 1.0, v85
	v_log_f32_e32 v85, v85
	s_nop 0
	v_fma_f32 v85, v88, s57, -v85
	v_fmac_f32_e32 v79, 0x3d800000, v85
	v_exp_f32_e32 v85, v79
	s_nop 0
	v_mul_f32_e32 v131, v85, v86
	v_min_f32_e64 v86, -v79, s33
	v_exp_f32_e32 v86, v86
	v_mul_f32_e32 v85, 0x3e000000, v87
	v_mul_f32_e32 v85, v86, v85
	v_fma_f32 v86, s64, v56, v66
	v_fmac_f32_e32 v86, s63, v24
	v_fmac_f32_e32 v86, s62, v0
	v_fmac_f32_e32 v86, s61, v32
	v_fmac_f32_e32 v86, s60, v4
	v_fmac_f32_e32 v86, s56, v36
	v_fmac_f32_e32 v86, s55, v8
	v_fmac_f32_e32 v86, s27, v40
	v_fmac_f32_e32 v86, s26, v12
	v_fmac_f32_e32 v86, s25, v48
	v_fmac_f32_e32 v86, s24, v28
	v_fmac_f32_e32 v86, s23, v44
	v_fmac_f32_e32 v86, s22, v16
	v_fmac_f32_e32 v86, s21, v52
	v_fmac_f32_e32 v86, s20, v20
	v_fmac_f32_e32 v86, s19, v60
	v_min_f32_e32 v87, 0, v86
	v_mul_f32_e64 v86, |v86|, s54
	v_exp_f32_e32 v86, v86
	s_nop 0
	v_add_f32_e32 v86, 1.0, v86
	v_log_f32_e32 v86, v86
	s_nop 0
	v_fma_f32 v86, v87, s57, -v86
	v_fmac_f32_e32 v78, 0x3d800000, v86
	v_exp_f32_e32 v86, v78
	v_min_f32_e64 v87, -v78, s33
	v_exp_f32_e32 v87, v87
	v_mul_f32_e32 v146, v86, v146
	v_mul_f32_e32 v86, 0x3e000000, v147
	v_mul_f32_e32 v86, v87, v86
	v_fma_f32 v87, s64, v59, v69
	v_fmac_f32_e32 v87, s63, v27
	v_fmac_f32_e32 v87, s62, v3
	v_fmac_f32_e32 v87, s61, v35
	v_fmac_f32_e32 v87, s60, v7
	v_fmac_f32_e32 v87, s56, v39
	v_fmac_f32_e32 v87, s55, v11
	v_fmac_f32_e32 v87, s27, v43
	v_fmac_f32_e32 v87, s26, v15
	v_fmac_f32_e32 v87, s25, v51
	v_fmac_f32_e32 v87, s24, v31
	v_fmac_f32_e32 v87, s23, v47
	v_fmac_f32_e32 v87, s22, v19
	v_fmac_f32_e32 v87, s21, v55
	v_fmac_f32_e32 v87, s20, v23
	v_fmac_f32_e32 v87, s19, v63
	v_min_f32_e32 v88, 0, v87
	v_mul_f32_e64 v87, |v87|, s54
	v_exp_f32_e32 v87, v87
	s_nop 0
	v_add_f32_e32 v87, 1.0, v87
	v_log_f32_e32 v87, v87
	s_nop 0
	v_fma_f32 v87, v88, s57, -v87
	v_fmac_f32_e32 v81, 0x3d800000, v87
	v_exp_f32_e32 v87, v81
	s_nop 0
	v_mul_f32_e32 v147, v87, v82
	v_mul_f32_e32 v82, 0x3e000000, v83
	v_min_f32_e64 v83, -v81, s33
	v_exp_f32_e32 v83, v83
	s_nop 0
	v_mul_f32_e32 v83, v83, v82
	v_cvt_pk_bf16_f32 v82, v86, v85
	v_cvt_pk_bf16_f32 v83, v84, v83
	v_add_co_u32_e32 v84, vcc, 0x64d0e000, v112
	global_store_dwordx2 v[144:145], v[82:83], off offset:1024
	v_cvt_pk_bf16_f32 v82, v146, v131
	v_cvt_pk_bf16_f32 v83, v130, v147
	v_addc_co_u32_e32 v85, vcc, 0, v113, vcc
	global_store_dwordx2 v[84:85], v[82:83], off offset:1024
	v_add_u32_e32 v82, 0x11c00, v156
	ds_read_b128 v[86:89], v82
	v_add_u32_e32 v82, 0x11c10, v156
	ds_read_b128 v[82:85], v82
	s_and_b64 vcc, exec, s[42:43]
	s_cbranch_vccnz .LBB0_829
	s_waitcnt lgkmcnt(1)
	v_cndmask_b32_e64 v86, v86, v74, s[38:39]
	s_nop 1
	v_mov_b32_dpp v181, v129 row_shl:4 row_mask:0xf bank_mask:0x5
	v_mov_b32_dpp v181, v129 row_shr:4 row_mask:0xf bank_mask:0xa
	v_mov_b32_dpp v182, v128 row_shl:4 row_mask:0xf bank_mask:0x5
	v_mov_b32_dpp v182, v128 row_shr:4 row_mask:0xf bank_mask:0xa
	v_cndmask_b32_e64 v156, v87, v75, s[38:39]
	s_waitcnt lgkmcnt(0)
	v_cndmask_b32_e64 v183, v181, -v181, s[40:41]
	s_waitcnt lgkmcnt(0)
	v_cndmask_b32_e64 v182, v182, -v182, s[40:41]
	v_pk_mul_f32 v[182:183], v[156:157], v[182:183] op_sel_hi:[0,1]
	v_pk_fma_f32 v[128:129], v[86:87], v[128:129], v[182:183] op_sel_hi:[0,1,1]
; __device__ __forceinline__ float bfe2(const v2u& w, int c) { return (c & 1) ? bfhi(w[c >> 1]) : bflo(w[c >> 1]); }
; template <int DIR> __device__ __forceinline__ void prep_gla_k(const ScanBufs<64>& B, const bf16* P, const float* w2g, const float* b2g, const f32x2* RR, const LAS f32x2* RC  , int g, int half, int lane, LAS v4u* Wl, LAS v4u* Gl  ) {
;     ...
;                     float k = bfe2(kr[j], c), q = bfe2(qr2[j], c);
;                     if (lat) { const f32x2 cs = csc[c]; const float pt = __shfl_xor(k, 4), pq = __shfl_xor(q, 4); k = k * cs.x + (second ? pt : -pt) * cs.y; q = q * cs.x + (second ? pq : -pq) * cs.y; }
.LBB0_829:
	v_readlane_b32 s60, v245, 42
	v_readlane_b32 s64, v245, 46
	s_waitcnt lgkmcnt(1)
	v_and_b32_e32 v87, 0xffff0000, v120
	s_and_b64 vcc, exec, s[42:43]
	v_and_b32_e32 v86, 0xffff0000, v118
	v_readlane_b32 s61, v245, 43
	v_readlane_b32 s59, v245, 44
	v_readlane_b32 s62, v245, 45
	v_readlane_b32 s65, v245, 47
	v_readlane_b32 s63, v245, 48
	s_cbranch_vccnz .LBB0_836
	v_cndmask_b32_e64 v88, v88, v76, s[38:39]
	s_nop 0
	s_nop 1
	v_mov_b32_dpp v120, v87 row_shl:4 row_mask:0xf bank_mask:0x5
	v_mov_b32_dpp v120, v87 row_shr:4 row_mask:0xf bank_mask:0xa
	v_mov_b32_dpp v156, v86 row_shl:4 row_mask:0xf bank_mask:0x5
	v_mov_b32_dpp v156, v86 row_shr:4 row_mask:0xf bank_mask:0xa
	v_cndmask_b32_e64 v118, v89, v77, s[38:39]
	s_waitcnt lgkmcnt(0)
	v_cndmask_b32_e64 v183, v120, -v120, s[40:41]
	s_waitcnt lgkmcnt(0)
	v_cndmask_b32_e64 v182, v156, -v156, s[40:41]
	v_pk_mul_f32 v[182:183], v[118:119], v[182:183] op_sel_hi:[0,1]
	v_pk_fma_f32 v[86:87], v[88:89], v[86:87], v[182:183] op_sel_hi:[0,1,1]
	v_lshlrev_b32_e32 v89, 16, v121
	s_and_b64 vcc, exec, s[42:43]
	v_lshlrev_b32_e32 v88, 16, v119
	s_cbranch_vccz .LBB0_837

; __device__ __forceinline__ float bfe2(const v2u& w, int c) { return (c & 1) ? bfhi(w[c >> 1]) : bflo(w[c >> 1]); }
; template <int DIR> __device__ __forceinline__ void prep_gla_k(const ScanBufs<64>& B, const bf16* P, const float* w2g, const float* b2g, const f32x2* RR, const LAS f32x2* RC  , int g, int half, int lane, LAS v4u* Wl, LAS v4u* Gl  ) {
;     ...
;                     float k = bfe2(kr[j], c), q = bfe2(qr2[j], c);
;                     if (lat) { const f32x2 cs = csc[c]; const float pt = __shfl_xor(k, 4), pq = __shfl_xor(q, 4); k = k * cs.x + (second ? pt : -pt) * cs.y; q = q * cs.x + (second ? pq : -pq) * cs.y; }
.LBB0_833:
	v_cndmask_b32_e64 v88, v88, v76, s[38:39]
	s_nop 0
	s_nop 1
	v_mov_b32_dpp v146, v87 row_shl:4 row_mask:0xf bank_mask:0x5
	v_mov_b32_dpp v146, v87 row_shr:4 row_mask:0xf bank_mask:0xa
	v_mov_b32_dpp v179, v86 row_shl:4 row_mask:0xf bank_mask:0x5
	v_mov_b32_dpp v179, v86 row_shr:4 row_mask:0xf bank_mask:0xa
	v_cndmask_b32_e64 v144, v89, v77, s[38:39]
	s_waitcnt lgkmcnt(0)
	v_cndmask_b32_e64 v181, v146, -v146, s[40:41]
	s_waitcnt lgkmcnt(0)
	v_cndmask_b32_e64 v180, v179, -v179, s[40:41]
	v_pk_mul_f32 v[180:181], v[144:145], v[180:181] op_sel_hi:[0,1]
	v_pk_fma_f32 v[86:87], v[88:89], v[86:87], v[180:181] op_sel_hi:[0,1,1]
	v_lshlrev_b32_e32 v89, 16, v147
	s_and_b64 vcc, exec, s[42:43]
	v_lshlrev_b32_e32 v88, 16, v145
	s_cbranch_vccz .LBB0_810
	s_branch .LBB0_811

; __device__ __forceinline__ float bfe2(const v2u& w, int c) { return (c & 1) ? bfhi(w[c >> 1]) : bflo(w[c >> 1]); }
; template <int DIR> __device__ __forceinline__ void prep_gla_k(const ScanBufs<64>& B, const bf16* P, const float* w2g, const float* b2g, const f32x2* RR, const LAS f32x2* RC  , int g, int half, int lane, LAS v4u* Wl, LAS v4u* Gl  ) {
;     ...
;                     float k = bfe2(kr[j], c), q = bfe2(qr2[j], c);
;                     if (lat) { const f32x2 cs = csc[c]; const float pt = __shfl_xor(k, 4), pq = __shfl_xor(q, 4); k = k * cs.x + (second ? pt : -pt) * cs.y; q = q * cs.x + (second ? pq : -pq) * cs.y; }
.LBB0_835:
	s_waitcnt lgkmcnt(0)
	v_cndmask_b32_e64 v82, v82, v70, s[38:39]
	s_nop 1
	v_mov_b32_dpp v130, v89 row_shl:4 row_mask:0xf bank_mask:0x5
	v_mov_b32_dpp v130, v89 row_shr:4 row_mask:0xf bank_mask:0xa
	v_mov_b32_dpp v181, v88 row_shl:4 row_mask:0xf bank_mask:0x5
	v_mov_b32_dpp v181, v88 row_shr:4 row_mask:0xf bank_mask:0xa
	v_cndmask_b32_e64 v128, v83, v71, s[38:39]
	s_waitcnt lgkmcnt(0)
	v_cndmask_b32_e64 v183, v130, -v130, s[40:41]
	s_waitcnt lgkmcnt(0)
	v_cndmask_b32_e64 v182, v181, -v181, s[40:41]
	v_pk_mul_f32 v[182:183], v[128:129], v[182:183] op_sel_hi:[0,1]
	v_pk_fma_f32 v[88:89], v[82:83], v[88:89], v[182:183] op_sel_hi:[0,1,1]
	v_and_b32_e32 v83, 0xffff0000, v131
	s_and_b64 vcc, exec, s[42:43]
	v_and_b32_e32 v82, 0xffff0000, v129
	s_cbranch_vccz .LBB0_826
	s_branch .LBB0_827

; __device__ __forceinline__ float bfe2(const v2u& w, int c) { return (c & 1) ? bfhi(w[c >> 1]) : bflo(w[c >> 1]); }
; template <int DIR> __device__ __forceinline__ void prep_gla_k(const ScanBufs<64>& B, const bf16* P, const float* w2g, const float* b2g, const f32x2* RR, const LAS f32x2* RC  , int g, int half, int lane, LAS v4u* Wl, LAS v4u* Gl  ) {
;     ...
;                     float k = bfe2(kr[j], c), q = bfe2(qr2[j], c);
;                     if (lat) { const f32x2 cs = csc[c]; const float pt = __shfl_xor(k, 4), pq = __shfl_xor(q, 4); k = k * cs.x + (second ? pt : -pt) * cs.y; q = q * cs.x + (second ? pq : -pq) * cs.y; }
.LBB0_837:
	s_waitcnt lgkmcnt(0)
	v_cndmask_b32_e64 v82, v82, v70, s[38:39]
	s_nop 1
	v_mov_b32_dpp v120, v89 row_shl:4 row_mask:0xf bank_mask:0x5
	v_mov_b32_dpp v120, v89 row_shr:4 row_mask:0xf bank_mask:0xa
	v_mov_b32_dpp v156, v88 row_shl:4 row_mask:0xf bank_mask:0x5
	v_mov_b32_dpp v156, v88 row_shr:4 row_mask:0xf bank_mask:0xa
	v_cndmask_b32_e64 v118, v83, v71, s[38:39]
	s_waitcnt lgkmcnt(0)
	v_cndmask_b32_e64 v183, v120, -v120, s[40:41]
	s_waitcnt lgkmcnt(0)
	v_cndmask_b32_e64 v182, v156, -v156, s[40:41]
	v_pk_mul_f32 v[182:183], v[118:119], v[182:183] op_sel_hi:[0,1]
	v_pk_fma_f32 v[88:89], v[82:83], v[88:89], v[182:183] op_sel_hi:[0,1,1]
	v_and_b32_e32 v83, 0xffff0000, v121
	s_and_b64 vcc, exec, s[42:43]
	v_and_b32_e32 v82, 0xffff0000, v119
	s_cbranch_vccnz .LBB0_772
.LBB0_838:
	v_cndmask_b32_e64 v84, v84, v72, s[38:39]
	s_nop 0
	s_nop 1
	v_mov_b32_dpp v119, v83 row_shl:4 row_mask:0xf bank_mask:0x5
	v_mov_b32_dpp v119, v83 row_shr:4 row_mask:0xf bank_mask:0xa
	v_mov_b32_dpp v120, v82 row_shl:4 row_mask:0xf bank_mask:0x5
	v_mov_b32_dpp v120, v82 row_shr:4 row_mask:0xf bank_mask:0xa
	v_cndmask_b32_e64 v118, v85, v73, s[38:39]
	s_waitcnt lgkmcnt(0)
	v_cndmask_b32_e64 v121, v119, -v119, s[40:41]
	s_waitcnt lgkmcnt(0)
	v_cndmask_b32_e64 v120, v120, -v120, s[40:41]
	v_pk_mul_f32 v[118:119], v[118:119], v[120:121] op_sel_hi:[0,1]
	v_pk_fma_f32 v[82:83], v[84:85], v[82:83], v[118:119] op_sel_hi:[0,1,1]
	s_branch .LBB0_772
